# merge: four per-group GEMM calls as one software-pipelined stream (next group's first two K-steps prefetched, one barrier per group boundary, C=0 first MFMAs)
# baseline (speedup 1.0000x reference)
.LBB0_1010:
	ds_read_b128 v[90:93], v119 offset:0
	ds_read_b128 v[208:211], v205 offset:0
	ds_read_b128 v[212:215], v119 offset:2560
	ds_read_b128 v[216:219], v119 offset:5120
	ds_read_b128 v[220:223], v119 offset:7680
	s_waitcnt lgkmcnt(3)
	v_mfma_f32_16x16x32_bf16 v[6:9], v[90:93], v[208:211], v[6:9]
	s_waitcnt lgkmcnt(2)
	v_mfma_f32_16x16x32_bf16 v[30:33], v[212:215], v[208:211], v[30:33]
	s_waitcnt vmcnt(11)
	ds_write_b128 v207, v[228:231] offset:0
	s_waitcnt lgkmcnt(2)
	v_mfma_f32_16x16x32_bf16 v[38:41], v[216:219], v[208:211], v[38:41]
	s_waitcnt lgkmcnt(1)
	v_mfma_f32_16x16x32_bf16 v[42:45], v[220:223], v[208:211], v[42:45]
	ds_read_b128 v[208:211], v205 offset:2560
	s_waitcnt lgkmcnt(0)
	v_mfma_f32_16x16x32_bf16 v[46:49], v[90:93], v[208:211], v[46:49]
	v_mfma_f32_16x16x32_bf16 v[26:29], v[212:215], v[208:211], v[26:29]
	s_waitcnt vmcnt(10)
	ds_write_b128 v207, v[232:235] offset:10240
	v_mfma_f32_16x16x32_bf16 v[14:17], v[216:219], v[208:211], v[14:17]
	v_mfma_f32_16x16x32_bf16 v[10:13], v[220:223], v[208:211], v[10:13]
	ds_read_b128 v[208:211], v205 offset:5120
	s_waitcnt lgkmcnt(0)
	v_mfma_f32_16x16x32_bf16 v[34:37], v[90:93], v[208:211], v[34:37]
	v_mfma_f32_16x16x32_bf16 v[22:25], v[212:215], v[208:211], v[22:25]
	s_waitcnt vmcnt(9)
	ds_write_b128 v207, v[236:239] offset:20480
	v_mfma_f32_16x16x32_bf16 v[18:21], v[216:219], v[208:211], v[18:21]
	v_mfma_f32_16x16x32_bf16 v[62:65], v[220:223], v[208:211], v[62:65]
	ds_read_b128 v[208:211], v205 offset:7680
	s_waitcnt lgkmcnt(0)
	v_mfma_f32_16x16x32_bf16 v[58:61], v[90:93], v[208:211], v[58:61]
	ds_read_b128 v[90:93], v119 offset:64
	v_mfma_f32_16x16x32_bf16 v[54:57], v[212:215], v[208:211], v[54:57]
	s_waitcnt vmcnt(8)
	ds_write_b128 v207, v[240:243] offset:30720
	ds_read_b128 v[212:215], v119 offset:2624
	v_mfma_f32_16x16x32_bf16 v[50:53], v[216:219], v[208:211], v[50:53]
	ds_read_b128 v[216:219], v119 offset:5184
	v_mfma_f32_16x16x32_bf16 v[2:5], v[220:223], v[208:211], v[2:5]
	ds_read_b128 v[220:223], v119 offset:7744
	ds_read_b128 v[208:211], v205 offset:64
	ds_read_b128 v[224:227], v205 offset:7744
	s_waitcnt lgkmcnt(1)
	v_mfma_f32_16x16x32_bf16 v[6:9], v[90:93], v[208:211], v[6:9]
	v_mfma_f32_16x16x32_bf16 v[30:33], v[212:215], v[208:211], v[30:33]
	s_waitcnt vmcnt(7)
	ds_write_b128 v0, v[244:247] offset:20480
	v_mfma_f32_16x16x32_bf16 v[38:41], v[216:219], v[208:211], v[38:41]
	v_mfma_f32_16x16x32_bf16 v[42:45], v[220:223], v[208:211], v[42:45]
	ds_read_b128 v[208:211], v205 offset:2624
	s_waitcnt lgkmcnt(0)
	v_mfma_f32_16x16x32_bf16 v[46:49], v[90:93], v[208:211], v[46:49]
	v_mfma_f32_16x16x32_bf16 v[26:29], v[212:215], v[208:211], v[26:29]
	s_waitcnt vmcnt(6)
	ds_write_b128 v0, v[248:251] offset:30720
	v_mfma_f32_16x16x32_bf16 v[14:17], v[216:219], v[208:211], v[14:17]
	v_mfma_f32_16x16x32_bf16 v[10:13], v[220:223], v[208:211], v[10:13]
	ds_read_b128 v[208:211], v205 offset:5184
	s_waitcnt lgkmcnt(0)
	v_mfma_f32_16x16x32_bf16 v[34:37], v[90:93], v[208:211], v[34:37]
	v_mfma_f32_16x16x32_bf16 v[22:25], v[212:215], v[208:211], v[22:25]
	v_mfma_f32_16x16x32_bf16 v[18:21], v[216:219], v[208:211], v[18:21]
	v_mfma_f32_16x16x32_bf16 v[62:65], v[220:223], v[208:211], v[62:65]
	v_mfma_f32_16x16x32_bf16 v[58:61], v[90:93], v[224:227], v[58:61]
	s_waitcnt lgkmcnt(0)
	v_mfma_f32_16x16x32_bf16 v[54:57], v[212:215], v[224:227], v[54:57]
	s_barrier
	v_mfma_f32_16x16x32_bf16 v[50:53], v[216:219], v[224:227], v[50:53]
	v_mfma_f32_16x16x32_bf16 v[2:5], v[220:223], v[224:227], v[2:5]
	global_load_dwordx4 v[228:231], v190, s[80:81] offset:384
	global_load_dwordx4 v[232:235], v191, s[80:81] offset:384
	global_load_dwordx4 v[236:239], v190, s[86:87] offset:384
	global_load_dwordx4 v[240:243], v191, s[86:87] offset:384
	global_load_dwordx4 v[244:247], v188, s[96:97] offset:384
	global_load_dwordx4 v[248:251], v188, s[98:99] offset:384
	ds_read_b128 v[90:93], v119 offset:20480
	ds_read_b128 v[208:211], v205 offset:40960
	ds_read_b128 v[212:215], v119 offset:23040
	ds_read_b128 v[216:219], v119 offset:25600
	ds_read_b128 v[220:223], v119 offset:28160
	s_waitcnt lgkmcnt(3)
	v_mfma_f32_16x16x32_bf16 v[6:9], v[90:93], v[208:211], v[6:9]
	s_waitcnt lgkmcnt(2)
	v_mfma_f32_16x16x32_bf16 v[30:33], v[212:215], v[208:211], v[30:33]
	s_waitcnt vmcnt(11)
	ds_write_b128 v206, v[66:69] offset:0
	s_waitcnt lgkmcnt(2)
	v_mfma_f32_16x16x32_bf16 v[38:41], v[216:219], v[208:211], v[38:41]
	s_waitcnt lgkmcnt(1)
	v_mfma_f32_16x16x32_bf16 v[42:45], v[220:223], v[208:211], v[42:45]
	ds_read_b128 v[208:211], v205 offset:43520
	s_waitcnt lgkmcnt(0)
	v_mfma_f32_16x16x32_bf16 v[46:49], v[90:93], v[208:211], v[46:49]
	v_mfma_f32_16x16x32_bf16 v[26:29], v[212:215], v[208:211], v[26:29]
	s_waitcnt vmcnt(10)
	ds_write_b128 v206, v[70:73] offset:10240
	v_mfma_f32_16x16x32_bf16 v[14:17], v[216:219], v[208:211], v[14:17]
	v_mfma_f32_16x16x32_bf16 v[10:13], v[220:223], v[208:211], v[10:13]
	ds_read_b128 v[208:211], v205 offset:46080
	s_waitcnt lgkmcnt(0)
	v_mfma_f32_16x16x32_bf16 v[34:37], v[90:93], v[208:211], v[34:37]
	v_mfma_f32_16x16x32_bf16 v[22:25], v[212:215], v[208:211], v[22:25]
	s_waitcnt vmcnt(9)
	ds_write_b128 v206, v[74:77] offset:20480
	v_mfma_f32_16x16x32_bf16 v[18:21], v[216:219], v[208:211], v[18:21]
	v_mfma_f32_16x16x32_bf16 v[62:65], v[220:223], v[208:211], v[62:65]
	ds_read_b128 v[208:211], v205 offset:48640
	s_waitcnt lgkmcnt(0)
	v_mfma_f32_16x16x32_bf16 v[58:61], v[90:93], v[208:211], v[58:61]
	ds_read_b128 v[90:93], v119 offset:20544
	v_mfma_f32_16x16x32_bf16 v[54:57], v[212:215], v[208:211], v[54:57]
	s_waitcnt vmcnt(8)
	ds_write_b128 v206, v[78:81] offset:30720
	ds_read_b128 v[212:215], v119 offset:23104
	v_mfma_f32_16x16x32_bf16 v[50:53], v[216:219], v[208:211], v[50:53]
	ds_read_b128 v[216:219], v119 offset:25664
	v_mfma_f32_16x16x32_bf16 v[2:5], v[220:223], v[208:211], v[2:5]
	ds_read_b128 v[220:223], v119 offset:28224
	ds_read_b128 v[208:211], v205 offset:41024
	ds_read_b128 v[224:227], v205 offset:48704
	s_waitcnt lgkmcnt(1)
	v_mfma_f32_16x16x32_bf16 v[6:9], v[90:93], v[208:211], v[6:9]
	v_mfma_f32_16x16x32_bf16 v[30:33], v[212:215], v[208:211], v[30:33]
	s_waitcnt vmcnt(7)
	ds_write_b128 v0, v[82:85] offset:0
	v_mfma_f32_16x16x32_bf16 v[38:41], v[216:219], v[208:211], v[38:41]
	v_mfma_f32_16x16x32_bf16 v[42:45], v[220:223], v[208:211], v[42:45]
	ds_read_b128 v[208:211], v205 offset:43584
	s_waitcnt lgkmcnt(0)
	v_mfma_f32_16x16x32_bf16 v[46:49], v[90:93], v[208:211], v[46:49]
	v_mfma_f32_16x16x32_bf16 v[26:29], v[212:215], v[208:211], v[26:29]
	s_waitcnt vmcnt(6)
	ds_write_b128 v0, v[86:89] offset:10240
	v_mfma_f32_16x16x32_bf16 v[14:17], v[216:219], v[208:211], v[14:17]
	v_mfma_f32_16x16x32_bf16 v[10:13], v[220:223], v[208:211], v[10:13]
	ds_read_b128 v[208:211], v205 offset:46144
	s_waitcnt lgkmcnt(0)
	v_mfma_f32_16x16x32_bf16 v[34:37], v[90:93], v[208:211], v[34:37]
	v_mfma_f32_16x16x32_bf16 v[22:25], v[212:215], v[208:211], v[22:25]
	v_mfma_f32_16x16x32_bf16 v[18:21], v[216:219], v[208:211], v[18:21]
	v_mfma_f32_16x16x32_bf16 v[62:65], v[220:223], v[208:211], v[62:65]
	v_mfma_f32_16x16x32_bf16 v[58:61], v[90:93], v[224:227], v[58:61]
	s_waitcnt lgkmcnt(0)
	v_mfma_f32_16x16x32_bf16 v[54:57], v[212:215], v[224:227], v[54:57]
	s_barrier
	v_mfma_f32_16x16x32_bf16 v[50:53], v[216:219], v[224:227], v[50:53]
	v_mfma_f32_16x16x32_bf16 v[2:5], v[220:223], v[224:227], v[2:5]
	global_load_dwordx4 v[66:69], v190, s[80:81] offset:512
	global_load_dwordx4 v[70:73], v191, s[80:81] offset:512
	global_load_dwordx4 v[74:77], v190, s[86:87] offset:512
	global_load_dwordx4 v[78:81], v191, s[86:87] offset:512
	global_load_dwordx4 v[82:85], v188, s[96:97] offset:512
	global_load_dwordx4 v[86:89], v188, s[98:99] offset:512
	ds_read_b128 v[90:93], v119 offset:0
	ds_read_b128 v[208:211], v205 offset:0
	ds_read_b128 v[212:215], v119 offset:2560
	ds_read_b128 v[216:219], v119 offset:5120
	ds_read_b128 v[220:223], v119 offset:7680
	s_waitcnt lgkmcnt(3)
	v_mfma_f32_16x16x32_bf16 v[6:9], v[90:93], v[208:211], v[6:9]
	s_waitcnt lgkmcnt(2)
	v_mfma_f32_16x16x32_bf16 v[30:33], v[212:215], v[208:211], v[30:33]
	s_waitcnt vmcnt(11)
	ds_write_b128 v207, v[228:231] offset:0
	s_waitcnt lgkmcnt(2)
	v_mfma_f32_16x16x32_bf16 v[38:41], v[216:219], v[208:211], v[38:41]
	s_waitcnt lgkmcnt(1)
	v_mfma_f32_16x16x32_bf16 v[42:45], v[220:223], v[208:211], v[42:45]
	ds_read_b128 v[208:211], v205 offset:2560
	s_waitcnt lgkmcnt(0)
	v_mfma_f32_16x16x32_bf16 v[46:49], v[90:93], v[208:211], v[46:49]
	v_mfma_f32_16x16x32_bf16 v[26:29], v[212:215], v[208:211], v[26:29]
	s_waitcnt vmcnt(10)
	ds_write_b128 v207, v[232:235] offset:10240
	v_mfma_f32_16x16x32_bf16 v[14:17], v[216:219], v[208:211], v[14:17]
	v_mfma_f32_16x16x32_bf16 v[10:13], v[220:223], v[208:211], v[10:13]
	ds_read_b128 v[208:211], v205 offset:5120
	s_waitcnt lgkmcnt(0)
	v_mfma_f32_16x16x32_bf16 v[34:37], v[90:93], v[208:211], v[34:37]
	v_mfma_f32_16x16x32_bf16 v[22:25], v[212:215], v[208:211], v[22:25]
	s_waitcnt vmcnt(9)
	ds_write_b128 v207, v[236:239] offset:20480
	v_mfma_f32_16x16x32_bf16 v[18:21], v[216:219], v[208:211], v[18:21]
	v_mfma_f32_16x16x32_bf16 v[62:65], v[220:223], v[208:211], v[62:65]
	ds_read_b128 v[208:211], v205 offset:7680
	s_waitcnt lgkmcnt(0)
	v_mfma_f32_16x16x32_bf16 v[58:61], v[90:93], v[208:211], v[58:61]
	ds_read_b128 v[90:93], v119 offset:64
	v_mfma_f32_16x16x32_bf16 v[54:57], v[212:215], v[208:211], v[54:57]
	s_waitcnt vmcnt(8)
	ds_write_b128 v207, v[240:243] offset:30720
	ds_read_b128 v[212:215], v119 offset:2624
	v_mfma_f32_16x16x32_bf16 v[50:53], v[216:219], v[208:211], v[50:53]
	ds_read_b128 v[216:219], v119 offset:5184
	v_mfma_f32_16x16x32_bf16 v[2:5], v[220:223], v[208:211], v[2:5]
	ds_read_b128 v[220:223], v119 offset:7744
	ds_read_b128 v[208:211], v205 offset:64
	ds_read_b128 v[224:227], v205 offset:7744
	s_waitcnt lgkmcnt(1)
	v_mfma_f32_16x16x32_bf16 v[6:9], v[90:93], v[208:211], v[6:9]
	v_mfma_f32_16x16x32_bf16 v[30:33], v[212:215], v[208:211], v[30:33]
	s_waitcnt vmcnt(7)
	ds_write_b128 v0, v[244:247] offset:20480
	v_mfma_f32_16x16x32_bf16 v[38:41], v[216:219], v[208:211], v[38:41]
	v_mfma_f32_16x16x32_bf16 v[42:45], v[220:223], v[208:211], v[42:45]
	ds_read_b128 v[208:211], v205 offset:2624
	s_waitcnt lgkmcnt(0)
	v_mfma_f32_16x16x32_bf16 v[46:49], v[90:93], v[208:211], v[46:49]
	v_mfma_f32_16x16x32_bf16 v[26:29], v[212:215], v[208:211], v[26:29]
	s_waitcnt vmcnt(6)
	ds_write_b128 v0, v[248:251] offset:30720
	v_mfma_f32_16x16x32_bf16 v[14:17], v[216:219], v[208:211], v[14:17]
	v_mfma_f32_16x16x32_bf16 v[10:13], v[220:223], v[208:211], v[10:13]
	ds_read_b128 v[208:211], v205 offset:5184
	s_waitcnt lgkmcnt(0)
	v_mfma_f32_16x16x32_bf16 v[34:37], v[90:93], v[208:211], v[34:37]
	v_mfma_f32_16x16x32_bf16 v[22:25], v[212:215], v[208:211], v[22:25]
	v_mfma_f32_16x16x32_bf16 v[18:21], v[216:219], v[208:211], v[18:21]
	v_mfma_f32_16x16x32_bf16 v[62:65], v[220:223], v[208:211], v[62:65]
	v_mfma_f32_16x16x32_bf16 v[58:61], v[90:93], v[224:227], v[58:61]
	s_waitcnt lgkmcnt(0)
	v_mfma_f32_16x16x32_bf16 v[54:57], v[212:215], v[224:227], v[54:57]
	s_barrier
	v_mfma_f32_16x16x32_bf16 v[50:53], v[216:219], v[224:227], v[50:53]
	v_mfma_f32_16x16x32_bf16 v[2:5], v[220:223], v[224:227], v[2:5]
	global_load_dwordx4 v[228:231], v190, s[80:81] offset:640
	global_load_dwordx4 v[232:235], v191, s[80:81] offset:640
	global_load_dwordx4 v[236:239], v190, s[86:87] offset:640
	global_load_dwordx4 v[240:243], v191, s[86:87] offset:640
	global_load_dwordx4 v[244:247], v188, s[96:97] offset:640
	global_load_dwordx4 v[248:251], v188, s[98:99] offset:640
	ds_read_b128 v[90:93], v119 offset:20480
	ds_read_b128 v[208:211], v205 offset:40960
	ds_read_b128 v[212:215], v119 offset:23040
	ds_read_b128 v[216:219], v119 offset:25600
	ds_read_b128 v[220:223], v119 offset:28160
	s_waitcnt lgkmcnt(3)
	v_mfma_f32_16x16x32_bf16 v[6:9], v[90:93], v[208:211], v[6:9]
	s_waitcnt lgkmcnt(2)
	v_mfma_f32_16x16x32_bf16 v[30:33], v[212:215], v[208:211], v[30:33]
	s_waitcnt vmcnt(11)
	ds_write_b128 v206, v[66:69] offset:0
	s_waitcnt lgkmcnt(2)
	v_mfma_f32_16x16x32_bf16 v[38:41], v[216:219], v[208:211], v[38:41]
	s_waitcnt lgkmcnt(1)
	v_mfma_f32_16x16x32_bf16 v[42:45], v[220:223], v[208:211], v[42:45]
	ds_read_b128 v[208:211], v205 offset:43520
	s_waitcnt lgkmcnt(0)
	v_mfma_f32_16x16x32_bf16 v[46:49], v[90:93], v[208:211], v[46:49]
	v_mfma_f32_16x16x32_bf16 v[26:29], v[212:215], v[208:211], v[26:29]
	s_waitcnt vmcnt(10)
	ds_write_b128 v206, v[70:73] offset:10240
	v_mfma_f32_16x16x32_bf16 v[14:17], v[216:219], v[208:211], v[14:17]
	v_mfma_f32_16x16x32_bf16 v[10:13], v[220:223], v[208:211], v[10:13]
	ds_read_b128 v[208:211], v205 offset:46080
	s_waitcnt lgkmcnt(0)
	v_mfma_f32_16x16x32_bf16 v[34:37], v[90:93], v[208:211], v[34:37]
	v_mfma_f32_16x16x32_bf16 v[22:25], v[212:215], v[208:211], v[22:25]
	s_waitcnt vmcnt(9)
	ds_write_b128 v206, v[74:77] offset:20480
	v_mfma_f32_16x16x32_bf16 v[18:21], v[216:219], v[208:211], v[18:21]
	v_mfma_f32_16x16x32_bf16 v[62:65], v[220:223], v[208:211], v[62:65]
	ds_read_b128 v[208:211], v205 offset:48640
	s_waitcnt lgkmcnt(0)
	v_mfma_f32_16x16x32_bf16 v[58:61], v[90:93], v[208:211], v[58:61]
	ds_read_b128 v[90:93], v119 offset:20544
	v_mfma_f32_16x16x32_bf16 v[54:57], v[212:215], v[208:211], v[54:57]
	s_waitcnt vmcnt(8)
	ds_write_b128 v206, v[78:81] offset:30720
	ds_read_b128 v[212:215], v119 offset:23104
	v_mfma_f32_16x16x32_bf16 v[50:53], v[216:219], v[208:211], v[50:53]
	ds_read_b128 v[216:219], v119 offset:25664
	v_mfma_f32_16x16x32_bf16 v[2:5], v[220:223], v[208:211], v[2:5]
	ds_read_b128 v[220:223], v119 offset:28224
	ds_read_b128 v[208:211], v205 offset:41024
	ds_read_b128 v[224:227], v205 offset:48704
	s_waitcnt lgkmcnt(1)
	v_mfma_f32_16x16x32_bf16 v[6:9], v[90:93], v[208:211], v[6:9]
	v_mfma_f32_16x16x32_bf16 v[30:33], v[212:215], v[208:211], v[30:33]
	s_waitcnt vmcnt(7)
	ds_write_b128 v0, v[82:85] offset:0
	v_mfma_f32_16x16x32_bf16 v[38:41], v[216:219], v[208:211], v[38:41]
	v_mfma_f32_16x16x32_bf16 v[42:45], v[220:223], v[208:211], v[42:45]
	ds_read_b128 v[208:211], v205 offset:43584
	s_waitcnt lgkmcnt(0)
	v_mfma_f32_16x16x32_bf16 v[46:49], v[90:93], v[208:211], v[46:49]
	v_mfma_f32_16x16x32_bf16 v[26:29], v[212:215], v[208:211], v[26:29]
	s_waitcnt vmcnt(6)
	ds_write_b128 v0, v[86:89] offset:10240
	v_mfma_f32_16x16x32_bf16 v[14:17], v[216:219], v[208:211], v[14:17]
	v_mfma_f32_16x16x32_bf16 v[10:13], v[220:223], v[208:211], v[10:13]
	ds_read_b128 v[208:211], v205 offset:46144
	s_waitcnt lgkmcnt(0)
	v_mfma_f32_16x16x32_bf16 v[34:37], v[90:93], v[208:211], v[34:37]
	v_mfma_f32_16x16x32_bf16 v[22:25], v[212:215], v[208:211], v[22:25]
	v_mfma_f32_16x16x32_bf16 v[18:21], v[216:219], v[208:211], v[18:21]
	v_mfma_f32_16x16x32_bf16 v[62:65], v[220:223], v[208:211], v[62:65]
	v_mfma_f32_16x16x32_bf16 v[58:61], v[90:93], v[224:227], v[58:61]
	s_waitcnt lgkmcnt(0)
	v_mfma_f32_16x16x32_bf16 v[54:57], v[212:215], v[224:227], v[54:57]
	s_barrier
	v_mfma_f32_16x16x32_bf16 v[50:53], v[216:219], v[224:227], v[50:53]
	v_mfma_f32_16x16x32_bf16 v[2:5], v[220:223], v[224:227], v[2:5]
	global_load_dwordx4 v[66:69], v190, s[80:81] offset:768
	global_load_dwordx4 v[70:73], v191, s[80:81] offset:768
	global_load_dwordx4 v[74:77], v190, s[86:87] offset:768
	global_load_dwordx4 v[78:81], v191, s[86:87] offset:768
	global_load_dwordx4 v[82:85], v188, s[96:97] offset:768
	global_load_dwordx4 v[86:89], v188, s[98:99] offset:768
	ds_read_b128 v[90:93], v119 offset:0
	ds_read_b128 v[208:211], v205 offset:0
	ds_read_b128 v[212:215], v119 offset:2560
	ds_read_b128 v[216:219], v119 offset:5120
	ds_read_b128 v[220:223], v119 offset:7680
	s_waitcnt lgkmcnt(3)
	v_mfma_f32_16x16x32_bf16 v[6:9], v[90:93], v[208:211], v[6:9]
	s_waitcnt lgkmcnt(2)
	v_mfma_f32_16x16x32_bf16 v[30:33], v[212:215], v[208:211], v[30:33]
	s_waitcnt vmcnt(11)
	ds_write_b128 v207, v[228:231] offset:0
	s_waitcnt lgkmcnt(2)
	v_mfma_f32_16x16x32_bf16 v[38:41], v[216:219], v[208:211], v[38:41]
	s_waitcnt lgkmcnt(1)
	v_mfma_f32_16x16x32_bf16 v[42:45], v[220:223], v[208:211], v[42:45]
	ds_read_b128 v[208:211], v205 offset:2560
	s_waitcnt lgkmcnt(0)
	v_mfma_f32_16x16x32_bf16 v[46:49], v[90:93], v[208:211], v[46:49]
	v_mfma_f32_16x16x32_bf16 v[26:29], v[212:215], v[208:211], v[26:29]
	s_waitcnt vmcnt(10)
	ds_write_b128 v207, v[232:235] offset:10240
	v_mfma_f32_16x16x32_bf16 v[14:17], v[216:219], v[208:211], v[14:17]
	v_mfma_f32_16x16x32_bf16 v[10:13], v[220:223], v[208:211], v[10:13]
	ds_read_b128 v[208:211], v205 offset:5120
	s_waitcnt lgkmcnt(0)
	v_mfma_f32_16x16x32_bf16 v[34:37], v[90:93], v[208:211], v[34:37]
	v_mfma_f32_16x16x32_bf16 v[22:25], v[212:215], v[208:211], v[22:25]
	s_waitcnt vmcnt(9)
	ds_write_b128 v207, v[236:239] offset:20480
	v_mfma_f32_16x16x32_bf16 v[18:21], v[216:219], v[208:211], v[18:21]
	v_mfma_f32_16x16x32_bf16 v[62:65], v[220:223], v[208:211], v[62:65]
	ds_read_b128 v[208:211], v205 offset:7680
	s_waitcnt lgkmcnt(0)
	v_mfma_f32_16x16x32_bf16 v[58:61], v[90:93], v[208:211], v[58:61]
	ds_read_b128 v[90:93], v119 offset:64
	v_mfma_f32_16x16x32_bf16 v[54:57], v[212:215], v[208:211], v[54:57]
	s_waitcnt vmcnt(8)
	ds_write_b128 v207, v[240:243] offset:30720
	ds_read_b128 v[212:215], v119 offset:2624
	v_mfma_f32_16x16x32_bf16 v[50:53], v[216:219], v[208:211], v[50:53]
	ds_read_b128 v[216:219], v119 offset:5184
	v_mfma_f32_16x16x32_bf16 v[2:5], v[220:223], v[208:211], v[2:5]
	ds_read_b128 v[220:223], v119 offset:7744
	ds_read_b128 v[208:211], v205 offset:64
	ds_read_b128 v[224:227], v205 offset:7744
	s_waitcnt lgkmcnt(1)
	v_mfma_f32_16x16x32_bf16 v[6:9], v[90:93], v[208:211], v[6:9]
	v_mfma_f32_16x16x32_bf16 v[30:33], v[212:215], v[208:211], v[30:33]
	s_waitcnt vmcnt(7)
	ds_write_b128 v0, v[244:247] offset:20480
	v_mfma_f32_16x16x32_bf16 v[38:41], v[216:219], v[208:211], v[38:41]
	v_mfma_f32_16x16x32_bf16 v[42:45], v[220:223], v[208:211], v[42:45]
	ds_read_b128 v[208:211], v205 offset:2624
	s_waitcnt lgkmcnt(0)
	v_mfma_f32_16x16x32_bf16 v[46:49], v[90:93], v[208:211], v[46:49]
	v_mfma_f32_16x16x32_bf16 v[26:29], v[212:215], v[208:211], v[26:29]
	s_waitcnt vmcnt(6)
	ds_write_b128 v0, v[248:251] offset:30720
	v_mfma_f32_16x16x32_bf16 v[14:17], v[216:219], v[208:211], v[14:17]
	v_mfma_f32_16x16x32_bf16 v[10:13], v[220:223], v[208:211], v[10:13]
	ds_read_b128 v[208:211], v205 offset:5184
	s_waitcnt lgkmcnt(0)
	v_mfma_f32_16x16x32_bf16 v[34:37], v[90:93], v[208:211], v[34:37]
	v_mfma_f32_16x16x32_bf16 v[22:25], v[212:215], v[208:211], v[22:25]
	v_mfma_f32_16x16x32_bf16 v[18:21], v[216:219], v[208:211], v[18:21]
	v_mfma_f32_16x16x32_bf16 v[62:65], v[220:223], v[208:211], v[62:65]
	v_mfma_f32_16x16x32_bf16 v[58:61], v[90:93], v[224:227], v[58:61]
	s_waitcnt lgkmcnt(0)
	v_mfma_f32_16x16x32_bf16 v[54:57], v[212:215], v[224:227], v[54:57]
	s_barrier
	v_mfma_f32_16x16x32_bf16 v[50:53], v[216:219], v[224:227], v[50:53]
	v_mfma_f32_16x16x32_bf16 v[2:5], v[220:223], v[224:227], v[2:5]
	global_load_dwordx4 v[228:231], v190, s[80:81] offset:896
	global_load_dwordx4 v[232:235], v191, s[80:81] offset:896
	global_load_dwordx4 v[236:239], v190, s[86:87] offset:896
	global_load_dwordx4 v[240:243], v191, s[86:87] offset:896
	global_load_dwordx4 v[244:247], v188, s[96:97] offset:896
	global_load_dwordx4 v[248:251], v188, s[98:99] offset:896
	ds_read_b128 v[90:93], v119 offset:20480
	ds_read_b128 v[208:211], v205 offset:40960
	ds_read_b128 v[212:215], v119 offset:23040
	ds_read_b128 v[216:219], v119 offset:25600
	ds_read_b128 v[220:223], v119 offset:28160
	s_waitcnt lgkmcnt(3)
	v_mfma_f32_16x16x32_bf16 v[6:9], v[90:93], v[208:211], v[6:9]
	s_waitcnt lgkmcnt(2)
	v_mfma_f32_16x16x32_bf16 v[30:33], v[212:215], v[208:211], v[30:33]
	s_waitcnt vmcnt(11)
	ds_write_b128 v206, v[66:69] offset:0
	s_waitcnt lgkmcnt(2)
	v_mfma_f32_16x16x32_bf16 v[38:41], v[216:219], v[208:211], v[38:41]
	s_waitcnt lgkmcnt(1)
	v_mfma_f32_16x16x32_bf16 v[42:45], v[220:223], v[208:211], v[42:45]
	ds_read_b128 v[208:211], v205 offset:43520
	s_waitcnt lgkmcnt(0)
	v_mfma_f32_16x16x32_bf16 v[46:49], v[90:93], v[208:211], v[46:49]
	v_mfma_f32_16x16x32_bf16 v[26:29], v[212:215], v[208:211], v[26:29]
	s_waitcnt vmcnt(10)
	ds_write_b128 v206, v[70:73] offset:10240
	v_mfma_f32_16x16x32_bf16 v[14:17], v[216:219], v[208:211], v[14:17]
	v_mfma_f32_16x16x32_bf16 v[10:13], v[220:223], v[208:211], v[10:13]
	ds_read_b128 v[208:211], v205 offset:46080
	s_waitcnt lgkmcnt(0)
	v_mfma_f32_16x16x32_bf16 v[34:37], v[90:93], v[208:211], v[34:37]
	v_mfma_f32_16x16x32_bf16 v[22:25], v[212:215], v[208:211], v[22:25]
	s_waitcnt vmcnt(9)
	ds_write_b128 v206, v[74:77] offset:20480
	v_mfma_f32_16x16x32_bf16 v[18:21], v[216:219], v[208:211], v[18:21]
	v_mfma_f32_16x16x32_bf16 v[62:65], v[220:223], v[208:211], v[62:65]
	ds_read_b128 v[208:211], v205 offset:48640
	s_waitcnt lgkmcnt(0)
	v_mfma_f32_16x16x32_bf16 v[58:61], v[90:93], v[208:211], v[58:61]
	ds_read_b128 v[90:93], v119 offset:20544
	v_mfma_f32_16x16x32_bf16 v[54:57], v[212:215], v[208:211], v[54:57]
	s_waitcnt vmcnt(8)
	ds_write_b128 v206, v[78:81] offset:30720
	ds_read_b128 v[212:215], v119 offset:23104
	v_mfma_f32_16x16x32_bf16 v[50:53], v[216:219], v[208:211], v[50:53]
	ds_read_b128 v[216:219], v119 offset:25664
	v_mfma_f32_16x16x32_bf16 v[2:5], v[220:223], v[208:211], v[2:5]
	ds_read_b128 v[220:223], v119 offset:28224
	ds_read_b128 v[208:211], v205 offset:41024
	ds_read_b128 v[224:227], v205 offset:48704
	s_waitcnt lgkmcnt(1)
	v_mfma_f32_16x16x32_bf16 v[6:9], v[90:93], v[208:211], v[6:9]
	v_mfma_f32_16x16x32_bf16 v[30:33], v[212:215], v[208:211], v[30:33]
	s_waitcnt vmcnt(7)
	ds_write_b128 v0, v[82:85] offset:0
	v_mfma_f32_16x16x32_bf16 v[38:41], v[216:219], v[208:211], v[38:41]
	v_mfma_f32_16x16x32_bf16 v[42:45], v[220:223], v[208:211], v[42:45]
	ds_read_b128 v[208:211], v205 offset:43584
	s_waitcnt lgkmcnt(0)
	v_mfma_f32_16x16x32_bf16 v[46:49], v[90:93], v[208:211], v[46:49]
	v_mfma_f32_16x16x32_bf16 v[26:29], v[212:215], v[208:211], v[26:29]
	s_waitcnt vmcnt(6)
	ds_write_b128 v0, v[86:89] offset:10240
	s_movk_i32 s10, 0x0
	s_mov_b32 s11, 0
	v_lshl_add_u64 v[82:83], v[128:129], 0, s[10:11]
	v_lshl_add_u64 v[84:85], v[132:133], 0, s[10:11]
	v_lshl_add_u64 v[86:87], v[152:153], 0, s[10:11]
	v_lshl_add_u64 v[88:89], v[154:155], 0, s[10:11]
	global_load_dwordx2 v[66:67], v[82:83], off
	global_load_dwordx2 v[68:69], v[82:83], off offset:32
	global_load_dwordx2 v[70:71], v[84:85], off
	global_load_dwordx2 v[72:73], v[84:85], off offset:32
	global_load_dwordx2 v[74:75], v[86:87], off
	global_load_dwordx2 v[76:77], v[86:87], off offset:32
	global_load_dwordx2 v[78:79], v[88:89], off
	global_load_dwordx2 v[80:81], v[88:89], off offset:32
	v_mfma_f32_16x16x32_bf16 v[14:17], v[216:219], v[208:211], v[14:17]
	v_mfma_f32_16x16x32_bf16 v[10:13], v[220:223], v[208:211], v[10:13]
	ds_read_b128 v[208:211], v205 offset:46144
	s_waitcnt lgkmcnt(0)
	v_mfma_f32_16x16x32_bf16 v[34:37], v[90:93], v[208:211], v[34:37]
	v_mfma_f32_16x16x32_bf16 v[22:25], v[212:215], v[208:211], v[22:25]
	v_mfma_f32_16x16x32_bf16 v[18:21], v[216:219], v[208:211], v[18:21]
	v_mfma_f32_16x16x32_bf16 v[62:65], v[220:223], v[208:211], v[62:65]
	v_mfma_f32_16x16x32_bf16 v[58:61], v[90:93], v[224:227], v[58:61]
	s_waitcnt lgkmcnt(0)
	v_mfma_f32_16x16x32_bf16 v[54:57], v[212:215], v[224:227], v[54:57]
	s_barrier
	v_mfma_f32_16x16x32_bf16 v[50:53], v[216:219], v[224:227], v[50:53]
	v_mfma_f32_16x16x32_bf16 v[2:5], v[220:223], v[224:227], v[2:5]
	ds_read_b128 v[90:93], v119 offset:0
	ds_read_b128 v[208:211], v205 offset:0
	ds_read_b128 v[212:215], v119 offset:2560
	ds_read_b128 v[216:219], v119 offset:5120
	ds_read_b128 v[220:223], v119 offset:7680
	s_waitcnt lgkmcnt(3)
	v_mfma_f32_16x16x32_bf16 v[6:9], v[90:93], v[208:211], v[6:9]
	s_waitcnt lgkmcnt(2)
	v_mfma_f32_16x16x32_bf16 v[30:33], v[212:215], v[208:211], v[30:33]
	s_waitcnt vmcnt(13)
	ds_write_b128 v207, v[228:231] offset:0
	s_waitcnt lgkmcnt(2)
	v_mfma_f32_16x16x32_bf16 v[38:41], v[216:219], v[208:211], v[38:41]
	s_waitcnt lgkmcnt(1)
	v_mfma_f32_16x16x32_bf16 v[42:45], v[220:223], v[208:211], v[42:45]
	ds_read_b128 v[208:211], v205 offset:2560
	s_waitcnt lgkmcnt(0)
	v_mfma_f32_16x16x32_bf16 v[46:49], v[90:93], v[208:211], v[46:49]
	v_mfma_f32_16x16x32_bf16 v[26:29], v[212:215], v[208:211], v[26:29]
	s_waitcnt vmcnt(12)
	ds_write_b128 v207, v[232:235] offset:10240
	v_mfma_f32_16x16x32_bf16 v[14:17], v[216:219], v[208:211], v[14:17]
	v_mfma_f32_16x16x32_bf16 v[10:13], v[220:223], v[208:211], v[10:13]
	ds_read_b128 v[208:211], v205 offset:5120
	s_waitcnt lgkmcnt(0)
	v_mfma_f32_16x16x32_bf16 v[34:37], v[90:93], v[208:211], v[34:37]
	v_mfma_f32_16x16x32_bf16 v[22:25], v[212:215], v[208:211], v[22:25]
	s_waitcnt vmcnt(11)
	ds_write_b128 v207, v[236:239] offset:20480
	v_mfma_f32_16x16x32_bf16 v[18:21], v[216:219], v[208:211], v[18:21]
	v_mfma_f32_16x16x32_bf16 v[62:65], v[220:223], v[208:211], v[62:65]
	ds_read_b128 v[208:211], v205 offset:7680
	s_waitcnt lgkmcnt(0)
	v_mfma_f32_16x16x32_bf16 v[58:61], v[90:93], v[208:211], v[58:61]
	ds_read_b128 v[90:93], v119 offset:64
	v_mfma_f32_16x16x32_bf16 v[54:57], v[212:215], v[208:211], v[54:57]
	s_waitcnt vmcnt(10)
	ds_write_b128 v207, v[240:243] offset:30720
	ds_read_b128 v[212:215], v119 offset:2624
	v_mfma_f32_16x16x32_bf16 v[50:53], v[216:219], v[208:211], v[50:53]
	ds_read_b128 v[216:219], v119 offset:5184
	v_mfma_f32_16x16x32_bf16 v[2:5], v[220:223], v[208:211], v[2:5]
	ds_read_b128 v[220:223], v119 offset:7744
	ds_read_b128 v[208:211], v205 offset:64
	ds_read_b128 v[224:227], v205 offset:7744
	s_waitcnt lgkmcnt(1)
	v_mfma_f32_16x16x32_bf16 v[6:9], v[90:93], v[208:211], v[6:9]
	v_mfma_f32_16x16x32_bf16 v[30:33], v[212:215], v[208:211], v[30:33]
	s_waitcnt vmcnt(9)
	ds_write_b128 v0, v[244:247] offset:20480
	v_mfma_f32_16x16x32_bf16 v[38:41], v[216:219], v[208:211], v[38:41]
	v_mfma_f32_16x16x32_bf16 v[42:45], v[220:223], v[208:211], v[42:45]
	ds_read_b128 v[208:211], v205 offset:2624
	s_waitcnt lgkmcnt(0)
	v_mfma_f32_16x16x32_bf16 v[46:49], v[90:93], v[208:211], v[46:49]
	v_mfma_f32_16x16x32_bf16 v[26:29], v[212:215], v[208:211], v[26:29]
	s_waitcnt vmcnt(8)
	ds_write_b128 v0, v[248:251] offset:30720
	s_add_u32 s80, s80, 0x400
	s_addc_u32 s81, s81, 0
	s_add_u32 s86, s80, 0x1f0000
	s_addc_u32 s87, s81, 0
	s_add_u32 s96, s96, 0x100000
	s_addc_u32 s97, s97, 0
	s_add_u32 s98, s96, 0x10000
	s_addc_u32 s99, s97, 0
	global_load_dwordx4 v[228:231], v190, s[80:81] offset:0
	global_load_dwordx4 v[232:235], v191, s[80:81] offset:0
	global_load_dwordx4 v[236:239], v190, s[86:87] offset:0
	global_load_dwordx4 v[240:243], v191, s[86:87] offset:0
	global_load_dwordx4 v[244:247], v188, s[96:97] offset:0
	global_load_dwordx4 v[248:251], v188, s[98:99] offset:0
	v_mfma_f32_16x16x32_bf16 v[14:17], v[216:219], v[208:211], v[14:17]
	v_mfma_f32_16x16x32_bf16 v[10:13], v[220:223], v[208:211], v[10:13]
	ds_read_b128 v[208:211], v205 offset:5184
	s_waitcnt lgkmcnt(0)
	v_mfma_f32_16x16x32_bf16 v[34:37], v[90:93], v[208:211], v[34:37]
	v_mfma_f32_16x16x32_bf16 v[22:25], v[212:215], v[208:211], v[22:25]
	v_mfma_f32_16x16x32_bf16 v[18:21], v[216:219], v[208:211], v[18:21]
	v_mfma_f32_16x16x32_bf16 v[62:65], v[220:223], v[208:211], v[62:65]
	v_mfma_f32_16x16x32_bf16 v[58:61], v[90:93], v[224:227], v[58:61]
	s_waitcnt lgkmcnt(0)
	v_mfma_f32_16x16x32_bf16 v[54:57], v[212:215], v[224:227], v[54:57]
	s_barrier
	v_mfma_f32_16x16x32_bf16 v[50:53], v[216:219], v[224:227], v[50:53]
	v_mfma_f32_16x16x32_bf16 v[2:5], v[220:223], v[224:227], v[2:5]
	ds_read_b128 v[90:93], v119 offset:20480
	ds_read_b128 v[208:211], v205 offset:40960
	ds_read_b128 v[212:215], v119 offset:23040
	ds_read_b128 v[216:219], v119 offset:25600
	ds_read_b128 v[220:223], v119 offset:28160
	s_waitcnt lgkmcnt(3)
	v_mfma_f32_16x16x32_bf16 v[6:9], v[90:93], v[208:211], v[6:9]
	s_waitcnt lgkmcnt(2)
	v_mfma_f32_16x16x32_bf16 v[30:33], v[212:215], v[208:211], v[30:33]
	s_waitcnt lgkmcnt(1)
	v_mfma_f32_16x16x32_bf16 v[38:41], v[216:219], v[208:211], v[38:41]
	s_waitcnt lgkmcnt(0)
	v_mfma_f32_16x16x32_bf16 v[42:45], v[220:223], v[208:211], v[42:45]
	ds_read_b128 v[208:211], v205 offset:43520
	s_waitcnt lgkmcnt(0)
	v_mfma_f32_16x16x32_bf16 v[46:49], v[90:93], v[208:211], v[46:49]
	v_mfma_f32_16x16x32_bf16 v[26:29], v[212:215], v[208:211], v[26:29]
	v_mfma_f32_16x16x32_bf16 v[14:17], v[216:219], v[208:211], v[14:17]
	v_mfma_f32_16x16x32_bf16 v[10:13], v[220:223], v[208:211], v[10:13]
	ds_read_b128 v[208:211], v205 offset:46080
	s_waitcnt lgkmcnt(0)
	v_mfma_f32_16x16x32_bf16 v[34:37], v[90:93], v[208:211], v[34:37]
	v_mfma_f32_16x16x32_bf16 v[22:25], v[212:215], v[208:211], v[22:25]
	v_mfma_f32_16x16x32_bf16 v[18:21], v[216:219], v[208:211], v[18:21]
	v_mfma_f32_16x16x32_bf16 v[62:65], v[220:223], v[208:211], v[62:65]
	ds_read_b128 v[208:211], v205 offset:48640
	s_waitcnt lgkmcnt(0)
	v_mfma_f32_16x16x32_bf16 v[58:61], v[90:93], v[208:211], v[58:61]
	ds_read_b128 v[90:93], v119 offset:20544
	v_mfma_f32_16x16x32_bf16 v[54:57], v[212:215], v[208:211], v[54:57]
	ds_read_b128 v[212:215], v119 offset:23104
	v_mfma_f32_16x16x32_bf16 v[50:53], v[216:219], v[208:211], v[50:53]
	ds_read_b128 v[216:219], v119 offset:25664
	v_mfma_f32_16x16x32_bf16 v[2:5], v[220:223], v[208:211], v[2:5]
	ds_read_b128 v[220:223], v119 offset:28224
	ds_read_b128 v[208:211], v205 offset:41024
	ds_read_b128 v[224:227], v205 offset:48704
	s_waitcnt lgkmcnt(1)
	v_mfma_f32_16x16x32_bf16 v[6:9], v[90:93], v[208:211], v[6:9]
	s_waitcnt vmcnt(6)
	v_mfma_f32_16x16x32_bf16 v[30:33], v[212:215], v[208:211], v[30:33]
	v_mfma_f32_16x16x32_bf16 v[38:41], v[216:219], v[208:211], v[38:41]
	v_mfma_f32_16x16x32_bf16 v[42:45], v[220:223], v[208:211], v[42:45]
	v_cvt_f32_ubyte0_e32 v86, v66
	v_cvt_f32_ubyte1_e32 v87, v66
	v_cvt_f32_ubyte2_e32 v88, v66
	v_cvt_f32_ubyte3_e32 v89, v66
	v_mul_f32_e32 v86, s34, v86
	v_mul_f32_e32 v87, s34, v87
	v_mul_f32_e32 v88, s34, v88
	v_mul_f32_e32 v89, s34, v89
	v_fma_f32 v184, v6, v86, v184
	v_fma_f32 v185, v7, v87, v185
	v_fma_f32 v186, v8, v88, v186
	v_fma_f32 v187, v9, v89, v187
	ds_read_b128 v[208:211], v205 offset:43584
	s_waitcnt lgkmcnt(0)
	v_mfma_f32_16x16x32_bf16 v[46:49], v[90:93], v[208:211], v[46:49]
	v_cvt_f32_ubyte0_e32 v82, v67
	v_cvt_f32_ubyte1_e32 v83, v67
	v_cvt_f32_ubyte2_e32 v84, v67
	v_cvt_f32_ubyte3_e32 v85, v67
	v_mul_f32_e32 v82, s34, v82
	v_mul_f32_e32 v83, s34, v83
	v_mul_f32_e32 v84, s34, v84
	v_mul_f32_e32 v85, s34, v85
	v_fma_f32 v180, v30, v82, v180
	v_fma_f32 v181, v31, v83, v181
	v_fma_f32 v182, v32, v84, v182
	v_fma_f32 v183, v33, v85, v183
	v_mfma_f32_16x16x32_bf16 v[26:29], v[212:215], v[208:211], v[26:29]
	v_cvt_f32_ubyte0_e32 v86, v68
	v_cvt_f32_ubyte1_e32 v87, v68
	v_cvt_f32_ubyte2_e32 v88, v68
	v_cvt_f32_ubyte3_e32 v89, v68
	v_mul_f32_e32 v86, s34, v86
	v_mul_f32_e32 v87, s34, v87
	v_mul_f32_e32 v88, s34, v88
	v_mul_f32_e32 v89, s34, v89
	v_fma_f32 v176, v38, v86, v176
	v_fma_f32 v177, v39, v87, v177
	v_fma_f32 v178, v40, v88, v178
	v_fma_f32 v179, v41, v89, v179
	v_mfma_f32_16x16x32_bf16 v[14:17], v[216:219], v[208:211], v[14:17]
	v_cvt_f32_ubyte0_e32 v82, v69
	v_cvt_f32_ubyte1_e32 v83, v69
	v_cvt_f32_ubyte2_e32 v84, v69
	v_cvt_f32_ubyte3_e32 v85, v69
	v_mul_f32_e32 v82, s34, v82
	v_mul_f32_e32 v83, s34, v83
	v_mul_f32_e32 v84, s34, v84
	v_mul_f32_e32 v85, s34, v85
	v_fma_f32 v172, v42, v82, v172
	v_fma_f32 v173, v43, v83, v173
	v_fma_f32 v174, v44, v84, v174
	v_fma_f32 v175, v45, v85, v175
	v_mfma_f32_16x16x32_bf16 v[10:13], v[220:223], v[208:211], v[10:13]
	v_cvt_f32_ubyte0_e32 v86, v70
	v_cvt_f32_ubyte1_e32 v87, v70
	v_cvt_f32_ubyte2_e32 v88, v70
	v_cvt_f32_ubyte3_e32 v89, v70
	v_mul_f32_e32 v86, s34, v86
	v_mul_f32_e32 v87, s34, v87
	v_mul_f32_e32 v88, s34, v88
	v_mul_f32_e32 v89, s34, v89
	v_fma_f32 v168, v46, v86, v168
	v_fma_f32 v169, v47, v87, v169
	v_fma_f32 v170, v48, v88, v170
	v_fma_f32 v171, v49, v89, v171
	ds_read_b128 v[208:211], v205 offset:46144
	s_waitcnt lgkmcnt(0)
	v_mfma_f32_16x16x32_bf16 v[34:37], v[90:93], v[208:211], v[34:37]
	v_cvt_f32_ubyte0_e32 v82, v71
	v_cvt_f32_ubyte1_e32 v83, v71
	v_cvt_f32_ubyte2_e32 v84, v71
	v_cvt_f32_ubyte3_e32 v85, v71
	v_mul_f32_e32 v82, s34, v82
	v_mul_f32_e32 v83, s34, v83
	v_mul_f32_e32 v84, s34, v84
	v_mul_f32_e32 v85, s34, v85
	v_fma_f32 v164, v26, v82, v164
	v_fma_f32 v165, v27, v83, v165
	v_fma_f32 v166, v28, v84, v166
	v_fma_f32 v167, v29, v85, v167
	v_mfma_f32_16x16x32_bf16 v[22:25], v[212:215], v[208:211], v[22:25]
	v_cvt_f32_ubyte0_e32 v86, v72
	v_cvt_f32_ubyte1_e32 v87, v72
	v_cvt_f32_ubyte2_e32 v88, v72
	v_cvt_f32_ubyte3_e32 v89, v72
	v_mul_f32_e32 v86, s34, v86
	v_mul_f32_e32 v87, s34, v87
	v_mul_f32_e32 v88, s34, v88
	v_mul_f32_e32 v89, s34, v89
	v_fma_f32 v160, v14, v86, v160
	v_fma_f32 v161, v15, v87, v161
	v_fma_f32 v162, v16, v88, v162
	v_fma_f32 v163, v17, v89, v163
	v_mfma_f32_16x16x32_bf16 v[18:21], v[216:219], v[208:211], v[18:21]
	v_cvt_f32_ubyte0_e32 v82, v73
	v_cvt_f32_ubyte1_e32 v83, v73
	v_cvt_f32_ubyte2_e32 v84, v73
	v_cvt_f32_ubyte3_e32 v85, v73
	v_mul_f32_e32 v82, s34, v82
	v_mul_f32_e32 v83, s34, v83
	v_mul_f32_e32 v84, s34, v84
	v_mul_f32_e32 v85, s34, v85
	v_fma_f32 v156, v10, v82, v156
	v_fma_f32 v157, v11, v83, v157
	v_fma_f32 v158, v12, v84, v158
	v_fma_f32 v159, v13, v85, v159
	v_mfma_f32_16x16x32_bf16 v[62:65], v[220:223], v[208:211], v[62:65]
	v_cvt_f32_ubyte0_e32 v86, v74
	v_cvt_f32_ubyte1_e32 v87, v74
	v_cvt_f32_ubyte2_e32 v88, v74
	v_cvt_f32_ubyte3_e32 v89, v74
	v_mul_f32_e32 v86, s34, v86
	v_mul_f32_e32 v87, s34, v87
	v_mul_f32_e32 v88, s34, v88
	v_mul_f32_e32 v89, s34, v89
	v_fma_f32 v136, v34, v86, v136
	v_fma_f32 v137, v35, v87, v137
	v_fma_f32 v150, v36, v88, v150
	v_fma_f32 v151, v37, v89, v151
	v_mfma_f32_16x16x32_bf16 v[58:61], v[90:93], v[224:227], v[58:61]
	v_cvt_f32_ubyte0_e32 v82, v75
	v_cvt_f32_ubyte1_e32 v83, v75
	v_cvt_f32_ubyte2_e32 v84, v75
	v_cvt_f32_ubyte3_e32 v85, v75
	v_mul_f32_e32 v82, s34, v82
	v_mul_f32_e32 v83, s34, v83
	v_mul_f32_e32 v84, s34, v84
	v_mul_f32_e32 v85, s34, v85
	v_fma_f32 v130, v22, v82, v130
	v_fma_f32 v131, v23, v83, v131
	v_fma_f32 v134, v24, v84, v134
	v_fma_f32 v135, v25, v85, v135
	v_mfma_f32_16x16x32_bf16 v[54:57], v[212:215], v[224:227], v[54:57]
	v_cvt_f32_ubyte0_e32 v86, v76
	v_cvt_f32_ubyte1_e32 v87, v76
	v_cvt_f32_ubyte2_e32 v88, v76
	v_cvt_f32_ubyte3_e32 v89, v76
	v_mul_f32_e32 v86, s34, v86
	v_mul_f32_e32 v87, s34, v87
	v_mul_f32_e32 v88, s34, v88
	v_mul_f32_e32 v89, s34, v89
	v_fma_f32 v124, v18, v86, v124
	v_fma_f32 v125, v19, v87, v125
	v_fma_f32 v126, v20, v88, v126
	v_fma_f32 v127, v21, v89, v127
	v_mfma_f32_16x16x32_bf16 v[50:53], v[216:219], v[224:227], v[50:53]
	v_cvt_f32_ubyte0_e32 v82, v77
	v_cvt_f32_ubyte1_e32 v83, v77
	v_cvt_f32_ubyte2_e32 v84, v77
	v_cvt_f32_ubyte3_e32 v85, v77
	v_mul_f32_e32 v82, s34, v82
	v_mul_f32_e32 v83, s34, v83
	v_mul_f32_e32 v84, s34, v84
	v_mul_f32_e32 v85, s34, v85
	v_fma_f32 v120, v62, v82, v120
	v_fma_f32 v121, v63, v83, v121
	v_fma_f32 v122, v64, v84, v122
	v_fma_f32 v123, v65, v85, v123
	v_mfma_f32_16x16x32_bf16 v[2:5], v[220:223], v[224:227], v[2:5]
	v_cvt_f32_ubyte0_e32 v86, v78
	v_cvt_f32_ubyte1_e32 v87, v78
	v_cvt_f32_ubyte2_e32 v88, v78
	v_cvt_f32_ubyte3_e32 v89, v78
	v_mul_f32_e32 v86, s34, v86
	v_mul_f32_e32 v87, s34, v87
	v_mul_f32_e32 v88, s34, v88
	v_mul_f32_e32 v89, s34, v89
	v_fma_f32 v114, v58, v86, v114
	v_fma_f32 v115, v59, v87, v115
	v_fma_f32 v116, v60, v88, v116
	v_fma_f32 v117, v61, v89, v117
	s_nop 7
	s_nop 3
	v_cvt_f32_ubyte0_e32 v86, v79
	v_cvt_f32_ubyte1_e32 v87, v79
	v_cvt_f32_ubyte2_e32 v88, v79
	v_cvt_f32_ubyte3_e32 v89, v79
	v_mul_f32_e32 v86, s34, v86
	v_mul_f32_e32 v87, s34, v87
	v_mul_f32_e32 v88, s34, v88
	v_mul_f32_e32 v89, s34, v89
	v_fma_f32 v106, v54, v86, v106
	v_fma_f32 v107, v55, v87, v107
	v_fma_f32 v108, v56, v88, v108
	v_fma_f32 v109, v57, v89, v109
	v_cvt_f32_ubyte0_e32 v82, v80
	v_cvt_f32_ubyte1_e32 v83, v80
	v_cvt_f32_ubyte2_e32 v84, v80
	v_cvt_f32_ubyte3_e32 v85, v80
	v_mul_f32_e32 v82, s34, v82
	v_mul_f32_e32 v83, s34, v83
	v_mul_f32_e32 v84, s34, v84
	v_mul_f32_e32 v85, s34, v85
	v_fma_f32 v100, v50, v82, v100
	v_fma_f32 v101, v51, v83, v101
	v_fma_f32 v102, v52, v84, v102
	v_fma_f32 v103, v53, v85, v103
	v_cvt_f32_ubyte0_e32 v86, v81
	v_cvt_f32_ubyte1_e32 v87, v81
	v_cvt_f32_ubyte2_e32 v88, v81
	v_cvt_f32_ubyte3_e32 v89, v81
	v_mul_f32_e32 v86, s34, v86
	v_mul_f32_e32 v87, s34, v87
	v_mul_f32_e32 v88, s34, v88
	v_mul_f32_e32 v89, s34, v89
	v_fma_f32 v96, v2, v86, v96
	v_fma_f32 v97, v3, v87, v97
	v_fma_f32 v98, v4, v88, v98
	v_fma_f32 v99, v5, v89, v99
	s_nop 0
	global_load_dwordx4 v[66:69], v190, s[80:81] offset:128
	global_load_dwordx4 v[70:73], v191, s[80:81] offset:128
	global_load_dwordx4 v[74:77], v190, s[86:87] offset:128
	global_load_dwordx4 v[78:81], v191, s[86:87] offset:128
	global_load_dwordx4 v[82:85], v188, s[96:97] offset:128
	global_load_dwordx4 v[86:89], v188, s[98:99] offset:128
	s_waitcnt vmcnt(11)
	ds_write_b128 v206, v[228:231] offset:0
	s_waitcnt vmcnt(10)
	ds_write_b128 v206, v[232:235] offset:10240
	s_waitcnt vmcnt(9)
	ds_write_b128 v206, v[236:239] offset:20480
	s_waitcnt vmcnt(8)
	ds_write_b128 v206, v[240:243] offset:30720
	s_waitcnt vmcnt(7)
	ds_write_b128 v0, v[244:247] offset:0
	s_waitcnt vmcnt(6)
	ds_write_b128 v0, v[248:251] offset:10240
	s_waitcnt lgkmcnt(0)
	s_barrier
	global_load_dwordx4 v[228:231], v190, s[80:81] offset:256
	global_load_dwordx4 v[232:235], v191, s[80:81] offset:256
	global_load_dwordx4 v[236:239], v190, s[86:87] offset:256
	global_load_dwordx4 v[240:243], v191, s[86:87] offset:256
	global_load_dwordx4 v[244:247], v188, s[96:97] offset:256
	global_load_dwordx4 v[248:251], v188, s[98:99] offset:256
	ds_read_b128 v[90:93], v119 offset:0
	ds_read_b128 v[208:211], v205 offset:0
	ds_read_b128 v[212:215], v119 offset:2560
	ds_read_b128 v[216:219], v119 offset:5120
	ds_read_b128 v[220:223], v119 offset:7680
	s_waitcnt lgkmcnt(3)
	v_mfma_f32_16x16x32_bf16 v[6:9], v[90:93], v[208:211], 0
	s_waitcnt lgkmcnt(2)
	v_mfma_f32_16x16x32_bf16 v[30:33], v[212:215], v[208:211], 0
	s_waitcnt vmcnt(11)
	ds_write_b128 v207, v[66:69] offset:0
	s_waitcnt lgkmcnt(2)
	v_mfma_f32_16x16x32_bf16 v[38:41], v[216:219], v[208:211], 0
	s_waitcnt lgkmcnt(1)
	v_mfma_f32_16x16x32_bf16 v[42:45], v[220:223], v[208:211], 0
	ds_read_b128 v[208:211], v205 offset:2560
	s_waitcnt lgkmcnt(0)
	v_mfma_f32_16x16x32_bf16 v[46:49], v[90:93], v[208:211], 0
	v_mfma_f32_16x16x32_bf16 v[26:29], v[212:215], v[208:211], 0
	s_waitcnt vmcnt(10)
	ds_write_b128 v207, v[70:73] offset:10240
	v_mfma_f32_16x16x32_bf16 v[14:17], v[216:219], v[208:211], 0
	v_mfma_f32_16x16x32_bf16 v[10:13], v[220:223], v[208:211], 0
	ds_read_b128 v[208:211], v205 offset:5120
	s_waitcnt lgkmcnt(0)
	v_mfma_f32_16x16x32_bf16 v[34:37], v[90:93], v[208:211], 0
	v_mfma_f32_16x16x32_bf16 v[22:25], v[212:215], v[208:211], 0
	s_waitcnt vmcnt(9)
	ds_write_b128 v207, v[74:77] offset:20480
	v_mfma_f32_16x16x32_bf16 v[18:21], v[216:219], v[208:211], 0
	v_mfma_f32_16x16x32_bf16 v[62:65], v[220:223], v[208:211], 0
	ds_read_b128 v[208:211], v205 offset:7680
	s_waitcnt lgkmcnt(0)
	v_mfma_f32_16x16x32_bf16 v[58:61], v[90:93], v[208:211], 0
	ds_read_b128 v[90:93], v119 offset:64
	v_mfma_f32_16x16x32_bf16 v[54:57], v[212:215], v[208:211], 0
	s_waitcnt vmcnt(8)
	ds_write_b128 v207, v[78:81] offset:30720
	ds_read_b128 v[212:215], v119 offset:2624
	v_mfma_f32_16x16x32_bf16 v[50:53], v[216:219], v[208:211], 0
	ds_read_b128 v[216:219], v119 offset:5184
	v_mfma_f32_16x16x32_bf16 v[2:5], v[220:223], v[208:211], 0
	ds_read_b128 v[220:223], v119 offset:7744
	ds_read_b128 v[208:211], v205 offset:64
	ds_read_b128 v[224:227], v205 offset:7744
	s_waitcnt lgkmcnt(1)
	v_mfma_f32_16x16x32_bf16 v[6:9], v[90:93], v[208:211], v[6:9]
	v_mfma_f32_16x16x32_bf16 v[30:33], v[212:215], v[208:211], v[30:33]
	s_waitcnt vmcnt(7)
	ds_write_b128 v0, v[82:85] offset:20480
	v_mfma_f32_16x16x32_bf16 v[38:41], v[216:219], v[208:211], v[38:41]
	v_mfma_f32_16x16x32_bf16 v[42:45], v[220:223], v[208:211], v[42:45]
	ds_read_b128 v[208:211], v205 offset:2624
	s_waitcnt lgkmcnt(0)
	v_mfma_f32_16x16x32_bf16 v[46:49], v[90:93], v[208:211], v[46:49]
	v_mfma_f32_16x16x32_bf16 v[26:29], v[212:215], v[208:211], v[26:29]
	s_waitcnt vmcnt(6)
	ds_write_b128 v0, v[86:89] offset:30720
	v_mfma_f32_16x16x32_bf16 v[14:17], v[216:219], v[208:211], v[14:17]
	v_mfma_f32_16x16x32_bf16 v[10:13], v[220:223], v[208:211], v[10:13]
	ds_read_b128 v[208:211], v205 offset:5184
	s_waitcnt lgkmcnt(0)
	v_mfma_f32_16x16x32_bf16 v[34:37], v[90:93], v[208:211], v[34:37]
	v_mfma_f32_16x16x32_bf16 v[22:25], v[212:215], v[208:211], v[22:25]
	v_mfma_f32_16x16x32_bf16 v[18:21], v[216:219], v[208:211], v[18:21]
	v_mfma_f32_16x16x32_bf16 v[62:65], v[220:223], v[208:211], v[62:65]
	v_mfma_f32_16x16x32_bf16 v[58:61], v[90:93], v[224:227], v[58:61]
	s_waitcnt lgkmcnt(0)
	v_mfma_f32_16x16x32_bf16 v[54:57], v[212:215], v[224:227], v[54:57]
	s_barrier
	v_mfma_f32_16x16x32_bf16 v[50:53], v[216:219], v[224:227], v[50:53]
	v_mfma_f32_16x16x32_bf16 v[2:5], v[220:223], v[224:227], v[2:5]
	global_load_dwordx4 v[66:69], v190, s[80:81] offset:384
	global_load_dwordx4 v[70:73], v191, s[80:81] offset:384
	global_load_dwordx4 v[74:77], v190, s[86:87] offset:384
	global_load_dwordx4 v[78:81], v191, s[86:87] offset:384
	global_load_dwordx4 v[82:85], v188, s[96:97] offset:384
	global_load_dwordx4 v[86:89], v188, s[98:99] offset:384
	ds_read_b128 v[90:93], v119 offset:20480
	ds_read_b128 v[208:211], v205 offset:40960
	ds_read_b128 v[212:215], v119 offset:23040
	ds_read_b128 v[216:219], v119 offset:25600
	ds_read_b128 v[220:223], v119 offset:28160
	s_waitcnt lgkmcnt(3)
	v_mfma_f32_16x16x32_bf16 v[6:9], v[90:93], v[208:211], v[6:9]
	s_waitcnt lgkmcnt(2)
	v_mfma_f32_16x16x32_bf16 v[30:33], v[212:215], v[208:211], v[30:33]
	s_waitcnt vmcnt(11)
	ds_write_b128 v206, v[228:231] offset:0
	s_waitcnt lgkmcnt(2)
	v_mfma_f32_16x16x32_bf16 v[38:41], v[216:219], v[208:211], v[38:41]
	s_waitcnt lgkmcnt(1)
	v_mfma_f32_16x16x32_bf16 v[42:45], v[220:223], v[208:211], v[42:45]
	ds_read_b128 v[208:211], v205 offset:43520
	s_waitcnt lgkmcnt(0)
	v_mfma_f32_16x16x32_bf16 v[46:49], v[90:93], v[208:211], v[46:49]
	v_mfma_f32_16x16x32_bf16 v[26:29], v[212:215], v[208:211], v[26:29]
	s_waitcnt vmcnt(10)
	ds_write_b128 v206, v[232:235] offset:10240
	v_mfma_f32_16x16x32_bf16 v[14:17], v[216:219], v[208:211], v[14:17]
	v_mfma_f32_16x16x32_bf16 v[10:13], v[220:223], v[208:211], v[10:13]
	ds_read_b128 v[208:211], v205 offset:46080
	s_waitcnt lgkmcnt(0)
	v_mfma_f32_16x16x32_bf16 v[34:37], v[90:93], v[208:211], v[34:37]
	v_mfma_f32_16x16x32_bf16 v[22:25], v[212:215], v[208:211], v[22:25]
	s_waitcnt vmcnt(9)
	ds_write_b128 v206, v[236:239] offset:20480
	v_mfma_f32_16x16x32_bf16 v[18:21], v[216:219], v[208:211], v[18:21]
	v_mfma_f32_16x16x32_bf16 v[62:65], v[220:223], v[208:211], v[62:65]
	ds_read_b128 v[208:211], v205 offset:48640
	s_waitcnt lgkmcnt(0)
	v_mfma_f32_16x16x32_bf16 v[58:61], v[90:93], v[208:211], v[58:61]
	ds_read_b128 v[90:93], v119 offset:20544
	v_mfma_f32_16x16x32_bf16 v[54:57], v[212:215], v[208:211], v[54:57]
	s_waitcnt vmcnt(8)
	ds_write_b128 v206, v[240:243] offset:30720
	ds_read_b128 v[212:215], v119 offset:23104
	v_mfma_f32_16x16x32_bf16 v[50:53], v[216:219], v[208:211], v[50:53]
	ds_read_b128 v[216:219], v119 offset:25664
	v_mfma_f32_16x16x32_bf16 v[2:5], v[220:223], v[208:211], v[2:5]
	ds_read_b128 v[220:223], v119 offset:28224
	ds_read_b128 v[208:211], v205 offset:41024
	ds_read_b128 v[224:227], v205 offset:48704
	s_waitcnt lgkmcnt(1)
	v_mfma_f32_16x16x32_bf16 v[6:9], v[90:93], v[208:211], v[6:9]
	v_mfma_f32_16x16x32_bf16 v[30:33], v[212:215], v[208:211], v[30:33]
	s_waitcnt vmcnt(7)
	ds_write_b128 v0, v[244:247] offset:0
	v_mfma_f32_16x16x32_bf16 v[38:41], v[216:219], v[208:211], v[38:41]
	v_mfma_f32_16x16x32_bf16 v[42:45], v[220:223], v[208:211], v[42:45]
	ds_read_b128 v[208:211], v205 offset:43584
	s_waitcnt lgkmcnt(0)
	v_mfma_f32_16x16x32_bf16 v[46:49], v[90:93], v[208:211], v[46:49]
	v_mfma_f32_16x16x32_bf16 v[26:29], v[212:215], v[208:211], v[26:29]
	s_waitcnt vmcnt(6)
	ds_write_b128 v0, v[248:251] offset:10240
	v_mfma_f32_16x16x32_bf16 v[14:17], v[216:219], v[208:211], v[14:17]
	v_mfma_f32_16x16x32_bf16 v[10:13], v[220:223], v[208:211], v[10:13]
	ds_read_b128 v[208:211], v205 offset:46144
	s_waitcnt lgkmcnt(0)
	v_mfma_f32_16x16x32_bf16 v[34:37], v[90:93], v[208:211], v[34:37]
	v_mfma_f32_16x16x32_bf16 v[22:25], v[212:215], v[208:211], v[22:25]
	v_mfma_f32_16x16x32_bf16 v[18:21], v[216:219], v[208:211], v[18:21]
	v_mfma_f32_16x16x32_bf16 v[62:65], v[220:223], v[208:211], v[62:65]
	v_mfma_f32_16x16x32_bf16 v[58:61], v[90:93], v[224:227], v[58:61]
	s_waitcnt lgkmcnt(0)
	v_mfma_f32_16x16x32_bf16 v[54:57], v[212:215], v[224:227], v[54:57]
	s_barrier
	v_mfma_f32_16x16x32_bf16 v[50:53], v[216:219], v[224:227], v[50:53]
	v_mfma_f32_16x16x32_bf16 v[2:5], v[220:223], v[224:227], v[2:5]
	global_load_dwordx4 v[228:231], v190, s[80:81] offset:512
	global_load_dwordx4 v[232:235], v191, s[80:81] offset:512
	global_load_dwordx4 v[236:239], v190, s[86:87] offset:512
	global_load_dwordx4 v[240:243], v191, s[86:87] offset:512
	global_load_dwordx4 v[244:247], v188, s[96:97] offset:512
	global_load_dwordx4 v[248:251], v188, s[98:99] offset:512
	ds_read_b128 v[90:93], v119 offset:0
	ds_read_b128 v[208:211], v205 offset:0
	ds_read_b128 v[212:215], v119 offset:2560
	ds_read_b128 v[216:219], v119 offset:5120
	ds_read_b128 v[220:223], v119 offset:7680
	s_waitcnt lgkmcnt(3)
	v_mfma_f32_16x16x32_bf16 v[6:9], v[90:93], v[208:211], v[6:9]
	s_waitcnt lgkmcnt(2)
	v_mfma_f32_16x16x32_bf16 v[30:33], v[212:215], v[208:211], v[30:33]
	s_waitcnt vmcnt(11)
	ds_write_b128 v207, v[66:69] offset:0
	s_waitcnt lgkmcnt(2)
	v_mfma_f32_16x16x32_bf16 v[38:41], v[216:219], v[208:211], v[38:41]
	s_waitcnt lgkmcnt(1)
	v_mfma_f32_16x16x32_bf16 v[42:45], v[220:223], v[208:211], v[42:45]
	ds_read_b128 v[208:211], v205 offset:2560
	s_waitcnt lgkmcnt(0)
	v_mfma_f32_16x16x32_bf16 v[46:49], v[90:93], v[208:211], v[46:49]
	v_mfma_f32_16x16x32_bf16 v[26:29], v[212:215], v[208:211], v[26:29]
	s_waitcnt vmcnt(10)
	ds_write_b128 v207, v[70:73] offset:10240
	v_mfma_f32_16x16x32_bf16 v[14:17], v[216:219], v[208:211], v[14:17]
	v_mfma_f32_16x16x32_bf16 v[10:13], v[220:223], v[208:211], v[10:13]
	ds_read_b128 v[208:211], v205 offset:5120
	s_waitcnt lgkmcnt(0)
	v_mfma_f32_16x16x32_bf16 v[34:37], v[90:93], v[208:211], v[34:37]
	v_mfma_f32_16x16x32_bf16 v[22:25], v[212:215], v[208:211], v[22:25]
	s_waitcnt vmcnt(9)
	ds_write_b128 v207, v[74:77] offset:20480
	v_mfma_f32_16x16x32_bf16 v[18:21], v[216:219], v[208:211], v[18:21]
	v_mfma_f32_16x16x32_bf16 v[62:65], v[220:223], v[208:211], v[62:65]
	ds_read_b128 v[208:211], v205 offset:7680
	s_waitcnt lgkmcnt(0)
	v_mfma_f32_16x16x32_bf16 v[58:61], v[90:93], v[208:211], v[58:61]
	ds_read_b128 v[90:93], v119 offset:64
	v_mfma_f32_16x16x32_bf16 v[54:57], v[212:215], v[208:211], v[54:57]
	s_waitcnt vmcnt(8)
	ds_write_b128 v207, v[78:81] offset:30720
	ds_read_b128 v[212:215], v119 offset:2624
	v_mfma_f32_16x16x32_bf16 v[50:53], v[216:219], v[208:211], v[50:53]
	ds_read_b128 v[216:219], v119 offset:5184
	v_mfma_f32_16x16x32_bf16 v[2:5], v[220:223], v[208:211], v[2:5]
	ds_read_b128 v[220:223], v119 offset:7744
	ds_read_b128 v[208:211], v205 offset:64
	ds_read_b128 v[224:227], v205 offset:7744
	s_waitcnt lgkmcnt(1)
	v_mfma_f32_16x16x32_bf16 v[6:9], v[90:93], v[208:211], v[6:9]
	v_mfma_f32_16x16x32_bf16 v[30:33], v[212:215], v[208:211], v[30:33]
	s_waitcnt vmcnt(7)
	ds_write_b128 v0, v[82:85] offset:20480
	v_mfma_f32_16x16x32_bf16 v[38:41], v[216:219], v[208:211], v[38:41]
	v_mfma_f32_16x16x32_bf16 v[42:45], v[220:223], v[208:211], v[42:45]
	ds_read_b128 v[208:211], v205 offset:2624
	s_waitcnt lgkmcnt(0)
	v_mfma_f32_16x16x32_bf16 v[46:49], v[90:93], v[208:211], v[46:49]
	v_mfma_f32_16x16x32_bf16 v[26:29], v[212:215], v[208:211], v[26:29]
	s_waitcnt vmcnt(6)
	ds_write_b128 v0, v[86:89] offset:30720
	v_mfma_f32_16x16x32_bf16 v[14:17], v[216:219], v[208:211], v[14:17]
	v_mfma_f32_16x16x32_bf16 v[10:13], v[220:223], v[208:211], v[10:13]
	ds_read_b128 v[208:211], v205 offset:5184
	s_waitcnt lgkmcnt(0)
	v_mfma_f32_16x16x32_bf16 v[34:37], v[90:93], v[208:211], v[34:37]
	v_mfma_f32_16x16x32_bf16 v[22:25], v[212:215], v[208:211], v[22:25]
	v_mfma_f32_16x16x32_bf16 v[18:21], v[216:219], v[208:211], v[18:21]
	v_mfma_f32_16x16x32_bf16 v[62:65], v[220:223], v[208:211], v[62:65]
	v_mfma_f32_16x16x32_bf16 v[58:61], v[90:93], v[224:227], v[58:61]
	s_waitcnt lgkmcnt(0)
	v_mfma_f32_16x16x32_bf16 v[54:57], v[212:215], v[224:227], v[54:57]
	s_barrier
	v_mfma_f32_16x16x32_bf16 v[50:53], v[216:219], v[224:227], v[50:53]
	v_mfma_f32_16x16x32_bf16 v[2:5], v[220:223], v[224:227], v[2:5]
	global_load_dwordx4 v[66:69], v190, s[80:81] offset:640
	global_load_dwordx4 v[70:73], v191, s[80:81] offset:640
	global_load_dwordx4 v[74:77], v190, s[86:87] offset:640
	global_load_dwordx4 v[78:81], v191, s[86:87] offset:640
	global_load_dwordx4 v[82:85], v188, s[96:97] offset:640
	global_load_dwordx4 v[86:89], v188, s[98:99] offset:640
	ds_read_b128 v[90:93], v119 offset:20480
	ds_read_b128 v[208:211], v205 offset:40960
	ds_read_b128 v[212:215], v119 offset:23040
	ds_read_b128 v[216:219], v119 offset:25600
	ds_read_b128 v[220:223], v119 offset:28160
	s_waitcnt lgkmcnt(3)
	v_mfma_f32_16x16x32_bf16 v[6:9], v[90:93], v[208:211], v[6:9]
	s_waitcnt lgkmcnt(2)
	v_mfma_f32_16x16x32_bf16 v[30:33], v[212:215], v[208:211], v[30:33]
	s_waitcnt vmcnt(11)
	ds_write_b128 v206, v[228:231] offset:0
	s_waitcnt lgkmcnt(2)
	v_mfma_f32_16x16x32_bf16 v[38:41], v[216:219], v[208:211], v[38:41]
	s_waitcnt lgkmcnt(1)
	v_mfma_f32_16x16x32_bf16 v[42:45], v[220:223], v[208:211], v[42:45]
	ds_read_b128 v[208:211], v205 offset:43520
	s_waitcnt lgkmcnt(0)
	v_mfma_f32_16x16x32_bf16 v[46:49], v[90:93], v[208:211], v[46:49]
	v_mfma_f32_16x16x32_bf16 v[26:29], v[212:215], v[208:211], v[26:29]
	s_waitcnt vmcnt(10)
	ds_write_b128 v206, v[232:235] offset:10240
	v_mfma_f32_16x16x32_bf16 v[14:17], v[216:219], v[208:211], v[14:17]
	v_mfma_f32_16x16x32_bf16 v[10:13], v[220:223], v[208:211], v[10:13]
	ds_read_b128 v[208:211], v205 offset:46080
	s_waitcnt lgkmcnt(0)
	v_mfma_f32_16x16x32_bf16 v[34:37], v[90:93], v[208:211], v[34:37]
	v_mfma_f32_16x16x32_bf16 v[22:25], v[212:215], v[208:211], v[22:25]
	s_waitcnt vmcnt(9)
	ds_write_b128 v206, v[236:239] offset:20480
	v_mfma_f32_16x16x32_bf16 v[18:21], v[216:219], v[208:211], v[18:21]
	v_mfma_f32_16x16x32_bf16 v[62:65], v[220:223], v[208:211], v[62:65]
	ds_read_b128 v[208:211], v205 offset:48640
	s_waitcnt lgkmcnt(0)
	v_mfma_f32_16x16x32_bf16 v[58:61], v[90:93], v[208:211], v[58:61]
	ds_read_b128 v[90:93], v119 offset:20544
	v_mfma_f32_16x16x32_bf16 v[54:57], v[212:215], v[208:211], v[54:57]
	s_waitcnt vmcnt(8)
	ds_write_b128 v206, v[240:243] offset:30720
	ds_read_b128 v[212:215], v119 offset:23104
	v_mfma_f32_16x16x32_bf16 v[50:53], v[216:219], v[208:211], v[50:53]
	ds_read_b128 v[216:219], v119 offset:25664
	v_mfma_f32_16x16x32_bf16 v[2:5], v[220:223], v[208:211], v[2:5]
	ds_read_b128 v[220:223], v119 offset:28224
	ds_read_b128 v[208:211], v205 offset:41024
	ds_read_b128 v[224:227], v205 offset:48704
	s_waitcnt lgkmcnt(1)
	v_mfma_f32_16x16x32_bf16 v[6:9], v[90:93], v[208:211], v[6:9]
	v_mfma_f32_16x16x32_bf16 v[30:33], v[212:215], v[208:211], v[30:33]
	s_waitcnt vmcnt(7)
	ds_write_b128 v0, v[244:247] offset:0
	v_mfma_f32_16x16x32_bf16 v[38:41], v[216:219], v[208:211], v[38:41]
	v_mfma_f32_16x16x32_bf16 v[42:45], v[220:223], v[208:211], v[42:45]
	ds_read_b128 v[208:211], v205 offset:43584
	s_waitcnt lgkmcnt(0)
	v_mfma_f32_16x16x32_bf16 v[46:49], v[90:93], v[208:211], v[46:49]
	v_mfma_f32_16x16x32_bf16 v[26:29], v[212:215], v[208:211], v[26:29]
	s_waitcnt vmcnt(6)
	ds_write_b128 v0, v[248:251] offset:10240
	v_mfma_f32_16x16x32_bf16 v[14:17], v[216:219], v[208:211], v[14:17]
	v_mfma_f32_16x16x32_bf16 v[10:13], v[220:223], v[208:211], v[10:13]
	ds_read_b128 v[208:211], v205 offset:46144
	s_waitcnt lgkmcnt(0)
	v_mfma_f32_16x16x32_bf16 v[34:37], v[90:93], v[208:211], v[34:37]
	v_mfma_f32_16x16x32_bf16 v[22:25], v[212:215], v[208:211], v[22:25]
	v_mfma_f32_16x16x32_bf16 v[18:21], v[216:219], v[208:211], v[18:21]
	v_mfma_f32_16x16x32_bf16 v[62:65], v[220:223], v[208:211], v[62:65]
	v_mfma_f32_16x16x32_bf16 v[58:61], v[90:93], v[224:227], v[58:61]
	s_waitcnt lgkmcnt(0)
	v_mfma_f32_16x16x32_bf16 v[54:57], v[212:215], v[224:227], v[54:57]
	s_barrier
	v_mfma_f32_16x16x32_bf16 v[50:53], v[216:219], v[224:227], v[50:53]
	v_mfma_f32_16x16x32_bf16 v[2:5], v[220:223], v[224:227], v[2:5]
	global_load_dwordx4 v[228:231], v190, s[80:81] offset:768
	global_load_dwordx4 v[232:235], v191, s[80:81] offset:768
	global_load_dwordx4 v[236:239], v190, s[86:87] offset:768
	global_load_dwordx4 v[240:243], v191, s[86:87] offset:768
	global_load_dwordx4 v[244:247], v188, s[96:97] offset:768
	global_load_dwordx4 v[248:251], v188, s[98:99] offset:768
	ds_read_b128 v[90:93], v119 offset:0
	ds_read_b128 v[208:211], v205 offset:0
	ds_read_b128 v[212:215], v119 offset:2560
	ds_read_b128 v[216:219], v119 offset:5120
	ds_read_b128 v[220:223], v119 offset:7680
	s_waitcnt lgkmcnt(3)
	v_mfma_f32_16x16x32_bf16 v[6:9], v[90:93], v[208:211], v[6:9]
	s_waitcnt lgkmcnt(2)
	v_mfma_f32_16x16x32_bf16 v[30:33], v[212:215], v[208:211], v[30:33]
	s_waitcnt vmcnt(11)
	ds_write_b128 v207, v[66:69] offset:0
	s_waitcnt lgkmcnt(2)
	v_mfma_f32_16x16x32_bf16 v[38:41], v[216:219], v[208:211], v[38:41]
	s_waitcnt lgkmcnt(1)
	v_mfma_f32_16x16x32_bf16 v[42:45], v[220:223], v[208:211], v[42:45]
	ds_read_b128 v[208:211], v205 offset:2560
	s_waitcnt lgkmcnt(0)
	v_mfma_f32_16x16x32_bf16 v[46:49], v[90:93], v[208:211], v[46:49]
	v_mfma_f32_16x16x32_bf16 v[26:29], v[212:215], v[208:211], v[26:29]
	s_waitcnt vmcnt(10)
	ds_write_b128 v207, v[70:73] offset:10240
	v_mfma_f32_16x16x32_bf16 v[14:17], v[216:219], v[208:211], v[14:17]
	v_mfma_f32_16x16x32_bf16 v[10:13], v[220:223], v[208:211], v[10:13]
	ds_read_b128 v[208:211], v205 offset:5120
	s_waitcnt lgkmcnt(0)
	v_mfma_f32_16x16x32_bf16 v[34:37], v[90:93], v[208:211], v[34:37]
	v_mfma_f32_16x16x32_bf16 v[22:25], v[212:215], v[208:211], v[22:25]
	s_waitcnt vmcnt(9)
	ds_write_b128 v207, v[74:77] offset:20480
	v_mfma_f32_16x16x32_bf16 v[18:21], v[216:219], v[208:211], v[18:21]
	v_mfma_f32_16x16x32_bf16 v[62:65], v[220:223], v[208:211], v[62:65]
	ds_read_b128 v[208:211], v205 offset:7680
	s_waitcnt lgkmcnt(0)
	v_mfma_f32_16x16x32_bf16 v[58:61], v[90:93], v[208:211], v[58:61]
	ds_read_b128 v[90:93], v119 offset:64
	v_mfma_f32_16x16x32_bf16 v[54:57], v[212:215], v[208:211], v[54:57]
	s_waitcnt vmcnt(8)
	ds_write_b128 v207, v[78:81] offset:30720
	ds_read_b128 v[212:215], v119 offset:2624
	v_mfma_f32_16x16x32_bf16 v[50:53], v[216:219], v[208:211], v[50:53]
	ds_read_b128 v[216:219], v119 offset:5184
	v_mfma_f32_16x16x32_bf16 v[2:5], v[220:223], v[208:211], v[2:5]
	ds_read_b128 v[220:223], v119 offset:7744
	ds_read_b128 v[208:211], v205 offset:64
	ds_read_b128 v[224:227], v205 offset:7744
	s_waitcnt lgkmcnt(1)
	v_mfma_f32_16x16x32_bf16 v[6:9], v[90:93], v[208:211], v[6:9]
	v_mfma_f32_16x16x32_bf16 v[30:33], v[212:215], v[208:211], v[30:33]
	s_waitcnt vmcnt(7)
	ds_write_b128 v0, v[82:85] offset:20480
	v_mfma_f32_16x16x32_bf16 v[38:41], v[216:219], v[208:211], v[38:41]
	v_mfma_f32_16x16x32_bf16 v[42:45], v[220:223], v[208:211], v[42:45]
	ds_read_b128 v[208:211], v205 offset:2624
	s_waitcnt lgkmcnt(0)
	v_mfma_f32_16x16x32_bf16 v[46:49], v[90:93], v[208:211], v[46:49]
	v_mfma_f32_16x16x32_bf16 v[26:29], v[212:215], v[208:211], v[26:29]
	s_waitcnt vmcnt(6)
	ds_write_b128 v0, v[86:89] offset:30720
	v_mfma_f32_16x16x32_bf16 v[14:17], v[216:219], v[208:211], v[14:17]
	v_mfma_f32_16x16x32_bf16 v[10:13], v[220:223], v[208:211], v[10:13]
	ds_read_b128 v[208:211], v205 offset:5184
	s_waitcnt lgkmcnt(0)
	v_mfma_f32_16x16x32_bf16 v[34:37], v[90:93], v[208:211], v[34:37]
	v_mfma_f32_16x16x32_bf16 v[22:25], v[212:215], v[208:211], v[22:25]
	v_mfma_f32_16x16x32_bf16 v[18:21], v[216:219], v[208:211], v[18:21]
	v_mfma_f32_16x16x32_bf16 v[62:65], v[220:223], v[208:211], v[62:65]
	v_mfma_f32_16x16x32_bf16 v[58:61], v[90:93], v[224:227], v[58:61]
	s_waitcnt lgkmcnt(0)
	v_mfma_f32_16x16x32_bf16 v[54:57], v[212:215], v[224:227], v[54:57]
	s_barrier
	v_mfma_f32_16x16x32_bf16 v[50:53], v[216:219], v[224:227], v[50:53]
	v_mfma_f32_16x16x32_bf16 v[2:5], v[220:223], v[224:227], v[2:5]
	global_load_dwordx4 v[66:69], v190, s[80:81] offset:896
	global_load_dwordx4 v[70:73], v191, s[80:81] offset:896
	global_load_dwordx4 v[74:77], v190, s[86:87] offset:896
	global_load_dwordx4 v[78:81], v191, s[86:87] offset:896
	global_load_dwordx4 v[82:85], v188, s[96:97] offset:896
	global_load_dwordx4 v[86:89], v188, s[98:99] offset:896
	ds_read_b128 v[90:93], v119 offset:20480
	ds_read_b128 v[208:211], v205 offset:40960
	ds_read_b128 v[212:215], v119 offset:23040
	ds_read_b128 v[216:219], v119 offset:25600
	ds_read_b128 v[220:223], v119 offset:28160
	s_waitcnt lgkmcnt(3)
	v_mfma_f32_16x16x32_bf16 v[6:9], v[90:93], v[208:211], v[6:9]
	s_waitcnt lgkmcnt(2)
	v_mfma_f32_16x16x32_bf16 v[30:33], v[212:215], v[208:211], v[30:33]
	s_waitcnt vmcnt(11)
	ds_write_b128 v206, v[228:231] offset:0
	s_waitcnt lgkmcnt(2)
	v_mfma_f32_16x16x32_bf16 v[38:41], v[216:219], v[208:211], v[38:41]
	s_waitcnt lgkmcnt(1)
	v_mfma_f32_16x16x32_bf16 v[42:45], v[220:223], v[208:211], v[42:45]
	ds_read_b128 v[208:211], v205 offset:43520
	s_waitcnt lgkmcnt(0)
	v_mfma_f32_16x16x32_bf16 v[46:49], v[90:93], v[208:211], v[46:49]
	v_mfma_f32_16x16x32_bf16 v[26:29], v[212:215], v[208:211], v[26:29]
	s_waitcnt vmcnt(10)
	ds_write_b128 v206, v[232:235] offset:10240
	v_mfma_f32_16x16x32_bf16 v[14:17], v[216:219], v[208:211], v[14:17]
	v_mfma_f32_16x16x32_bf16 v[10:13], v[220:223], v[208:211], v[10:13]
	ds_read_b128 v[208:211], v205 offset:46080
	s_waitcnt lgkmcnt(0)
	v_mfma_f32_16x16x32_bf16 v[34:37], v[90:93], v[208:211], v[34:37]
	v_mfma_f32_16x16x32_bf16 v[22:25], v[212:215], v[208:211], v[22:25]
	s_waitcnt vmcnt(9)
	ds_write_b128 v206, v[236:239] offset:20480
	v_mfma_f32_16x16x32_bf16 v[18:21], v[216:219], v[208:211], v[18:21]
	v_mfma_f32_16x16x32_bf16 v[62:65], v[220:223], v[208:211], v[62:65]
	ds_read_b128 v[208:211], v205 offset:48640
	s_waitcnt lgkmcnt(0)
	v_mfma_f32_16x16x32_bf16 v[58:61], v[90:93], v[208:211], v[58:61]
	ds_read_b128 v[90:93], v119 offset:20544
	v_mfma_f32_16x16x32_bf16 v[54:57], v[212:215], v[208:211], v[54:57]
	s_waitcnt vmcnt(8)
	ds_write_b128 v206, v[240:243] offset:30720
	ds_read_b128 v[212:215], v119 offset:23104
	v_mfma_f32_16x16x32_bf16 v[50:53], v[216:219], v[208:211], v[50:53]
	ds_read_b128 v[216:219], v119 offset:25664
	v_mfma_f32_16x16x32_bf16 v[2:5], v[220:223], v[208:211], v[2:5]
	ds_read_b128 v[220:223], v119 offset:28224
	ds_read_b128 v[208:211], v205 offset:41024
	ds_read_b128 v[224:227], v205 offset:48704
	s_waitcnt lgkmcnt(1)
	v_mfma_f32_16x16x32_bf16 v[6:9], v[90:93], v[208:211], v[6:9]
	v_mfma_f32_16x16x32_bf16 v[30:33], v[212:215], v[208:211], v[30:33]
	s_waitcnt vmcnt(7)
	ds_write_b128 v0, v[244:247] offset:0
	v_mfma_f32_16x16x32_bf16 v[38:41], v[216:219], v[208:211], v[38:41]
	v_mfma_f32_16x16x32_bf16 v[42:45], v[220:223], v[208:211], v[42:45]
	ds_read_b128 v[208:211], v205 offset:43584
	s_waitcnt lgkmcnt(0)
	v_mfma_f32_16x16x32_bf16 v[46:49], v[90:93], v[208:211], v[46:49]
	v_mfma_f32_16x16x32_bf16 v[26:29], v[212:215], v[208:211], v[26:29]
	s_waitcnt vmcnt(6)
	ds_write_b128 v0, v[248:251] offset:10240
	s_movk_i32 s10, 0x400
	s_mov_b32 s11, 0
	v_lshl_add_u64 v[244:245], v[128:129], 0, s[10:11]
	v_lshl_add_u64 v[246:247], v[132:133], 0, s[10:11]
	v_lshl_add_u64 v[248:249], v[152:153], 0, s[10:11]
	v_lshl_add_u64 v[250:251], v[154:155], 0, s[10:11]
	global_load_dwordx2 v[228:229], v[244:245], off
	global_load_dwordx2 v[230:231], v[244:245], off offset:32
	global_load_dwordx2 v[232:233], v[246:247], off
	global_load_dwordx2 v[234:235], v[246:247], off offset:32
	global_load_dwordx2 v[236:237], v[248:249], off
	global_load_dwordx2 v[238:239], v[248:249], off offset:32
	global_load_dwordx2 v[240:241], v[250:251], off
	global_load_dwordx2 v[242:243], v[250:251], off offset:32
	v_mfma_f32_16x16x32_bf16 v[14:17], v[216:219], v[208:211], v[14:17]
	v_mfma_f32_16x16x32_bf16 v[10:13], v[220:223], v[208:211], v[10:13]
	ds_read_b128 v[208:211], v205 offset:46144
	s_waitcnt lgkmcnt(0)
	v_mfma_f32_16x16x32_bf16 v[34:37], v[90:93], v[208:211], v[34:37]
	v_mfma_f32_16x16x32_bf16 v[22:25], v[212:215], v[208:211], v[22:25]
	v_mfma_f32_16x16x32_bf16 v[18:21], v[216:219], v[208:211], v[18:21]
	v_mfma_f32_16x16x32_bf16 v[62:65], v[220:223], v[208:211], v[62:65]
	v_mfma_f32_16x16x32_bf16 v[58:61], v[90:93], v[224:227], v[58:61]
	s_waitcnt lgkmcnt(0)
	v_mfma_f32_16x16x32_bf16 v[54:57], v[212:215], v[224:227], v[54:57]
	s_barrier
	v_mfma_f32_16x16x32_bf16 v[50:53], v[216:219], v[224:227], v[50:53]
	v_mfma_f32_16x16x32_bf16 v[2:5], v[220:223], v[224:227], v[2:5]
	ds_read_b128 v[90:93], v119 offset:0
	ds_read_b128 v[208:211], v205 offset:0
	ds_read_b128 v[212:215], v119 offset:2560
	ds_read_b128 v[216:219], v119 offset:5120
	ds_read_b128 v[220:223], v119 offset:7680
	s_waitcnt lgkmcnt(3)
	v_mfma_f32_16x16x32_bf16 v[6:9], v[90:93], v[208:211], v[6:9]
	s_waitcnt lgkmcnt(2)
	v_mfma_f32_16x16x32_bf16 v[30:33], v[212:215], v[208:211], v[30:33]
	s_waitcnt vmcnt(13)
	ds_write_b128 v207, v[66:69] offset:0
	s_waitcnt lgkmcnt(2)
	v_mfma_f32_16x16x32_bf16 v[38:41], v[216:219], v[208:211], v[38:41]
	s_waitcnt lgkmcnt(1)
	v_mfma_f32_16x16x32_bf16 v[42:45], v[220:223], v[208:211], v[42:45]
	ds_read_b128 v[208:211], v205 offset:2560
	s_waitcnt lgkmcnt(0)
	v_mfma_f32_16x16x32_bf16 v[46:49], v[90:93], v[208:211], v[46:49]
	v_mfma_f32_16x16x32_bf16 v[26:29], v[212:215], v[208:211], v[26:29]
	s_waitcnt vmcnt(12)
	ds_write_b128 v207, v[70:73] offset:10240
	v_mfma_f32_16x16x32_bf16 v[14:17], v[216:219], v[208:211], v[14:17]
	v_mfma_f32_16x16x32_bf16 v[10:13], v[220:223], v[208:211], v[10:13]
	ds_read_b128 v[208:211], v205 offset:5120
	s_waitcnt lgkmcnt(0)
	v_mfma_f32_16x16x32_bf16 v[34:37], v[90:93], v[208:211], v[34:37]
	v_mfma_f32_16x16x32_bf16 v[22:25], v[212:215], v[208:211], v[22:25]
	s_waitcnt vmcnt(11)
	ds_write_b128 v207, v[74:77] offset:20480
	v_mfma_f32_16x16x32_bf16 v[18:21], v[216:219], v[208:211], v[18:21]
	v_mfma_f32_16x16x32_bf16 v[62:65], v[220:223], v[208:211], v[62:65]
	ds_read_b128 v[208:211], v205 offset:7680
	s_waitcnt lgkmcnt(0)
	v_mfma_f32_16x16x32_bf16 v[58:61], v[90:93], v[208:211], v[58:61]
	ds_read_b128 v[90:93], v119 offset:64
	v_mfma_f32_16x16x32_bf16 v[54:57], v[212:215], v[208:211], v[54:57]
	s_waitcnt vmcnt(10)
	ds_write_b128 v207, v[78:81] offset:30720
	ds_read_b128 v[212:215], v119 offset:2624
	v_mfma_f32_16x16x32_bf16 v[50:53], v[216:219], v[208:211], v[50:53]
	ds_read_b128 v[216:219], v119 offset:5184
	v_mfma_f32_16x16x32_bf16 v[2:5], v[220:223], v[208:211], v[2:5]
	ds_read_b128 v[220:223], v119 offset:7744
	ds_read_b128 v[208:211], v205 offset:64
	ds_read_b128 v[224:227], v205 offset:7744
	s_waitcnt lgkmcnt(1)
	v_mfma_f32_16x16x32_bf16 v[6:9], v[90:93], v[208:211], v[6:9]
	v_mfma_f32_16x16x32_bf16 v[30:33], v[212:215], v[208:211], v[30:33]
	s_waitcnt vmcnt(9)
	ds_write_b128 v0, v[82:85] offset:20480
	v_mfma_f32_16x16x32_bf16 v[38:41], v[216:219], v[208:211], v[38:41]
	v_mfma_f32_16x16x32_bf16 v[42:45], v[220:223], v[208:211], v[42:45]
	ds_read_b128 v[208:211], v205 offset:2624
	s_waitcnt lgkmcnt(0)
	v_mfma_f32_16x16x32_bf16 v[46:49], v[90:93], v[208:211], v[46:49]
	v_mfma_f32_16x16x32_bf16 v[26:29], v[212:215], v[208:211], v[26:29]
	s_waitcnt vmcnt(8)
	ds_write_b128 v0, v[86:89] offset:30720
	s_add_u32 s80, s80, 0x600
	s_addc_u32 s81, s81, 0
	s_add_u32 s86, s80, 0x1f0000
	s_addc_u32 s87, s81, 0
	s_add_u32 s96, s96, 0x100000
	s_addc_u32 s97, s97, 0
	s_add_u32 s98, s96, 0x10000
	s_addc_u32 s99, s97, 0
	global_load_dwordx4 v[66:69], v190, s[80:81] offset:0
	global_load_dwordx4 v[70:73], v191, s[80:81] offset:0
	global_load_dwordx4 v[74:77], v190, s[86:87] offset:0
	global_load_dwordx4 v[78:81], v191, s[86:87] offset:0
	global_load_dwordx4 v[82:85], v188, s[96:97] offset:0
	global_load_dwordx4 v[86:89], v188, s[98:99] offset:0
	v_mfma_f32_16x16x32_bf16 v[14:17], v[216:219], v[208:211], v[14:17]
	v_mfma_f32_16x16x32_bf16 v[10:13], v[220:223], v[208:211], v[10:13]
	ds_read_b128 v[208:211], v205 offset:5184
	s_waitcnt lgkmcnt(0)
	v_mfma_f32_16x16x32_bf16 v[34:37], v[90:93], v[208:211], v[34:37]
	v_mfma_f32_16x16x32_bf16 v[22:25], v[212:215], v[208:211], v[22:25]
	v_mfma_f32_16x16x32_bf16 v[18:21], v[216:219], v[208:211], v[18:21]
	v_mfma_f32_16x16x32_bf16 v[62:65], v[220:223], v[208:211], v[62:65]
	v_mfma_f32_16x16x32_bf16 v[58:61], v[90:93], v[224:227], v[58:61]
	s_waitcnt lgkmcnt(0)
	v_mfma_f32_16x16x32_bf16 v[54:57], v[212:215], v[224:227], v[54:57]
	s_barrier
	v_mfma_f32_16x16x32_bf16 v[50:53], v[216:219], v[224:227], v[50:53]
	v_mfma_f32_16x16x32_bf16 v[2:5], v[220:223], v[224:227], v[2:5]
	ds_read_b128 v[90:93], v119 offset:20480
	ds_read_b128 v[208:211], v205 offset:40960
	ds_read_b128 v[212:215], v119 offset:23040
	ds_read_b128 v[216:219], v119 offset:25600
	ds_read_b128 v[220:223], v119 offset:28160
	s_waitcnt lgkmcnt(3)
	v_mfma_f32_16x16x32_bf16 v[6:9], v[90:93], v[208:211], v[6:9]
	s_waitcnt lgkmcnt(2)
	v_mfma_f32_16x16x32_bf16 v[30:33], v[212:215], v[208:211], v[30:33]
	s_waitcnt lgkmcnt(1)
	v_mfma_f32_16x16x32_bf16 v[38:41], v[216:219], v[208:211], v[38:41]
	s_waitcnt lgkmcnt(0)
	v_mfma_f32_16x16x32_bf16 v[42:45], v[220:223], v[208:211], v[42:45]
	ds_read_b128 v[208:211], v205 offset:43520
	s_waitcnt lgkmcnt(0)
	v_mfma_f32_16x16x32_bf16 v[46:49], v[90:93], v[208:211], v[46:49]
	v_mfma_f32_16x16x32_bf16 v[26:29], v[212:215], v[208:211], v[26:29]
	v_mfma_f32_16x16x32_bf16 v[14:17], v[216:219], v[208:211], v[14:17]
	v_mfma_f32_16x16x32_bf16 v[10:13], v[220:223], v[208:211], v[10:13]
	ds_read_b128 v[208:211], v205 offset:46080
	s_waitcnt lgkmcnt(0)
	v_mfma_f32_16x16x32_bf16 v[34:37], v[90:93], v[208:211], v[34:37]
	v_mfma_f32_16x16x32_bf16 v[22:25], v[212:215], v[208:211], v[22:25]
	v_mfma_f32_16x16x32_bf16 v[18:21], v[216:219], v[208:211], v[18:21]
	v_mfma_f32_16x16x32_bf16 v[62:65], v[220:223], v[208:211], v[62:65]
	ds_read_b128 v[208:211], v205 offset:48640
	s_waitcnt lgkmcnt(0)
	v_mfma_f32_16x16x32_bf16 v[58:61], v[90:93], v[208:211], v[58:61]
	ds_read_b128 v[90:93], v119 offset:20544
	v_mfma_f32_16x16x32_bf16 v[54:57], v[212:215], v[208:211], v[54:57]
	ds_read_b128 v[212:215], v119 offset:23104
	v_mfma_f32_16x16x32_bf16 v[50:53], v[216:219], v[208:211], v[50:53]
	ds_read_b128 v[216:219], v119 offset:25664
	v_mfma_f32_16x16x32_bf16 v[2:5], v[220:223], v[208:211], v[2:5]
	ds_read_b128 v[220:223], v119 offset:28224
	ds_read_b128 v[208:211], v205 offset:41024
	ds_read_b128 v[224:227], v205 offset:48704
	s_waitcnt lgkmcnt(1)
	v_mfma_f32_16x16x32_bf16 v[6:9], v[90:93], v[208:211], v[6:9]
	s_waitcnt vmcnt(6)
	v_mfma_f32_16x16x32_bf16 v[30:33], v[212:215], v[208:211], v[30:33]
	v_mfma_f32_16x16x32_bf16 v[38:41], v[216:219], v[208:211], v[38:41]
	v_mfma_f32_16x16x32_bf16 v[42:45], v[220:223], v[208:211], v[42:45]
	v_cvt_f32_ubyte0_e32 v248, v228
	v_cvt_f32_ubyte1_e32 v249, v228
	v_cvt_f32_ubyte2_e32 v250, v228
	v_cvt_f32_ubyte3_e32 v251, v228
	v_mul_f32_e32 v248, s34, v248
	v_mul_f32_e32 v249, s34, v249
	v_mul_f32_e32 v250, s34, v250
	v_mul_f32_e32 v251, s34, v251
	v_fma_f32 v184, v6, v248, v184
	v_fma_f32 v185, v7, v249, v185
	v_fma_f32 v186, v8, v250, v186
	v_fma_f32 v187, v9, v251, v187
	ds_read_b128 v[208:211], v205 offset:43584
	s_waitcnt lgkmcnt(0)
	v_mfma_f32_16x16x32_bf16 v[46:49], v[90:93], v[208:211], v[46:49]
	v_cvt_f32_ubyte0_e32 v244, v229
	v_cvt_f32_ubyte1_e32 v245, v229
	v_cvt_f32_ubyte2_e32 v246, v229
	v_cvt_f32_ubyte3_e32 v247, v229
	v_mul_f32_e32 v244, s34, v244
	v_mul_f32_e32 v245, s34, v245
	v_mul_f32_e32 v246, s34, v246
	v_mul_f32_e32 v247, s34, v247
	v_fma_f32 v180, v30, v244, v180
	v_fma_f32 v181, v31, v245, v181
	v_fma_f32 v182, v32, v246, v182
	v_fma_f32 v183, v33, v247, v183
	v_mfma_f32_16x16x32_bf16 v[26:29], v[212:215], v[208:211], v[26:29]
	v_cvt_f32_ubyte0_e32 v248, v230
	v_cvt_f32_ubyte1_e32 v249, v230
	v_cvt_f32_ubyte2_e32 v250, v230
	v_cvt_f32_ubyte3_e32 v251, v230
	v_mul_f32_e32 v248, s34, v248
	v_mul_f32_e32 v249, s34, v249
	v_mul_f32_e32 v250, s34, v250
	v_mul_f32_e32 v251, s34, v251
	v_fma_f32 v176, v38, v248, v176
	v_fma_f32 v177, v39, v249, v177
	v_fma_f32 v178, v40, v250, v178
	v_fma_f32 v179, v41, v251, v179
	v_mfma_f32_16x16x32_bf16 v[14:17], v[216:219], v[208:211], v[14:17]
	v_cvt_f32_ubyte0_e32 v244, v231
	v_cvt_f32_ubyte1_e32 v245, v231
	v_cvt_f32_ubyte2_e32 v246, v231
	v_cvt_f32_ubyte3_e32 v247, v231
	v_mul_f32_e32 v244, s34, v244
	v_mul_f32_e32 v245, s34, v245
	v_mul_f32_e32 v246, s34, v246
	v_mul_f32_e32 v247, s34, v247
	v_fma_f32 v172, v42, v244, v172
	v_fma_f32 v173, v43, v245, v173
	v_fma_f32 v174, v44, v246, v174
	v_fma_f32 v175, v45, v247, v175
	v_mfma_f32_16x16x32_bf16 v[10:13], v[220:223], v[208:211], v[10:13]
	v_cvt_f32_ubyte0_e32 v248, v232
	v_cvt_f32_ubyte1_e32 v249, v232
	v_cvt_f32_ubyte2_e32 v250, v232
	v_cvt_f32_ubyte3_e32 v251, v232
	v_mul_f32_e32 v248, s34, v248
	v_mul_f32_e32 v249, s34, v249
	v_mul_f32_e32 v250, s34, v250
	v_mul_f32_e32 v251, s34, v251
	v_fma_f32 v168, v46, v248, v168
	v_fma_f32 v169, v47, v249, v169
	v_fma_f32 v170, v48, v250, v170
	v_fma_f32 v171, v49, v251, v171
	ds_read_b128 v[208:211], v205 offset:46144
	s_waitcnt lgkmcnt(0)
	v_mfma_f32_16x16x32_bf16 v[34:37], v[90:93], v[208:211], v[34:37]
	v_cvt_f32_ubyte0_e32 v244, v233
	v_cvt_f32_ubyte1_e32 v245, v233
	v_cvt_f32_ubyte2_e32 v246, v233
	v_cvt_f32_ubyte3_e32 v247, v233
	v_mul_f32_e32 v244, s34, v244
	v_mul_f32_e32 v245, s34, v245
	v_mul_f32_e32 v246, s34, v246
	v_mul_f32_e32 v247, s34, v247
	v_fma_f32 v164, v26, v244, v164
	v_fma_f32 v165, v27, v245, v165
	v_fma_f32 v166, v28, v246, v166
	v_fma_f32 v167, v29, v247, v167
	v_mfma_f32_16x16x32_bf16 v[22:25], v[212:215], v[208:211], v[22:25]
	v_cvt_f32_ubyte0_e32 v248, v234
	v_cvt_f32_ubyte1_e32 v249, v234
	v_cvt_f32_ubyte2_e32 v250, v234
	v_cvt_f32_ubyte3_e32 v251, v234
	v_mul_f32_e32 v248, s34, v248
	v_mul_f32_e32 v249, s34, v249
	v_mul_f32_e32 v250, s34, v250
	v_mul_f32_e32 v251, s34, v251
	v_fma_f32 v160, v14, v248, v160
	v_fma_f32 v161, v15, v249, v161
	v_fma_f32 v162, v16, v250, v162
	v_fma_f32 v163, v17, v251, v163
	v_mfma_f32_16x16x32_bf16 v[18:21], v[216:219], v[208:211], v[18:21]
	v_cvt_f32_ubyte0_e32 v244, v235
	v_cvt_f32_ubyte1_e32 v245, v235
	v_cvt_f32_ubyte2_e32 v246, v235
	v_cvt_f32_ubyte3_e32 v247, v235
	v_mul_f32_e32 v244, s34, v244
	v_mul_f32_e32 v245, s34, v245
	v_mul_f32_e32 v246, s34, v246
	v_mul_f32_e32 v247, s34, v247
	v_fma_f32 v156, v10, v244, v156
	v_fma_f32 v157, v11, v245, v157
	v_fma_f32 v158, v12, v246, v158
	v_fma_f32 v159, v13, v247, v159
	v_mfma_f32_16x16x32_bf16 v[62:65], v[220:223], v[208:211], v[62:65]
	v_cvt_f32_ubyte0_e32 v248, v236
	v_cvt_f32_ubyte1_e32 v249, v236
	v_cvt_f32_ubyte2_e32 v250, v236
	v_cvt_f32_ubyte3_e32 v251, v236
	v_mul_f32_e32 v248, s34, v248
	v_mul_f32_e32 v249, s34, v249
	v_mul_f32_e32 v250, s34, v250
	v_mul_f32_e32 v251, s34, v251
	v_fma_f32 v136, v34, v248, v136
	v_fma_f32 v137, v35, v249, v137
	v_fma_f32 v150, v36, v250, v150
	v_fma_f32 v151, v37, v251, v151
	v_mfma_f32_16x16x32_bf16 v[58:61], v[90:93], v[224:227], v[58:61]
	v_cvt_f32_ubyte0_e32 v244, v237
	v_cvt_f32_ubyte1_e32 v245, v237
	v_cvt_f32_ubyte2_e32 v246, v237
	v_cvt_f32_ubyte3_e32 v247, v237
	v_mul_f32_e32 v244, s34, v244
	v_mul_f32_e32 v245, s34, v245
	v_mul_f32_e32 v246, s34, v246
	v_mul_f32_e32 v247, s34, v247
	v_fma_f32 v130, v22, v244, v130
	v_fma_f32 v131, v23, v245, v131
	v_fma_f32 v134, v24, v246, v134
	v_fma_f32 v135, v25, v247, v135
	v_mfma_f32_16x16x32_bf16 v[54:57], v[212:215], v[224:227], v[54:57]
	v_cvt_f32_ubyte0_e32 v248, v238
	v_cvt_f32_ubyte1_e32 v249, v238
	v_cvt_f32_ubyte2_e32 v250, v238
	v_cvt_f32_ubyte3_e32 v251, v238
	v_mul_f32_e32 v248, s34, v248
	v_mul_f32_e32 v249, s34, v249
	v_mul_f32_e32 v250, s34, v250
	v_mul_f32_e32 v251, s34, v251
	v_fma_f32 v124, v18, v248, v124
	v_fma_f32 v125, v19, v249, v125
	v_fma_f32 v126, v20, v250, v126
	v_fma_f32 v127, v21, v251, v127
	v_mfma_f32_16x16x32_bf16 v[50:53], v[216:219], v[224:227], v[50:53]
	v_cvt_f32_ubyte0_e32 v244, v239
	v_cvt_f32_ubyte1_e32 v245, v239
	v_cvt_f32_ubyte2_e32 v246, v239
	v_cvt_f32_ubyte3_e32 v247, v239
	v_mul_f32_e32 v244, s34, v244
	v_mul_f32_e32 v245, s34, v245
	v_mul_f32_e32 v246, s34, v246
	v_mul_f32_e32 v247, s34, v247
	v_fma_f32 v120, v62, v244, v120
	v_fma_f32 v121, v63, v245, v121
	v_fma_f32 v122, v64, v246, v122
	v_fma_f32 v123, v65, v247, v123
	v_mfma_f32_16x16x32_bf16 v[2:5], v[220:223], v[224:227], v[2:5]
	v_cvt_f32_ubyte0_e32 v248, v240
	v_cvt_f32_ubyte1_e32 v249, v240
	v_cvt_f32_ubyte2_e32 v250, v240
	v_cvt_f32_ubyte3_e32 v251, v240
	v_mul_f32_e32 v248, s34, v248
	v_mul_f32_e32 v249, s34, v249
	v_mul_f32_e32 v250, s34, v250
	v_mul_f32_e32 v251, s34, v251
	v_fma_f32 v114, v58, v248, v114
	v_fma_f32 v115, v59, v249, v115
	v_fma_f32 v116, v60, v250, v116
	v_fma_f32 v117, v61, v251, v117
	s_nop 7
	s_nop 3
	v_cvt_f32_ubyte0_e32 v248, v241
	v_cvt_f32_ubyte1_e32 v249, v241
	v_cvt_f32_ubyte2_e32 v250, v241
	v_cvt_f32_ubyte3_e32 v251, v241
	v_mul_f32_e32 v248, s34, v248
	v_mul_f32_e32 v249, s34, v249
	v_mul_f32_e32 v250, s34, v250
	v_mul_f32_e32 v251, s34, v251
	v_fma_f32 v106, v54, v248, v106
	v_fma_f32 v107, v55, v249, v107
	v_fma_f32 v108, v56, v250, v108
	v_fma_f32 v109, v57, v251, v109
	v_cvt_f32_ubyte0_e32 v244, v242
	v_cvt_f32_ubyte1_e32 v245, v242
	v_cvt_f32_ubyte2_e32 v246, v242
	v_cvt_f32_ubyte3_e32 v247, v242
	v_mul_f32_e32 v244, s34, v244
	v_mul_f32_e32 v245, s34, v245
	v_mul_f32_e32 v246, s34, v246
	v_mul_f32_e32 v247, s34, v247
	v_fma_f32 v100, v50, v244, v100
	v_fma_f32 v101, v51, v245, v101
	v_fma_f32 v102, v52, v246, v102
	v_fma_f32 v103, v53, v247, v103
	v_cvt_f32_ubyte0_e32 v248, v243
	v_cvt_f32_ubyte1_e32 v249, v243
	v_cvt_f32_ubyte2_e32 v250, v243
	v_cvt_f32_ubyte3_e32 v251, v243
	v_mul_f32_e32 v248, s34, v248
	v_mul_f32_e32 v249, s34, v249
	v_mul_f32_e32 v250, s34, v250
	v_mul_f32_e32 v251, s34, v251
	v_fma_f32 v96, v2, v248, v96
	v_fma_f32 v97, v3, v249, v97
	v_fma_f32 v98, v4, v250, v98
	v_fma_f32 v99, v5, v251, v99
	s_nop 0
	global_load_dwordx4 v[228:231], v190, s[80:81] offset:128
	global_load_dwordx4 v[232:235], v191, s[80:81] offset:128
	global_load_dwordx4 v[236:239], v190, s[86:87] offset:128
	global_load_dwordx4 v[240:243], v191, s[86:87] offset:128
	global_load_dwordx4 v[244:247], v188, s[96:97] offset:128
	global_load_dwordx4 v[248:251], v188, s[98:99] offset:128
	s_waitcnt vmcnt(11)
	ds_write_b128 v206, v[66:69] offset:0
	s_waitcnt vmcnt(10)
	ds_write_b128 v206, v[70:73] offset:10240
	s_waitcnt vmcnt(9)
	ds_write_b128 v206, v[74:77] offset:20480
	s_waitcnt vmcnt(8)
	ds_write_b128 v206, v[78:81] offset:30720
	s_waitcnt vmcnt(7)
	ds_write_b128 v0, v[82:85] offset:0
	s_waitcnt vmcnt(6)
	ds_write_b128 v0, v[86:89] offset:10240
	s_waitcnt lgkmcnt(0)
	s_barrier
	global_load_dwordx4 v[66:69], v190, s[80:81] offset:256
	global_load_dwordx4 v[70:73], v191, s[80:81] offset:256
	global_load_dwordx4 v[74:77], v190, s[86:87] offset:256
	global_load_dwordx4 v[78:81], v191, s[86:87] offset:256
	global_load_dwordx4 v[82:85], v188, s[96:97] offset:256
	global_load_dwordx4 v[86:89], v188, s[98:99] offset:256
	ds_read_b128 v[90:93], v119 offset:0
	ds_read_b128 v[208:211], v205 offset:0
	ds_read_b128 v[212:215], v119 offset:2560
	ds_read_b128 v[216:219], v119 offset:5120
	ds_read_b128 v[220:223], v119 offset:7680
	s_waitcnt lgkmcnt(3)
	v_mfma_f32_16x16x32_bf16 v[6:9], v[90:93], v[208:211], 0
	s_waitcnt lgkmcnt(2)
	v_mfma_f32_16x16x32_bf16 v[30:33], v[212:215], v[208:211], 0
	s_waitcnt vmcnt(11)
	ds_write_b128 v207, v[228:231] offset:0
	s_waitcnt lgkmcnt(2)
	v_mfma_f32_16x16x32_bf16 v[38:41], v[216:219], v[208:211], 0
	s_waitcnt lgkmcnt(1)
	v_mfma_f32_16x16x32_bf16 v[42:45], v[220:223], v[208:211], 0
	ds_read_b128 v[208:211], v205 offset:2560
	s_waitcnt lgkmcnt(0)
	v_mfma_f32_16x16x32_bf16 v[46:49], v[90:93], v[208:211], 0
	v_mfma_f32_16x16x32_bf16 v[26:29], v[212:215], v[208:211], 0
	s_waitcnt vmcnt(10)
	ds_write_b128 v207, v[232:235] offset:10240
	v_mfma_f32_16x16x32_bf16 v[14:17], v[216:219], v[208:211], 0
	v_mfma_f32_16x16x32_bf16 v[10:13], v[220:223], v[208:211], 0
	ds_read_b128 v[208:211], v205 offset:5120
	s_waitcnt lgkmcnt(0)
	v_mfma_f32_16x16x32_bf16 v[34:37], v[90:93], v[208:211], 0
	v_mfma_f32_16x16x32_bf16 v[22:25], v[212:215], v[208:211], 0
	s_waitcnt vmcnt(9)
	ds_write_b128 v207, v[236:239] offset:20480
	v_mfma_f32_16x16x32_bf16 v[18:21], v[216:219], v[208:211], 0
	v_mfma_f32_16x16x32_bf16 v[62:65], v[220:223], v[208:211], 0
	ds_read_b128 v[208:211], v205 offset:7680
	s_waitcnt lgkmcnt(0)
	v_mfma_f32_16x16x32_bf16 v[58:61], v[90:93], v[208:211], 0
	ds_read_b128 v[90:93], v119 offset:64
	v_mfma_f32_16x16x32_bf16 v[54:57], v[212:215], v[208:211], 0
	s_waitcnt vmcnt(8)
	ds_write_b128 v207, v[240:243] offset:30720
	ds_read_b128 v[212:215], v119 offset:2624
	v_mfma_f32_16x16x32_bf16 v[50:53], v[216:219], v[208:211], 0
	ds_read_b128 v[216:219], v119 offset:5184
	v_mfma_f32_16x16x32_bf16 v[2:5], v[220:223], v[208:211], 0
	ds_read_b128 v[220:223], v119 offset:7744
	ds_read_b128 v[208:211], v205 offset:64
	ds_read_b128 v[224:227], v205 offset:7744
	s_waitcnt lgkmcnt(1)
	v_mfma_f32_16x16x32_bf16 v[6:9], v[90:93], v[208:211], v[6:9]
	v_mfma_f32_16x16x32_bf16 v[30:33], v[212:215], v[208:211], v[30:33]
	s_waitcnt vmcnt(7)
	ds_write_b128 v0, v[244:247] offset:20480
	v_mfma_f32_16x16x32_bf16 v[38:41], v[216:219], v[208:211], v[38:41]
	v_mfma_f32_16x16x32_bf16 v[42:45], v[220:223], v[208:211], v[42:45]
	ds_read_b128 v[208:211], v205 offset:2624
	s_waitcnt lgkmcnt(0)
	v_mfma_f32_16x16x32_bf16 v[46:49], v[90:93], v[208:211], v[46:49]
	v_mfma_f32_16x16x32_bf16 v[26:29], v[212:215], v[208:211], v[26:29]
	s_waitcnt vmcnt(6)
	ds_write_b128 v0, v[248:251] offset:30720
	v_mfma_f32_16x16x32_bf16 v[14:17], v[216:219], v[208:211], v[14:17]
	v_mfma_f32_16x16x32_bf16 v[10:13], v[220:223], v[208:211], v[10:13]
	ds_read_b128 v[208:211], v205 offset:5184
	s_waitcnt lgkmcnt(0)
	v_mfma_f32_16x16x32_bf16 v[34:37], v[90:93], v[208:211], v[34:37]
	v_mfma_f32_16x16x32_bf16 v[22:25], v[212:215], v[208:211], v[22:25]
	v_mfma_f32_16x16x32_bf16 v[18:21], v[216:219], v[208:211], v[18:21]
	v_mfma_f32_16x16x32_bf16 v[62:65], v[220:223], v[208:211], v[62:65]
	v_mfma_f32_16x16x32_bf16 v[58:61], v[90:93], v[224:227], v[58:61]
	s_waitcnt lgkmcnt(0)
	v_mfma_f32_16x16x32_bf16 v[54:57], v[212:215], v[224:227], v[54:57]
	s_barrier
	v_mfma_f32_16x16x32_bf16 v[50:53], v[216:219], v[224:227], v[50:53]
	v_mfma_f32_16x16x32_bf16 v[2:5], v[220:223], v[224:227], v[2:5]
	global_load_dwordx4 v[228:231], v190, s[80:81] offset:384
	global_load_dwordx4 v[232:235], v191, s[80:81] offset:384
	global_load_dwordx4 v[236:239], v190, s[86:87] offset:384
	global_load_dwordx4 v[240:243], v191, s[86:87] offset:384
	global_load_dwordx4 v[244:247], v188, s[96:97] offset:384
	global_load_dwordx4 v[248:251], v188, s[98:99] offset:384
	ds_read_b128 v[90:93], v119 offset:20480
	ds_read_b128 v[208:211], v205 offset:40960
	ds_read_b128 v[212:215], v119 offset:23040
	ds_read_b128 v[216:219], v119 offset:25600
	ds_read_b128 v[220:223], v119 offset:28160
	s_waitcnt lgkmcnt(3)
	v_mfma_f32_16x16x32_bf16 v[6:9], v[90:93], v[208:211], v[6:9]
	s_waitcnt lgkmcnt(2)
	v_mfma_f32_16x16x32_bf16 v[30:33], v[212:215], v[208:211], v[30:33]
	s_waitcnt vmcnt(11)
	ds_write_b128 v206, v[66:69] offset:0
	s_waitcnt lgkmcnt(2)
	v_mfma_f32_16x16x32_bf16 v[38:41], v[216:219], v[208:211], v[38:41]
	s_waitcnt lgkmcnt(1)
	v_mfma_f32_16x16x32_bf16 v[42:45], v[220:223], v[208:211], v[42:45]
	ds_read_b128 v[208:211], v205 offset:43520
	s_waitcnt lgkmcnt(0)
	v_mfma_f32_16x16x32_bf16 v[46:49], v[90:93], v[208:211], v[46:49]
	v_mfma_f32_16x16x32_bf16 v[26:29], v[212:215], v[208:211], v[26:29]
	s_waitcnt vmcnt(10)
	ds_write_b128 v206, v[70:73] offset:10240
	v_mfma_f32_16x16x32_bf16 v[14:17], v[216:219], v[208:211], v[14:17]
	v_mfma_f32_16x16x32_bf16 v[10:13], v[220:223], v[208:211], v[10:13]
	ds_read_b128 v[208:211], v205 offset:46080
	s_waitcnt lgkmcnt(0)
	v_mfma_f32_16x16x32_bf16 v[34:37], v[90:93], v[208:211], v[34:37]
	v_mfma_f32_16x16x32_bf16 v[22:25], v[212:215], v[208:211], v[22:25]
	s_waitcnt vmcnt(9)
	ds_write_b128 v206, v[74:77] offset:20480
	v_mfma_f32_16x16x32_bf16 v[18:21], v[216:219], v[208:211], v[18:21]
	v_mfma_f32_16x16x32_bf16 v[62:65], v[220:223], v[208:211], v[62:65]
	ds_read_b128 v[208:211], v205 offset:48640
	s_waitcnt lgkmcnt(0)
	v_mfma_f32_16x16x32_bf16 v[58:61], v[90:93], v[208:211], v[58:61]
	ds_read_b128 v[90:93], v119 offset:20544
	v_mfma_f32_16x16x32_bf16 v[54:57], v[212:215], v[208:211], v[54:57]
	s_waitcnt vmcnt(8)
	ds_write_b128 v206, v[78:81] offset:30720
	ds_read_b128 v[212:215], v119 offset:23104
	v_mfma_f32_16x16x32_bf16 v[50:53], v[216:219], v[208:211], v[50:53]
	ds_read_b128 v[216:219], v119 offset:25664
	v_mfma_f32_16x16x32_bf16 v[2:5], v[220:223], v[208:211], v[2:5]
	ds_read_b128 v[220:223], v119 offset:28224
	ds_read_b128 v[208:211], v205 offset:41024
	ds_read_b128 v[224:227], v205 offset:48704
	s_waitcnt lgkmcnt(1)
	v_mfma_f32_16x16x32_bf16 v[6:9], v[90:93], v[208:211], v[6:9]
	v_mfma_f32_16x16x32_bf16 v[30:33], v[212:215], v[208:211], v[30:33]
	s_waitcnt vmcnt(7)
	ds_write_b128 v0, v[82:85] offset:0
	v_mfma_f32_16x16x32_bf16 v[38:41], v[216:219], v[208:211], v[38:41]
	v_mfma_f32_16x16x32_bf16 v[42:45], v[220:223], v[208:211], v[42:45]
	ds_read_b128 v[208:211], v205 offset:43584
	s_waitcnt lgkmcnt(0)
	v_mfma_f32_16x16x32_bf16 v[46:49], v[90:93], v[208:211], v[46:49]
	v_mfma_f32_16x16x32_bf16 v[26:29], v[212:215], v[208:211], v[26:29]
	s_waitcnt vmcnt(6)
	ds_write_b128 v0, v[86:89] offset:10240
	v_mfma_f32_16x16x32_bf16 v[14:17], v[216:219], v[208:211], v[14:17]
	v_mfma_f32_16x16x32_bf16 v[10:13], v[220:223], v[208:211], v[10:13]
	ds_read_b128 v[208:211], v205 offset:46144
	s_waitcnt lgkmcnt(0)
	v_mfma_f32_16x16x32_bf16 v[34:37], v[90:93], v[208:211], v[34:37]
	v_mfma_f32_16x16x32_bf16 v[22:25], v[212:215], v[208:211], v[22:25]
	v_mfma_f32_16x16x32_bf16 v[18:21], v[216:219], v[208:211], v[18:21]
	v_mfma_f32_16x16x32_bf16 v[62:65], v[220:223], v[208:211], v[62:65]
	v_mfma_f32_16x16x32_bf16 v[58:61], v[90:93], v[224:227], v[58:61]
	s_waitcnt lgkmcnt(0)
	v_mfma_f32_16x16x32_bf16 v[54:57], v[212:215], v[224:227], v[54:57]
	s_barrier
	v_mfma_f32_16x16x32_bf16 v[50:53], v[216:219], v[224:227], v[50:53]
	v_mfma_f32_16x16x32_bf16 v[2:5], v[220:223], v[224:227], v[2:5]
	global_load_dwordx4 v[66:69], v190, s[80:81] offset:512
	global_load_dwordx4 v[70:73], v191, s[80:81] offset:512
	global_load_dwordx4 v[74:77], v190, s[86:87] offset:512
	global_load_dwordx4 v[78:81], v191, s[86:87] offset:512
	global_load_dwordx4 v[82:85], v188, s[96:97] offset:512
	global_load_dwordx4 v[86:89], v188, s[98:99] offset:512
	ds_read_b128 v[90:93], v119 offset:0
	ds_read_b128 v[208:211], v205 offset:0
	ds_read_b128 v[212:215], v119 offset:2560
	ds_read_b128 v[216:219], v119 offset:5120
	ds_read_b128 v[220:223], v119 offset:7680
	s_waitcnt lgkmcnt(3)
	v_mfma_f32_16x16x32_bf16 v[6:9], v[90:93], v[208:211], v[6:9]
	s_waitcnt lgkmcnt(2)
	v_mfma_f32_16x16x32_bf16 v[30:33], v[212:215], v[208:211], v[30:33]
	s_waitcnt vmcnt(11)
	ds_write_b128 v207, v[228:231] offset:0
	s_waitcnt lgkmcnt(2)
	v_mfma_f32_16x16x32_bf16 v[38:41], v[216:219], v[208:211], v[38:41]
	s_waitcnt lgkmcnt(1)
	v_mfma_f32_16x16x32_bf16 v[42:45], v[220:223], v[208:211], v[42:45]
	ds_read_b128 v[208:211], v205 offset:2560
	s_waitcnt lgkmcnt(0)
	v_mfma_f32_16x16x32_bf16 v[46:49], v[90:93], v[208:211], v[46:49]
	v_mfma_f32_16x16x32_bf16 v[26:29], v[212:215], v[208:211], v[26:29]
	s_waitcnt vmcnt(10)
	ds_write_b128 v207, v[232:235] offset:10240
	v_mfma_f32_16x16x32_bf16 v[14:17], v[216:219], v[208:211], v[14:17]
	v_mfma_f32_16x16x32_bf16 v[10:13], v[220:223], v[208:211], v[10:13]
	ds_read_b128 v[208:211], v205 offset:5120
	s_waitcnt lgkmcnt(0)
	v_mfma_f32_16x16x32_bf16 v[34:37], v[90:93], v[208:211], v[34:37]
	v_mfma_f32_16x16x32_bf16 v[22:25], v[212:215], v[208:211], v[22:25]
	s_waitcnt vmcnt(9)
	ds_write_b128 v207, v[236:239] offset:20480
	v_mfma_f32_16x16x32_bf16 v[18:21], v[216:219], v[208:211], v[18:21]
	v_mfma_f32_16x16x32_bf16 v[62:65], v[220:223], v[208:211], v[62:65]
	ds_read_b128 v[208:211], v205 offset:7680
	s_waitcnt lgkmcnt(0)
	v_mfma_f32_16x16x32_bf16 v[58:61], v[90:93], v[208:211], v[58:61]
	ds_read_b128 v[90:93], v119 offset:64
	v_mfma_f32_16x16x32_bf16 v[54:57], v[212:215], v[208:211], v[54:57]
	s_waitcnt vmcnt(8)
	ds_write_b128 v207, v[240:243] offset:30720
	ds_read_b128 v[212:215], v119 offset:2624
	v_mfma_f32_16x16x32_bf16 v[50:53], v[216:219], v[208:211], v[50:53]
	ds_read_b128 v[216:219], v119 offset:5184
	v_mfma_f32_16x16x32_bf16 v[2:5], v[220:223], v[208:211], v[2:5]
	ds_read_b128 v[220:223], v119 offset:7744
	ds_read_b128 v[208:211], v205 offset:64
	ds_read_b128 v[224:227], v205 offset:7744
	s_waitcnt lgkmcnt(1)
	v_mfma_f32_16x16x32_bf16 v[6:9], v[90:93], v[208:211], v[6:9]
	v_mfma_f32_16x16x32_bf16 v[30:33], v[212:215], v[208:211], v[30:33]
	s_waitcnt vmcnt(7)
	ds_write_b128 v0, v[244:247] offset:20480
	v_mfma_f32_16x16x32_bf16 v[38:41], v[216:219], v[208:211], v[38:41]
	v_mfma_f32_16x16x32_bf16 v[42:45], v[220:223], v[208:211], v[42:45]
	ds_read_b128 v[208:211], v205 offset:2624
	s_waitcnt lgkmcnt(0)
	v_mfma_f32_16x16x32_bf16 v[46:49], v[90:93], v[208:211], v[46:49]
	v_mfma_f32_16x16x32_bf16 v[26:29], v[212:215], v[208:211], v[26:29]
	s_waitcnt vmcnt(6)
	ds_write_b128 v0, v[248:251] offset:30720
	v_mfma_f32_16x16x32_bf16 v[14:17], v[216:219], v[208:211], v[14:17]
	v_mfma_f32_16x16x32_bf16 v[10:13], v[220:223], v[208:211], v[10:13]
	ds_read_b128 v[208:211], v205 offset:5184
	s_waitcnt lgkmcnt(0)
	v_mfma_f32_16x16x32_bf16 v[34:37], v[90:93], v[208:211], v[34:37]
	v_mfma_f32_16x16x32_bf16 v[22:25], v[212:215], v[208:211], v[22:25]
	v_mfma_f32_16x16x32_bf16 v[18:21], v[216:219], v[208:211], v[18:21]
	v_mfma_f32_16x16x32_bf16 v[62:65], v[220:223], v[208:211], v[62:65]
	v_mfma_f32_16x16x32_bf16 v[58:61], v[90:93], v[224:227], v[58:61]
	s_waitcnt lgkmcnt(0)
	v_mfma_f32_16x16x32_bf16 v[54:57], v[212:215], v[224:227], v[54:57]
	s_barrier
	v_mfma_f32_16x16x32_bf16 v[50:53], v[216:219], v[224:227], v[50:53]
	v_mfma_f32_16x16x32_bf16 v[2:5], v[220:223], v[224:227], v[2:5]
	global_load_dwordx4 v[228:231], v190, s[80:81] offset:640
	global_load_dwordx4 v[232:235], v191, s[80:81] offset:640
	global_load_dwordx4 v[236:239], v190, s[86:87] offset:640
	global_load_dwordx4 v[240:243], v191, s[86:87] offset:640
	global_load_dwordx4 v[244:247], v188, s[96:97] offset:640
	global_load_dwordx4 v[248:251], v188, s[98:99] offset:640
	ds_read_b128 v[90:93], v119 offset:20480
	ds_read_b128 v[208:211], v205 offset:40960
	ds_read_b128 v[212:215], v119 offset:23040
	ds_read_b128 v[216:219], v119 offset:25600
	ds_read_b128 v[220:223], v119 offset:28160
	s_waitcnt lgkmcnt(3)
	v_mfma_f32_16x16x32_bf16 v[6:9], v[90:93], v[208:211], v[6:9]
	s_waitcnt lgkmcnt(2)
	v_mfma_f32_16x16x32_bf16 v[30:33], v[212:215], v[208:211], v[30:33]
	s_waitcnt vmcnt(11)
	ds_write_b128 v206, v[66:69] offset:0
	s_waitcnt lgkmcnt(2)
	v_mfma_f32_16x16x32_bf16 v[38:41], v[216:219], v[208:211], v[38:41]
	s_waitcnt lgkmcnt(1)
	v_mfma_f32_16x16x32_bf16 v[42:45], v[220:223], v[208:211], v[42:45]
	ds_read_b128 v[208:211], v205 offset:43520
	s_waitcnt lgkmcnt(0)
	v_mfma_f32_16x16x32_bf16 v[46:49], v[90:93], v[208:211], v[46:49]
	v_mfma_f32_16x16x32_bf16 v[26:29], v[212:215], v[208:211], v[26:29]
	s_waitcnt vmcnt(10)
	ds_write_b128 v206, v[70:73] offset:10240
	v_mfma_f32_16x16x32_bf16 v[14:17], v[216:219], v[208:211], v[14:17]
	v_mfma_f32_16x16x32_bf16 v[10:13], v[220:223], v[208:211], v[10:13]
	ds_read_b128 v[208:211], v205 offset:46080
	s_waitcnt lgkmcnt(0)
	v_mfma_f32_16x16x32_bf16 v[34:37], v[90:93], v[208:211], v[34:37]
	v_mfma_f32_16x16x32_bf16 v[22:25], v[212:215], v[208:211], v[22:25]
	s_waitcnt vmcnt(9)
	ds_write_b128 v206, v[74:77] offset:20480
	v_mfma_f32_16x16x32_bf16 v[18:21], v[216:219], v[208:211], v[18:21]
	v_mfma_f32_16x16x32_bf16 v[62:65], v[220:223], v[208:211], v[62:65]
	ds_read_b128 v[208:211], v205 offset:48640
	s_waitcnt lgkmcnt(0)
	v_mfma_f32_16x16x32_bf16 v[58:61], v[90:93], v[208:211], v[58:61]
	ds_read_b128 v[90:93], v119 offset:20544
	v_mfma_f32_16x16x32_bf16 v[54:57], v[212:215], v[208:211], v[54:57]
	s_waitcnt vmcnt(8)
	ds_write_b128 v206, v[78:81] offset:30720
	ds_read_b128 v[212:215], v119 offset:23104
	v_mfma_f32_16x16x32_bf16 v[50:53], v[216:219], v[208:211], v[50:53]
	ds_read_b128 v[216:219], v119 offset:25664
	v_mfma_f32_16x16x32_bf16 v[2:5], v[220:223], v[208:211], v[2:5]
	ds_read_b128 v[220:223], v119 offset:28224
	ds_read_b128 v[208:211], v205 offset:41024
	ds_read_b128 v[224:227], v205 offset:48704
	s_waitcnt lgkmcnt(1)
	v_mfma_f32_16x16x32_bf16 v[6:9], v[90:93], v[208:211], v[6:9]
	v_mfma_f32_16x16x32_bf16 v[30:33], v[212:215], v[208:211], v[30:33]
	s_waitcnt vmcnt(7)
	ds_write_b128 v0, v[82:85] offset:0
	v_mfma_f32_16x16x32_bf16 v[38:41], v[216:219], v[208:211], v[38:41]
	v_mfma_f32_16x16x32_bf16 v[42:45], v[220:223], v[208:211], v[42:45]
	ds_read_b128 v[208:211], v205 offset:43584
	s_waitcnt lgkmcnt(0)
	v_mfma_f32_16x16x32_bf16 v[46:49], v[90:93], v[208:211], v[46:49]
	v_mfma_f32_16x16x32_bf16 v[26:29], v[212:215], v[208:211], v[26:29]
	s_waitcnt vmcnt(6)
	ds_write_b128 v0, v[86:89] offset:10240
	v_mfma_f32_16x16x32_bf16 v[14:17], v[216:219], v[208:211], v[14:17]
	v_mfma_f32_16x16x32_bf16 v[10:13], v[220:223], v[208:211], v[10:13]
	ds_read_b128 v[208:211], v205 offset:46144
	s_waitcnt lgkmcnt(0)
	v_mfma_f32_16x16x32_bf16 v[34:37], v[90:93], v[208:211], v[34:37]
	v_mfma_f32_16x16x32_bf16 v[22:25], v[212:215], v[208:211], v[22:25]
	v_mfma_f32_16x16x32_bf16 v[18:21], v[216:219], v[208:211], v[18:21]
	v_mfma_f32_16x16x32_bf16 v[62:65], v[220:223], v[208:211], v[62:65]
	v_mfma_f32_16x16x32_bf16 v[58:61], v[90:93], v[224:227], v[58:61]
	s_waitcnt lgkmcnt(0)
	v_mfma_f32_16x16x32_bf16 v[54:57], v[212:215], v[224:227], v[54:57]
	s_barrier
	v_mfma_f32_16x16x32_bf16 v[50:53], v[216:219], v[224:227], v[50:53]
	v_mfma_f32_16x16x32_bf16 v[2:5], v[220:223], v[224:227], v[2:5]
	global_load_dwordx4 v[66:69], v190, s[80:81] offset:768
	global_load_dwordx4 v[70:73], v191, s[80:81] offset:768
	global_load_dwordx4 v[74:77], v190, s[86:87] offset:768
	global_load_dwordx4 v[78:81], v191, s[86:87] offset:768
	global_load_dwordx4 v[82:85], v188, s[96:97] offset:768
	global_load_dwordx4 v[86:89], v188, s[98:99] offset:768
	ds_read_b128 v[90:93], v119 offset:0
	ds_read_b128 v[208:211], v205 offset:0
	ds_read_b128 v[212:215], v119 offset:2560
	ds_read_b128 v[216:219], v119 offset:5120
	ds_read_b128 v[220:223], v119 offset:7680
	s_waitcnt lgkmcnt(3)
	v_mfma_f32_16x16x32_bf16 v[6:9], v[90:93], v[208:211], v[6:9]
	s_waitcnt lgkmcnt(2)
	v_mfma_f32_16x16x32_bf16 v[30:33], v[212:215], v[208:211], v[30:33]
	s_waitcnt vmcnt(11)
	ds_write_b128 v207, v[228:231] offset:0
	s_waitcnt lgkmcnt(2)
	v_mfma_f32_16x16x32_bf16 v[38:41], v[216:219], v[208:211], v[38:41]
	s_waitcnt lgkmcnt(1)
	v_mfma_f32_16x16x32_bf16 v[42:45], v[220:223], v[208:211], v[42:45]
	ds_read_b128 v[208:211], v205 offset:2560
	s_waitcnt lgkmcnt(0)
	v_mfma_f32_16x16x32_bf16 v[46:49], v[90:93], v[208:211], v[46:49]
	v_mfma_f32_16x16x32_bf16 v[26:29], v[212:215], v[208:211], v[26:29]
	s_waitcnt vmcnt(10)
	ds_write_b128 v207, v[232:235] offset:10240
	v_mfma_f32_16x16x32_bf16 v[14:17], v[216:219], v[208:211], v[14:17]
	v_mfma_f32_16x16x32_bf16 v[10:13], v[220:223], v[208:211], v[10:13]
	ds_read_b128 v[208:211], v205 offset:5120
	s_waitcnt lgkmcnt(0)
	v_mfma_f32_16x16x32_bf16 v[34:37], v[90:93], v[208:211], v[34:37]
	v_mfma_f32_16x16x32_bf16 v[22:25], v[212:215], v[208:211], v[22:25]
	s_waitcnt vmcnt(9)
	ds_write_b128 v207, v[236:239] offset:20480
	v_mfma_f32_16x16x32_bf16 v[18:21], v[216:219], v[208:211], v[18:21]
	v_mfma_f32_16x16x32_bf16 v[62:65], v[220:223], v[208:211], v[62:65]
	ds_read_b128 v[208:211], v205 offset:7680
	s_waitcnt lgkmcnt(0)
	v_mfma_f32_16x16x32_bf16 v[58:61], v[90:93], v[208:211], v[58:61]
	ds_read_b128 v[90:93], v119 offset:64
	v_mfma_f32_16x16x32_bf16 v[54:57], v[212:215], v[208:211], v[54:57]
	s_waitcnt vmcnt(8)
	ds_write_b128 v207, v[240:243] offset:30720
	ds_read_b128 v[212:215], v119 offset:2624
	v_mfma_f32_16x16x32_bf16 v[50:53], v[216:219], v[208:211], v[50:53]
	ds_read_b128 v[216:219], v119 offset:5184
	v_mfma_f32_16x16x32_bf16 v[2:5], v[220:223], v[208:211], v[2:5]
	ds_read_b128 v[220:223], v119 offset:7744
	ds_read_b128 v[208:211], v205 offset:64
	ds_read_b128 v[224:227], v205 offset:7744
	s_waitcnt lgkmcnt(1)
	v_mfma_f32_16x16x32_bf16 v[6:9], v[90:93], v[208:211], v[6:9]
	v_mfma_f32_16x16x32_bf16 v[30:33], v[212:215], v[208:211], v[30:33]
	s_waitcnt vmcnt(7)
	ds_write_b128 v0, v[244:247] offset:20480
	v_mfma_f32_16x16x32_bf16 v[38:41], v[216:219], v[208:211], v[38:41]
	v_mfma_f32_16x16x32_bf16 v[42:45], v[220:223], v[208:211], v[42:45]
	ds_read_b128 v[208:211], v205 offset:2624
	s_waitcnt lgkmcnt(0)
	v_mfma_f32_16x16x32_bf16 v[46:49], v[90:93], v[208:211], v[46:49]
	v_mfma_f32_16x16x32_bf16 v[26:29], v[212:215], v[208:211], v[26:29]
	s_waitcnt vmcnt(6)
	ds_write_b128 v0, v[248:251] offset:30720
	v_mfma_f32_16x16x32_bf16 v[14:17], v[216:219], v[208:211], v[14:17]
	v_mfma_f32_16x16x32_bf16 v[10:13], v[220:223], v[208:211], v[10:13]
	ds_read_b128 v[208:211], v205 offset:5184
	s_waitcnt lgkmcnt(0)
	v_mfma_f32_16x16x32_bf16 v[34:37], v[90:93], v[208:211], v[34:37]
	v_mfma_f32_16x16x32_bf16 v[22:25], v[212:215], v[208:211], v[22:25]
	v_mfma_f32_16x16x32_bf16 v[18:21], v[216:219], v[208:211], v[18:21]
	v_mfma_f32_16x16x32_bf16 v[62:65], v[220:223], v[208:211], v[62:65]
	v_mfma_f32_16x16x32_bf16 v[58:61], v[90:93], v[224:227], v[58:61]
	s_waitcnt lgkmcnt(0)
	v_mfma_f32_16x16x32_bf16 v[54:57], v[212:215], v[224:227], v[54:57]
	s_barrier
	v_mfma_f32_16x16x32_bf16 v[50:53], v[216:219], v[224:227], v[50:53]
	v_mfma_f32_16x16x32_bf16 v[2:5], v[220:223], v[224:227], v[2:5]
	global_load_dwordx4 v[228:231], v190, s[80:81] offset:896
	global_load_dwordx4 v[232:235], v191, s[80:81] offset:896
	global_load_dwordx4 v[236:239], v190, s[86:87] offset:896
	global_load_dwordx4 v[240:243], v191, s[86:87] offset:896
	global_load_dwordx4 v[244:247], v188, s[96:97] offset:896
	global_load_dwordx4 v[248:251], v188, s[98:99] offset:896
	ds_read_b128 v[90:93], v119 offset:20480
	ds_read_b128 v[208:211], v205 offset:40960
	ds_read_b128 v[212:215], v119 offset:23040
	ds_read_b128 v[216:219], v119 offset:25600
	ds_read_b128 v[220:223], v119 offset:28160
	s_waitcnt lgkmcnt(3)
	v_mfma_f32_16x16x32_bf16 v[6:9], v[90:93], v[208:211], v[6:9]
	s_waitcnt lgkmcnt(2)
	v_mfma_f32_16x16x32_bf16 v[30:33], v[212:215], v[208:211], v[30:33]
	s_waitcnt vmcnt(11)
	ds_write_b128 v206, v[66:69] offset:0
	s_waitcnt lgkmcnt(2)
	v_mfma_f32_16x16x32_bf16 v[38:41], v[216:219], v[208:211], v[38:41]
	s_waitcnt lgkmcnt(1)
	v_mfma_f32_16x16x32_bf16 v[42:45], v[220:223], v[208:211], v[42:45]
	ds_read_b128 v[208:211], v205 offset:43520
	s_waitcnt lgkmcnt(0)
	v_mfma_f32_16x16x32_bf16 v[46:49], v[90:93], v[208:211], v[46:49]
	v_mfma_f32_16x16x32_bf16 v[26:29], v[212:215], v[208:211], v[26:29]
	s_waitcnt vmcnt(10)
	ds_write_b128 v206, v[70:73] offset:10240
	v_mfma_f32_16x16x32_bf16 v[14:17], v[216:219], v[208:211], v[14:17]
	v_mfma_f32_16x16x32_bf16 v[10:13], v[220:223], v[208:211], v[10:13]
	ds_read_b128 v[208:211], v205 offset:46080
	s_waitcnt lgkmcnt(0)
	v_mfma_f32_16x16x32_bf16 v[34:37], v[90:93], v[208:211], v[34:37]
	v_mfma_f32_16x16x32_bf16 v[22:25], v[212:215], v[208:211], v[22:25]
	s_waitcnt vmcnt(9)
	ds_write_b128 v206, v[74:77] offset:20480
	v_mfma_f32_16x16x32_bf16 v[18:21], v[216:219], v[208:211], v[18:21]
	v_mfma_f32_16x16x32_bf16 v[62:65], v[220:223], v[208:211], v[62:65]
	ds_read_b128 v[208:211], v205 offset:48640
	s_waitcnt lgkmcnt(0)
	v_mfma_f32_16x16x32_bf16 v[58:61], v[90:93], v[208:211], v[58:61]
	ds_read_b128 v[90:93], v119 offset:20544
	v_mfma_f32_16x16x32_bf16 v[54:57], v[212:215], v[208:211], v[54:57]
	s_waitcnt vmcnt(8)
	ds_write_b128 v206, v[78:81] offset:30720
	ds_read_b128 v[212:215], v119 offset:23104
	v_mfma_f32_16x16x32_bf16 v[50:53], v[216:219], v[208:211], v[50:53]
	ds_read_b128 v[216:219], v119 offset:25664
	v_mfma_f32_16x16x32_bf16 v[2:5], v[220:223], v[208:211], v[2:5]
	ds_read_b128 v[220:223], v119 offset:28224
	ds_read_b128 v[208:211], v205 offset:41024
	ds_read_b128 v[224:227], v205 offset:48704
	s_waitcnt lgkmcnt(1)
	v_mfma_f32_16x16x32_bf16 v[6:9], v[90:93], v[208:211], v[6:9]
	v_mfma_f32_16x16x32_bf16 v[30:33], v[212:215], v[208:211], v[30:33]
	s_waitcnt vmcnt(7)
	ds_write_b128 v0, v[82:85] offset:0
	v_mfma_f32_16x16x32_bf16 v[38:41], v[216:219], v[208:211], v[38:41]
	v_mfma_f32_16x16x32_bf16 v[42:45], v[220:223], v[208:211], v[42:45]
	ds_read_b128 v[208:211], v205 offset:43584
	s_waitcnt lgkmcnt(0)
	v_mfma_f32_16x16x32_bf16 v[46:49], v[90:93], v[208:211], v[46:49]
	v_mfma_f32_16x16x32_bf16 v[26:29], v[212:215], v[208:211], v[26:29]
	s_waitcnt vmcnt(6)
	ds_write_b128 v0, v[86:89] offset:10240
	s_movk_i32 s10, 0x800
	s_mov_b32 s11, 0
	v_lshl_add_u64 v[82:83], v[128:129], 0, s[10:11]
	v_lshl_add_u64 v[84:85], v[132:133], 0, s[10:11]
	v_lshl_add_u64 v[86:87], v[152:153], 0, s[10:11]
	v_lshl_add_u64 v[88:89], v[154:155], 0, s[10:11]
	global_load_dwordx2 v[66:67], v[82:83], off
	global_load_dwordx2 v[68:69], v[82:83], off offset:32
	global_load_dwordx2 v[70:71], v[84:85], off
	global_load_dwordx2 v[72:73], v[84:85], off offset:32
	global_load_dwordx2 v[74:75], v[86:87], off
	global_load_dwordx2 v[76:77], v[86:87], off offset:32
	global_load_dwordx2 v[78:79], v[88:89], off
	global_load_dwordx2 v[80:81], v[88:89], off offset:32
	v_mfma_f32_16x16x32_bf16 v[14:17], v[216:219], v[208:211], v[14:17]
	v_mfma_f32_16x16x32_bf16 v[10:13], v[220:223], v[208:211], v[10:13]
	ds_read_b128 v[208:211], v205 offset:46144
	s_waitcnt lgkmcnt(0)
	v_mfma_f32_16x16x32_bf16 v[34:37], v[90:93], v[208:211], v[34:37]
	v_mfma_f32_16x16x32_bf16 v[22:25], v[212:215], v[208:211], v[22:25]
	v_mfma_f32_16x16x32_bf16 v[18:21], v[216:219], v[208:211], v[18:21]
	v_mfma_f32_16x16x32_bf16 v[62:65], v[220:223], v[208:211], v[62:65]
	v_mfma_f32_16x16x32_bf16 v[58:61], v[90:93], v[224:227], v[58:61]
	s_waitcnt lgkmcnt(0)
	v_mfma_f32_16x16x32_bf16 v[54:57], v[212:215], v[224:227], v[54:57]
	s_barrier
	v_mfma_f32_16x16x32_bf16 v[50:53], v[216:219], v[224:227], v[50:53]
	v_mfma_f32_16x16x32_bf16 v[2:5], v[220:223], v[224:227], v[2:5]
	ds_read_b128 v[90:93], v119 offset:0
	ds_read_b128 v[208:211], v205 offset:0
	ds_read_b128 v[212:215], v119 offset:2560
	ds_read_b128 v[216:219], v119 offset:5120
	ds_read_b128 v[220:223], v119 offset:7680
	s_waitcnt lgkmcnt(3)
	v_mfma_f32_16x16x32_bf16 v[6:9], v[90:93], v[208:211], v[6:9]
	s_waitcnt lgkmcnt(2)
	v_mfma_f32_16x16x32_bf16 v[30:33], v[212:215], v[208:211], v[30:33]
	s_waitcnt vmcnt(13)
	ds_write_b128 v207, v[228:231] offset:0
	s_waitcnt lgkmcnt(2)
	v_mfma_f32_16x16x32_bf16 v[38:41], v[216:219], v[208:211], v[38:41]
	s_waitcnt lgkmcnt(1)
	v_mfma_f32_16x16x32_bf16 v[42:45], v[220:223], v[208:211], v[42:45]
	ds_read_b128 v[208:211], v205 offset:2560
	s_waitcnt lgkmcnt(0)
	v_mfma_f32_16x16x32_bf16 v[46:49], v[90:93], v[208:211], v[46:49]
	v_mfma_f32_16x16x32_bf16 v[26:29], v[212:215], v[208:211], v[26:29]
	s_waitcnt vmcnt(12)
	ds_write_b128 v207, v[232:235] offset:10240
	v_mfma_f32_16x16x32_bf16 v[14:17], v[216:219], v[208:211], v[14:17]
	v_mfma_f32_16x16x32_bf16 v[10:13], v[220:223], v[208:211], v[10:13]
	ds_read_b128 v[208:211], v205 offset:5120
	s_waitcnt lgkmcnt(0)
	v_mfma_f32_16x16x32_bf16 v[34:37], v[90:93], v[208:211], v[34:37]
	v_mfma_f32_16x16x32_bf16 v[22:25], v[212:215], v[208:211], v[22:25]
	s_waitcnt vmcnt(11)
	ds_write_b128 v207, v[236:239] offset:20480
	v_mfma_f32_16x16x32_bf16 v[18:21], v[216:219], v[208:211], v[18:21]
	v_mfma_f32_16x16x32_bf16 v[62:65], v[220:223], v[208:211], v[62:65]
	ds_read_b128 v[208:211], v205 offset:7680
	s_waitcnt lgkmcnt(0)
	v_mfma_f32_16x16x32_bf16 v[58:61], v[90:93], v[208:211], v[58:61]
	ds_read_b128 v[90:93], v119 offset:64
	v_mfma_f32_16x16x32_bf16 v[54:57], v[212:215], v[208:211], v[54:57]
	s_waitcnt vmcnt(10)
	ds_write_b128 v207, v[240:243] offset:30720
	ds_read_b128 v[212:215], v119 offset:2624
	v_mfma_f32_16x16x32_bf16 v[50:53], v[216:219], v[208:211], v[50:53]
	ds_read_b128 v[216:219], v119 offset:5184
	v_mfma_f32_16x16x32_bf16 v[2:5], v[220:223], v[208:211], v[2:5]
	ds_read_b128 v[220:223], v119 offset:7744
	ds_read_b128 v[208:211], v205 offset:64
	ds_read_b128 v[224:227], v205 offset:7744
	s_waitcnt lgkmcnt(1)
	v_mfma_f32_16x16x32_bf16 v[6:9], v[90:93], v[208:211], v[6:9]
	v_mfma_f32_16x16x32_bf16 v[30:33], v[212:215], v[208:211], v[30:33]
	s_waitcnt vmcnt(9)
	ds_write_b128 v0, v[244:247] offset:20480
	v_mfma_f32_16x16x32_bf16 v[38:41], v[216:219], v[208:211], v[38:41]
	v_mfma_f32_16x16x32_bf16 v[42:45], v[220:223], v[208:211], v[42:45]
	ds_read_b128 v[208:211], v205 offset:2624
	s_waitcnt lgkmcnt(0)
	v_mfma_f32_16x16x32_bf16 v[46:49], v[90:93], v[208:211], v[46:49]
	v_mfma_f32_16x16x32_bf16 v[26:29], v[212:215], v[208:211], v[26:29]
	s_waitcnt vmcnt(8)
	ds_write_b128 v0, v[248:251] offset:30720
	s_add_u32 s80, s80, 0xc00
	s_addc_u32 s81, s81, 0
	s_add_u32 s86, s80, 0x1f0000
	s_addc_u32 s87, s81, 0
	s_add_u32 s96, s96, 0x100000
	s_addc_u32 s97, s97, 0
	s_add_u32 s98, s96, 0x10000
	s_addc_u32 s99, s97, 0
	global_load_dwordx4 v[228:231], v190, s[80:81] offset:0
	global_load_dwordx4 v[232:235], v191, s[80:81] offset:0
	global_load_dwordx4 v[236:239], v190, s[86:87] offset:0
	global_load_dwordx4 v[240:243], v191, s[86:87] offset:0
	global_load_dwordx4 v[244:247], v188, s[96:97] offset:0
	global_load_dwordx4 v[248:251], v188, s[98:99] offset:0
	v_mfma_f32_16x16x32_bf16 v[14:17], v[216:219], v[208:211], v[14:17]
	v_mfma_f32_16x16x32_bf16 v[10:13], v[220:223], v[208:211], v[10:13]
	ds_read_b128 v[208:211], v205 offset:5184
	s_waitcnt lgkmcnt(0)
	v_mfma_f32_16x16x32_bf16 v[34:37], v[90:93], v[208:211], v[34:37]
	v_mfma_f32_16x16x32_bf16 v[22:25], v[212:215], v[208:211], v[22:25]
	v_mfma_f32_16x16x32_bf16 v[18:21], v[216:219], v[208:211], v[18:21]
	v_mfma_f32_16x16x32_bf16 v[62:65], v[220:223], v[208:211], v[62:65]
	v_mfma_f32_16x16x32_bf16 v[58:61], v[90:93], v[224:227], v[58:61]
	s_waitcnt lgkmcnt(0)
	v_mfma_f32_16x16x32_bf16 v[54:57], v[212:215], v[224:227], v[54:57]
	s_barrier
	v_mfma_f32_16x16x32_bf16 v[50:53], v[216:219], v[224:227], v[50:53]
	v_mfma_f32_16x16x32_bf16 v[2:5], v[220:223], v[224:227], v[2:5]
	ds_read_b128 v[90:93], v119 offset:20480
	ds_read_b128 v[208:211], v205 offset:40960
	ds_read_b128 v[212:215], v119 offset:23040
	ds_read_b128 v[216:219], v119 offset:25600
	ds_read_b128 v[220:223], v119 offset:28160
	s_waitcnt lgkmcnt(3)
	v_mfma_f32_16x16x32_bf16 v[6:9], v[90:93], v[208:211], v[6:9]
	s_waitcnt lgkmcnt(2)
	v_mfma_f32_16x16x32_bf16 v[30:33], v[212:215], v[208:211], v[30:33]
	s_waitcnt lgkmcnt(1)
	v_mfma_f32_16x16x32_bf16 v[38:41], v[216:219], v[208:211], v[38:41]
	s_waitcnt lgkmcnt(0)
	v_mfma_f32_16x16x32_bf16 v[42:45], v[220:223], v[208:211], v[42:45]
	ds_read_b128 v[208:211], v205 offset:43520
	s_waitcnt lgkmcnt(0)
	v_mfma_f32_16x16x32_bf16 v[46:49], v[90:93], v[208:211], v[46:49]
	v_mfma_f32_16x16x32_bf16 v[26:29], v[212:215], v[208:211], v[26:29]
	v_mfma_f32_16x16x32_bf16 v[14:17], v[216:219], v[208:211], v[14:17]
	v_mfma_f32_16x16x32_bf16 v[10:13], v[220:223], v[208:211], v[10:13]
	ds_read_b128 v[208:211], v205 offset:46080
	s_waitcnt lgkmcnt(0)
	v_mfma_f32_16x16x32_bf16 v[34:37], v[90:93], v[208:211], v[34:37]
	v_mfma_f32_16x16x32_bf16 v[22:25], v[212:215], v[208:211], v[22:25]
	v_mfma_f32_16x16x32_bf16 v[18:21], v[216:219], v[208:211], v[18:21]
	v_mfma_f32_16x16x32_bf16 v[62:65], v[220:223], v[208:211], v[62:65]
	ds_read_b128 v[208:211], v205 offset:48640
	s_waitcnt lgkmcnt(0)
	v_mfma_f32_16x16x32_bf16 v[58:61], v[90:93], v[208:211], v[58:61]
	ds_read_b128 v[90:93], v119 offset:20544
	v_mfma_f32_16x16x32_bf16 v[54:57], v[212:215], v[208:211], v[54:57]
	ds_read_b128 v[212:215], v119 offset:23104
	v_mfma_f32_16x16x32_bf16 v[50:53], v[216:219], v[208:211], v[50:53]
	ds_read_b128 v[216:219], v119 offset:25664
	v_mfma_f32_16x16x32_bf16 v[2:5], v[220:223], v[208:211], v[2:5]
	ds_read_b128 v[220:223], v119 offset:28224
	ds_read_b128 v[208:211], v205 offset:41024
	ds_read_b128 v[224:227], v205 offset:48704
	s_waitcnt lgkmcnt(1)
	v_mfma_f32_16x16x32_bf16 v[6:9], v[90:93], v[208:211], v[6:9]
	s_waitcnt vmcnt(6)
	v_mfma_f32_16x16x32_bf16 v[30:33], v[212:215], v[208:211], v[30:33]
	v_mfma_f32_16x16x32_bf16 v[38:41], v[216:219], v[208:211], v[38:41]
	v_mfma_f32_16x16x32_bf16 v[42:45], v[220:223], v[208:211], v[42:45]
	v_cvt_f32_ubyte0_e32 v86, v66
	v_cvt_f32_ubyte1_e32 v87, v66
	v_cvt_f32_ubyte2_e32 v88, v66
	v_cvt_f32_ubyte3_e32 v89, v66
	v_mul_f32_e32 v86, s34, v86
	v_mul_f32_e32 v87, s34, v87
	v_mul_f32_e32 v88, s34, v88
	v_mul_f32_e32 v89, s34, v89
	v_fma_f32 v184, v6, v86, v184
	v_fma_f32 v185, v7, v87, v185
	v_fma_f32 v186, v8, v88, v186
	v_fma_f32 v187, v9, v89, v187
	ds_read_b128 v[208:211], v205 offset:43584
	s_waitcnt lgkmcnt(0)
	v_mfma_f32_16x16x32_bf16 v[46:49], v[90:93], v[208:211], v[46:49]
	v_cvt_f32_ubyte0_e32 v82, v67
	v_cvt_f32_ubyte1_e32 v83, v67
	v_cvt_f32_ubyte2_e32 v84, v67
	v_cvt_f32_ubyte3_e32 v85, v67
	v_mul_f32_e32 v82, s34, v82
	v_mul_f32_e32 v83, s34, v83
	v_mul_f32_e32 v84, s34, v84
	v_mul_f32_e32 v85, s34, v85
	v_fma_f32 v180, v30, v82, v180
	v_fma_f32 v181, v31, v83, v181
	v_fma_f32 v182, v32, v84, v182
	v_fma_f32 v183, v33, v85, v183
	v_mfma_f32_16x16x32_bf16 v[26:29], v[212:215], v[208:211], v[26:29]
	v_cvt_f32_ubyte0_e32 v86, v68
	v_cvt_f32_ubyte1_e32 v87, v68
	v_cvt_f32_ubyte2_e32 v88, v68
	v_cvt_f32_ubyte3_e32 v89, v68
	v_mul_f32_e32 v86, s34, v86
	v_mul_f32_e32 v87, s34, v87
	v_mul_f32_e32 v88, s34, v88
	v_mul_f32_e32 v89, s34, v89
	v_fma_f32 v176, v38, v86, v176
	v_fma_f32 v177, v39, v87, v177
	v_fma_f32 v178, v40, v88, v178
	v_fma_f32 v179, v41, v89, v179
	v_mfma_f32_16x16x32_bf16 v[14:17], v[216:219], v[208:211], v[14:17]
	v_cvt_f32_ubyte0_e32 v82, v69
	v_cvt_f32_ubyte1_e32 v83, v69
	v_cvt_f32_ubyte2_e32 v84, v69
	v_cvt_f32_ubyte3_e32 v85, v69
	v_mul_f32_e32 v82, s34, v82
	v_mul_f32_e32 v83, s34, v83
	v_mul_f32_e32 v84, s34, v84
	v_mul_f32_e32 v85, s34, v85
	v_fma_f32 v172, v42, v82, v172
	v_fma_f32 v173, v43, v83, v173
	v_fma_f32 v174, v44, v84, v174
	v_fma_f32 v175, v45, v85, v175
	v_mfma_f32_16x16x32_bf16 v[10:13], v[220:223], v[208:211], v[10:13]
	v_cvt_f32_ubyte0_e32 v86, v70
	v_cvt_f32_ubyte1_e32 v87, v70
	v_cvt_f32_ubyte2_e32 v88, v70
	v_cvt_f32_ubyte3_e32 v89, v70
	v_mul_f32_e32 v86, s34, v86
	v_mul_f32_e32 v87, s34, v87
	v_mul_f32_e32 v88, s34, v88
	v_mul_f32_e32 v89, s34, v89
	v_fma_f32 v168, v46, v86, v168
	v_fma_f32 v169, v47, v87, v169
	v_fma_f32 v170, v48, v88, v170
	v_fma_f32 v171, v49, v89, v171
	ds_read_b128 v[208:211], v205 offset:46144
	s_waitcnt lgkmcnt(0)
	v_mfma_f32_16x16x32_bf16 v[34:37], v[90:93], v[208:211], v[34:37]
	v_cvt_f32_ubyte0_e32 v82, v71
	v_cvt_f32_ubyte1_e32 v83, v71
	v_cvt_f32_ubyte2_e32 v84, v71
	v_cvt_f32_ubyte3_e32 v85, v71
	v_mul_f32_e32 v82, s34, v82
	v_mul_f32_e32 v83, s34, v83
	v_mul_f32_e32 v84, s34, v84
	v_mul_f32_e32 v85, s34, v85
	v_fma_f32 v164, v26, v82, v164
	v_fma_f32 v165, v27, v83, v165
	v_fma_f32 v166, v28, v84, v166
	v_fma_f32 v167, v29, v85, v167
	v_mfma_f32_16x16x32_bf16 v[22:25], v[212:215], v[208:211], v[22:25]
	v_cvt_f32_ubyte0_e32 v86, v72
	v_cvt_f32_ubyte1_e32 v87, v72
	v_cvt_f32_ubyte2_e32 v88, v72
	v_cvt_f32_ubyte3_e32 v89, v72
	v_mul_f32_e32 v86, s34, v86
	v_mul_f32_e32 v87, s34, v87
	v_mul_f32_e32 v88, s34, v88
	v_mul_f32_e32 v89, s34, v89
	v_fma_f32 v160, v14, v86, v160
	v_fma_f32 v161, v15, v87, v161
	v_fma_f32 v162, v16, v88, v162
	v_fma_f32 v163, v17, v89, v163
	v_mfma_f32_16x16x32_bf16 v[18:21], v[216:219], v[208:211], v[18:21]
	v_cvt_f32_ubyte0_e32 v82, v73
	v_cvt_f32_ubyte1_e32 v83, v73
	v_cvt_f32_ubyte2_e32 v84, v73
	v_cvt_f32_ubyte3_e32 v85, v73
	v_mul_f32_e32 v82, s34, v82
	v_mul_f32_e32 v83, s34, v83
	v_mul_f32_e32 v84, s34, v84
	v_mul_f32_e32 v85, s34, v85
	v_fma_f32 v156, v10, v82, v156
	v_fma_f32 v157, v11, v83, v157
	v_fma_f32 v158, v12, v84, v158
	v_fma_f32 v159, v13, v85, v159
	v_mfma_f32_16x16x32_bf16 v[62:65], v[220:223], v[208:211], v[62:65]
	v_cvt_f32_ubyte0_e32 v86, v74
	v_cvt_f32_ubyte1_e32 v87, v74
	v_cvt_f32_ubyte2_e32 v88, v74
	v_cvt_f32_ubyte3_e32 v89, v74
	v_mul_f32_e32 v86, s34, v86
	v_mul_f32_e32 v87, s34, v87
	v_mul_f32_e32 v88, s34, v88
	v_mul_f32_e32 v89, s34, v89
	v_fma_f32 v136, v34, v86, v136
	v_fma_f32 v137, v35, v87, v137
	v_fma_f32 v150, v36, v88, v150
	v_fma_f32 v151, v37, v89, v151
	v_mfma_f32_16x16x32_bf16 v[58:61], v[90:93], v[224:227], v[58:61]
	v_cvt_f32_ubyte0_e32 v82, v75
	v_cvt_f32_ubyte1_e32 v83, v75
	v_cvt_f32_ubyte2_e32 v84, v75
	v_cvt_f32_ubyte3_e32 v85, v75
	v_mul_f32_e32 v82, s34, v82
	v_mul_f32_e32 v83, s34, v83
	v_mul_f32_e32 v84, s34, v84
	v_mul_f32_e32 v85, s34, v85
	v_fma_f32 v130, v22, v82, v130
	v_fma_f32 v131, v23, v83, v131
	v_fma_f32 v134, v24, v84, v134
	v_fma_f32 v135, v25, v85, v135
	v_mfma_f32_16x16x32_bf16 v[54:57], v[212:215], v[224:227], v[54:57]
	v_cvt_f32_ubyte0_e32 v86, v76
	v_cvt_f32_ubyte1_e32 v87, v76
	v_cvt_f32_ubyte2_e32 v88, v76
	v_cvt_f32_ubyte3_e32 v89, v76
	v_mul_f32_e32 v86, s34, v86
	v_mul_f32_e32 v87, s34, v87
	v_mul_f32_e32 v88, s34, v88
	v_mul_f32_e32 v89, s34, v89
	v_fma_f32 v124, v18, v86, v124
	v_fma_f32 v125, v19, v87, v125
	v_fma_f32 v126, v20, v88, v126
	v_fma_f32 v127, v21, v89, v127
	v_mfma_f32_16x16x32_bf16 v[50:53], v[216:219], v[224:227], v[50:53]
	v_cvt_f32_ubyte0_e32 v82, v77
	v_cvt_f32_ubyte1_e32 v83, v77
	v_cvt_f32_ubyte2_e32 v84, v77
	v_cvt_f32_ubyte3_e32 v85, v77
	v_mul_f32_e32 v82, s34, v82
	v_mul_f32_e32 v83, s34, v83
	v_mul_f32_e32 v84, s34, v84
	v_mul_f32_e32 v85, s34, v85
	v_fma_f32 v120, v62, v82, v120
	v_fma_f32 v121, v63, v83, v121
	v_fma_f32 v122, v64, v84, v122
	v_fma_f32 v123, v65, v85, v123
	v_mfma_f32_16x16x32_bf16 v[2:5], v[220:223], v[224:227], v[2:5]
	v_cvt_f32_ubyte0_e32 v86, v78
	v_cvt_f32_ubyte1_e32 v87, v78
	v_cvt_f32_ubyte2_e32 v88, v78
	v_cvt_f32_ubyte3_e32 v89, v78
	v_mul_f32_e32 v86, s34, v86
	v_mul_f32_e32 v87, s34, v87
	v_mul_f32_e32 v88, s34, v88
	v_mul_f32_e32 v89, s34, v89
	v_fma_f32 v114, v58, v86, v114
	v_fma_f32 v115, v59, v87, v115
	v_fma_f32 v116, v60, v88, v116
	v_fma_f32 v117, v61, v89, v117
	s_nop 7
	s_nop 3
	v_cvt_f32_ubyte0_e32 v86, v79
	v_cvt_f32_ubyte1_e32 v87, v79
	v_cvt_f32_ubyte2_e32 v88, v79
	v_cvt_f32_ubyte3_e32 v89, v79
	v_mul_f32_e32 v86, s34, v86
	v_mul_f32_e32 v87, s34, v87
	v_mul_f32_e32 v88, s34, v88
	v_mul_f32_e32 v89, s34, v89
	v_fma_f32 v106, v54, v86, v106
	v_fma_f32 v107, v55, v87, v107
	v_fma_f32 v108, v56, v88, v108
	v_fma_f32 v109, v57, v89, v109
	v_cvt_f32_ubyte0_e32 v82, v80
	v_cvt_f32_ubyte1_e32 v83, v80
	v_cvt_f32_ubyte2_e32 v84, v80
	v_cvt_f32_ubyte3_e32 v85, v80
	v_mul_f32_e32 v82, s34, v82
	v_mul_f32_e32 v83, s34, v83
	v_mul_f32_e32 v84, s34, v84
	v_mul_f32_e32 v85, s34, v85
	v_fma_f32 v100, v50, v82, v100
	v_fma_f32 v101, v51, v83, v101
	v_fma_f32 v102, v52, v84, v102
	v_fma_f32 v103, v53, v85, v103
	v_cvt_f32_ubyte0_e32 v86, v81
	v_cvt_f32_ubyte1_e32 v87, v81
	v_cvt_f32_ubyte2_e32 v88, v81
	v_cvt_f32_ubyte3_e32 v89, v81
	v_mul_f32_e32 v86, s34, v86
	v_mul_f32_e32 v87, s34, v87
	v_mul_f32_e32 v88, s34, v88
	v_mul_f32_e32 v89, s34, v89
	v_fma_f32 v96, v2, v86, v96
	v_fma_f32 v97, v3, v87, v97
	v_fma_f32 v98, v4, v88, v98
	v_fma_f32 v99, v5, v89, v99
	s_nop 0
	global_load_dwordx4 v[66:69], v190, s[80:81] offset:128
	global_load_dwordx4 v[70:73], v191, s[80:81] offset:128
	global_load_dwordx4 v[74:77], v190, s[86:87] offset:128
	global_load_dwordx4 v[78:81], v191, s[86:87] offset:128
	global_load_dwordx4 v[82:85], v188, s[96:97] offset:128
	global_load_dwordx4 v[86:89], v188, s[98:99] offset:128
	s_waitcnt vmcnt(11)
	ds_write_b128 v206, v[228:231] offset:0
	s_waitcnt vmcnt(10)
	ds_write_b128 v206, v[232:235] offset:10240
	s_waitcnt vmcnt(9)
	ds_write_b128 v206, v[236:239] offset:20480
	s_waitcnt vmcnt(8)
	ds_write_b128 v206, v[240:243] offset:30720
	s_waitcnt vmcnt(7)
	ds_write_b128 v0, v[244:247] offset:0
	s_waitcnt vmcnt(6)
	ds_write_b128 v0, v[248:251] offset:10240
	s_waitcnt lgkmcnt(0)
	s_barrier
	global_load_dwordx4 v[228:231], v190, s[80:81] offset:256
	global_load_dwordx4 v[232:235], v191, s[80:81] offset:256
	global_load_dwordx4 v[236:239], v190, s[86:87] offset:256
	global_load_dwordx4 v[240:243], v191, s[86:87] offset:256
	global_load_dwordx4 v[244:247], v188, s[96:97] offset:256
	global_load_dwordx4 v[248:251], v188, s[98:99] offset:256
	ds_read_b128 v[90:93], v119 offset:0
	ds_read_b128 v[208:211], v205 offset:0
	ds_read_b128 v[212:215], v119 offset:2560
	ds_read_b128 v[216:219], v119 offset:5120
	ds_read_b128 v[220:223], v119 offset:7680
	s_waitcnt lgkmcnt(3)
	v_mfma_f32_16x16x32_bf16 v[6:9], v[90:93], v[208:211], 0
	s_waitcnt lgkmcnt(2)
	v_mfma_f32_16x16x32_bf16 v[30:33], v[212:215], v[208:211], 0
	s_waitcnt vmcnt(11)
	ds_write_b128 v207, v[66:69] offset:0
	s_waitcnt lgkmcnt(2)
	v_mfma_f32_16x16x32_bf16 v[38:41], v[216:219], v[208:211], 0
	s_waitcnt lgkmcnt(1)
	v_mfma_f32_16x16x32_bf16 v[42:45], v[220:223], v[208:211], 0
	ds_read_b128 v[208:211], v205 offset:2560
	s_waitcnt lgkmcnt(0)
	v_mfma_f32_16x16x32_bf16 v[46:49], v[90:93], v[208:211], 0
	v_mfma_f32_16x16x32_bf16 v[26:29], v[212:215], v[208:211], 0
	s_waitcnt vmcnt(10)
	ds_write_b128 v207, v[70:73] offset:10240
	v_mfma_f32_16x16x32_bf16 v[14:17], v[216:219], v[208:211], 0
	v_mfma_f32_16x16x32_bf16 v[10:13], v[220:223], v[208:211], 0
	ds_read_b128 v[208:211], v205 offset:5120
	s_waitcnt lgkmcnt(0)
	v_mfma_f32_16x16x32_bf16 v[34:37], v[90:93], v[208:211], 0
	v_mfma_f32_16x16x32_bf16 v[22:25], v[212:215], v[208:211], 0
	s_waitcnt vmcnt(9)
	ds_write_b128 v207, v[74:77] offset:20480
	v_mfma_f32_16x16x32_bf16 v[18:21], v[216:219], v[208:211], 0
	v_mfma_f32_16x16x32_bf16 v[62:65], v[220:223], v[208:211], 0
	ds_read_b128 v[208:211], v205 offset:7680
	s_waitcnt lgkmcnt(0)
	v_mfma_f32_16x16x32_bf16 v[58:61], v[90:93], v[208:211], 0
	ds_read_b128 v[90:93], v119 offset:64
	v_mfma_f32_16x16x32_bf16 v[54:57], v[212:215], v[208:211], 0
	s_waitcnt vmcnt(8)
	ds_write_b128 v207, v[78:81] offset:30720
	ds_read_b128 v[212:215], v119 offset:2624
	v_mfma_f32_16x16x32_bf16 v[50:53], v[216:219], v[208:211], 0
	ds_read_b128 v[216:219], v119 offset:5184
	v_mfma_f32_16x16x32_bf16 v[2:5], v[220:223], v[208:211], 0
	ds_read_b128 v[220:223], v119 offset:7744
	ds_read_b128 v[208:211], v205 offset:64
	ds_read_b128 v[224:227], v205 offset:7744
	s_waitcnt lgkmcnt(1)
	v_mfma_f32_16x16x32_bf16 v[6:9], v[90:93], v[208:211], v[6:9]
	v_mfma_f32_16x16x32_bf16 v[30:33], v[212:215], v[208:211], v[30:33]
	s_waitcnt vmcnt(7)
	ds_write_b128 v0, v[82:85] offset:20480
	v_mfma_f32_16x16x32_bf16 v[38:41], v[216:219], v[208:211], v[38:41]
	v_mfma_f32_16x16x32_bf16 v[42:45], v[220:223], v[208:211], v[42:45]
	ds_read_b128 v[208:211], v205 offset:2624
	s_waitcnt lgkmcnt(0)
	v_mfma_f32_16x16x32_bf16 v[46:49], v[90:93], v[208:211], v[46:49]
	v_mfma_f32_16x16x32_bf16 v[26:29], v[212:215], v[208:211], v[26:29]
	s_waitcnt vmcnt(6)
	ds_write_b128 v0, v[86:89] offset:30720
	v_mfma_f32_16x16x32_bf16 v[14:17], v[216:219], v[208:211], v[14:17]
	v_mfma_f32_16x16x32_bf16 v[10:13], v[220:223], v[208:211], v[10:13]
	ds_read_b128 v[208:211], v205 offset:5184
	s_waitcnt lgkmcnt(0)
	v_mfma_f32_16x16x32_bf16 v[34:37], v[90:93], v[208:211], v[34:37]
	v_mfma_f32_16x16x32_bf16 v[22:25], v[212:215], v[208:211], v[22:25]
	v_mfma_f32_16x16x32_bf16 v[18:21], v[216:219], v[208:211], v[18:21]
	v_mfma_f32_16x16x32_bf16 v[62:65], v[220:223], v[208:211], v[62:65]
	v_mfma_f32_16x16x32_bf16 v[58:61], v[90:93], v[224:227], v[58:61]
	s_waitcnt lgkmcnt(0)
	v_mfma_f32_16x16x32_bf16 v[54:57], v[212:215], v[224:227], v[54:57]
	s_barrier
	v_mfma_f32_16x16x32_bf16 v[50:53], v[216:219], v[224:227], v[50:53]
	v_mfma_f32_16x16x32_bf16 v[2:5], v[220:223], v[224:227], v[2:5]
	global_load_dwordx4 v[66:69], v190, s[80:81] offset:384
	global_load_dwordx4 v[70:73], v191, s[80:81] offset:384
	global_load_dwordx4 v[74:77], v190, s[86:87] offset:384
	global_load_dwordx4 v[78:81], v191, s[86:87] offset:384
	global_load_dwordx4 v[82:85], v188, s[96:97] offset:384
	global_load_dwordx4 v[86:89], v188, s[98:99] offset:384
	ds_read_b128 v[90:93], v119 offset:20480
	ds_read_b128 v[208:211], v205 offset:40960
	ds_read_b128 v[212:215], v119 offset:23040
	ds_read_b128 v[216:219], v119 offset:25600
	ds_read_b128 v[220:223], v119 offset:28160
	s_waitcnt lgkmcnt(3)
	v_mfma_f32_16x16x32_bf16 v[6:9], v[90:93], v[208:211], v[6:9]
	s_waitcnt lgkmcnt(2)
	v_mfma_f32_16x16x32_bf16 v[30:33], v[212:215], v[208:211], v[30:33]
	s_waitcnt vmcnt(11)
	ds_write_b128 v206, v[228:231] offset:0
	s_waitcnt lgkmcnt(2)
	v_mfma_f32_16x16x32_bf16 v[38:41], v[216:219], v[208:211], v[38:41]
	s_waitcnt lgkmcnt(1)
	v_mfma_f32_16x16x32_bf16 v[42:45], v[220:223], v[208:211], v[42:45]
	ds_read_b128 v[208:211], v205 offset:43520
	s_waitcnt lgkmcnt(0)
	v_mfma_f32_16x16x32_bf16 v[46:49], v[90:93], v[208:211], v[46:49]
	v_mfma_f32_16x16x32_bf16 v[26:29], v[212:215], v[208:211], v[26:29]
	s_waitcnt vmcnt(10)
	ds_write_b128 v206, v[232:235] offset:10240
	v_mfma_f32_16x16x32_bf16 v[14:17], v[216:219], v[208:211], v[14:17]
	v_mfma_f32_16x16x32_bf16 v[10:13], v[220:223], v[208:211], v[10:13]
	ds_read_b128 v[208:211], v205 offset:46080
	s_waitcnt lgkmcnt(0)
	v_mfma_f32_16x16x32_bf16 v[34:37], v[90:93], v[208:211], v[34:37]
	v_mfma_f32_16x16x32_bf16 v[22:25], v[212:215], v[208:211], v[22:25]
	s_waitcnt vmcnt(9)
	ds_write_b128 v206, v[236:239] offset:20480
	v_mfma_f32_16x16x32_bf16 v[18:21], v[216:219], v[208:211], v[18:21]
	v_mfma_f32_16x16x32_bf16 v[62:65], v[220:223], v[208:211], v[62:65]
	ds_read_b128 v[208:211], v205 offset:48640
	s_waitcnt lgkmcnt(0)
	v_mfma_f32_16x16x32_bf16 v[58:61], v[90:93], v[208:211], v[58:61]
	ds_read_b128 v[90:93], v119 offset:20544
	v_mfma_f32_16x16x32_bf16 v[54:57], v[212:215], v[208:211], v[54:57]
	s_waitcnt vmcnt(8)
	ds_write_b128 v206, v[240:243] offset:30720
	ds_read_b128 v[212:215], v119 offset:23104
	v_mfma_f32_16x16x32_bf16 v[50:53], v[216:219], v[208:211], v[50:53]
	ds_read_b128 v[216:219], v119 offset:25664
	v_mfma_f32_16x16x32_bf16 v[2:5], v[220:223], v[208:211], v[2:5]
	ds_read_b128 v[220:223], v119 offset:28224
	ds_read_b128 v[208:211], v205 offset:41024
	ds_read_b128 v[224:227], v205 offset:48704
	s_waitcnt lgkmcnt(1)
	v_mfma_f32_16x16x32_bf16 v[6:9], v[90:93], v[208:211], v[6:9]
	v_mfma_f32_16x16x32_bf16 v[30:33], v[212:215], v[208:211], v[30:33]
	s_waitcnt vmcnt(7)
	ds_write_b128 v0, v[244:247] offset:0
	v_mfma_f32_16x16x32_bf16 v[38:41], v[216:219], v[208:211], v[38:41]
	v_mfma_f32_16x16x32_bf16 v[42:45], v[220:223], v[208:211], v[42:45]
	ds_read_b128 v[208:211], v205 offset:43584
	s_waitcnt lgkmcnt(0)
	v_mfma_f32_16x16x32_bf16 v[46:49], v[90:93], v[208:211], v[46:49]
	v_mfma_f32_16x16x32_bf16 v[26:29], v[212:215], v[208:211], v[26:29]
	s_waitcnt vmcnt(6)
	ds_write_b128 v0, v[248:251] offset:10240
	v_mfma_f32_16x16x32_bf16 v[14:17], v[216:219], v[208:211], v[14:17]
	v_mfma_f32_16x16x32_bf16 v[10:13], v[220:223], v[208:211], v[10:13]
	ds_read_b128 v[208:211], v205 offset:46144
	s_waitcnt lgkmcnt(0)
	v_mfma_f32_16x16x32_bf16 v[34:37], v[90:93], v[208:211], v[34:37]
	v_mfma_f32_16x16x32_bf16 v[22:25], v[212:215], v[208:211], v[22:25]
	v_mfma_f32_16x16x32_bf16 v[18:21], v[216:219], v[208:211], v[18:21]
	v_mfma_f32_16x16x32_bf16 v[62:65], v[220:223], v[208:211], v[62:65]
	v_mfma_f32_16x16x32_bf16 v[58:61], v[90:93], v[224:227], v[58:61]
	s_waitcnt lgkmcnt(0)
	v_mfma_f32_16x16x32_bf16 v[54:57], v[212:215], v[224:227], v[54:57]
	s_barrier
	v_mfma_f32_16x16x32_bf16 v[50:53], v[216:219], v[224:227], v[50:53]
	v_mfma_f32_16x16x32_bf16 v[2:5], v[220:223], v[224:227], v[2:5]
	global_load_dwordx4 v[228:231], v190, s[80:81] offset:512
	global_load_dwordx4 v[232:235], v191, s[80:81] offset:512
	global_load_dwordx4 v[236:239], v190, s[86:87] offset:512
	global_load_dwordx4 v[240:243], v191, s[86:87] offset:512
	global_load_dwordx4 v[244:247], v188, s[96:97] offset:512
	global_load_dwordx4 v[248:251], v188, s[98:99] offset:512
	ds_read_b128 v[90:93], v119 offset:0
	ds_read_b128 v[208:211], v205 offset:0
	ds_read_b128 v[212:215], v119 offset:2560
	ds_read_b128 v[216:219], v119 offset:5120
	ds_read_b128 v[220:223], v119 offset:7680
	s_waitcnt lgkmcnt(3)
	v_mfma_f32_16x16x32_bf16 v[6:9], v[90:93], v[208:211], v[6:9]
	s_waitcnt lgkmcnt(2)
	v_mfma_f32_16x16x32_bf16 v[30:33], v[212:215], v[208:211], v[30:33]
	s_waitcnt vmcnt(11)
	ds_write_b128 v207, v[66:69] offset:0
	s_waitcnt lgkmcnt(2)
	v_mfma_f32_16x16x32_bf16 v[38:41], v[216:219], v[208:211], v[38:41]
	s_waitcnt lgkmcnt(1)
	v_mfma_f32_16x16x32_bf16 v[42:45], v[220:223], v[208:211], v[42:45]
	ds_read_b128 v[208:211], v205 offset:2560
	s_waitcnt lgkmcnt(0)
	v_mfma_f32_16x16x32_bf16 v[46:49], v[90:93], v[208:211], v[46:49]
	v_mfma_f32_16x16x32_bf16 v[26:29], v[212:215], v[208:211], v[26:29]
	s_waitcnt vmcnt(10)
	ds_write_b128 v207, v[70:73] offset:10240
	v_mfma_f32_16x16x32_bf16 v[14:17], v[216:219], v[208:211], v[14:17]
	v_mfma_f32_16x16x32_bf16 v[10:13], v[220:223], v[208:211], v[10:13]
	ds_read_b128 v[208:211], v205 offset:5120
	s_waitcnt lgkmcnt(0)
	v_mfma_f32_16x16x32_bf16 v[34:37], v[90:93], v[208:211], v[34:37]
	v_mfma_f32_16x16x32_bf16 v[22:25], v[212:215], v[208:211], v[22:25]
	s_waitcnt vmcnt(9)
	ds_write_b128 v207, v[74:77] offset:20480
	v_mfma_f32_16x16x32_bf16 v[18:21], v[216:219], v[208:211], v[18:21]
	v_mfma_f32_16x16x32_bf16 v[62:65], v[220:223], v[208:211], v[62:65]
	ds_read_b128 v[208:211], v205 offset:7680
	s_waitcnt lgkmcnt(0)
	v_mfma_f32_16x16x32_bf16 v[58:61], v[90:93], v[208:211], v[58:61]
	ds_read_b128 v[90:93], v119 offset:64
	v_mfma_f32_16x16x32_bf16 v[54:57], v[212:215], v[208:211], v[54:57]
	s_waitcnt vmcnt(8)
	ds_write_b128 v207, v[78:81] offset:30720
	ds_read_b128 v[212:215], v119 offset:2624
	v_mfma_f32_16x16x32_bf16 v[50:53], v[216:219], v[208:211], v[50:53]
	ds_read_b128 v[216:219], v119 offset:5184
	v_mfma_f32_16x16x32_bf16 v[2:5], v[220:223], v[208:211], v[2:5]
	ds_read_b128 v[220:223], v119 offset:7744
	ds_read_b128 v[208:211], v205 offset:64
	ds_read_b128 v[224:227], v205 offset:7744
	s_waitcnt lgkmcnt(1)
	v_mfma_f32_16x16x32_bf16 v[6:9], v[90:93], v[208:211], v[6:9]
	v_mfma_f32_16x16x32_bf16 v[30:33], v[212:215], v[208:211], v[30:33]
	s_waitcnt vmcnt(7)
	ds_write_b128 v0, v[82:85] offset:20480
	v_mfma_f32_16x16x32_bf16 v[38:41], v[216:219], v[208:211], v[38:41]
	v_mfma_f32_16x16x32_bf16 v[42:45], v[220:223], v[208:211], v[42:45]
	ds_read_b128 v[208:211], v205 offset:2624
	s_waitcnt lgkmcnt(0)
	v_mfma_f32_16x16x32_bf16 v[46:49], v[90:93], v[208:211], v[46:49]
	v_mfma_f32_16x16x32_bf16 v[26:29], v[212:215], v[208:211], v[26:29]
	s_waitcnt vmcnt(6)
	ds_write_b128 v0, v[86:89] offset:30720
	v_mfma_f32_16x16x32_bf16 v[14:17], v[216:219], v[208:211], v[14:17]
	v_mfma_f32_16x16x32_bf16 v[10:13], v[220:223], v[208:211], v[10:13]
	ds_read_b128 v[208:211], v205 offset:5184
	s_waitcnt lgkmcnt(0)
	v_mfma_f32_16x16x32_bf16 v[34:37], v[90:93], v[208:211], v[34:37]
	v_mfma_f32_16x16x32_bf16 v[22:25], v[212:215], v[208:211], v[22:25]
	v_mfma_f32_16x16x32_bf16 v[18:21], v[216:219], v[208:211], v[18:21]
	v_mfma_f32_16x16x32_bf16 v[62:65], v[220:223], v[208:211], v[62:65]
	v_mfma_f32_16x16x32_bf16 v[58:61], v[90:93], v[224:227], v[58:61]
	s_waitcnt lgkmcnt(0)
	v_mfma_f32_16x16x32_bf16 v[54:57], v[212:215], v[224:227], v[54:57]
	s_barrier
	v_mfma_f32_16x16x32_bf16 v[50:53], v[216:219], v[224:227], v[50:53]
	v_mfma_f32_16x16x32_bf16 v[2:5], v[220:223], v[224:227], v[2:5]
	global_load_dwordx4 v[66:69], v190, s[80:81] offset:640
	global_load_dwordx4 v[70:73], v191, s[80:81] offset:640
	global_load_dwordx4 v[74:77], v190, s[86:87] offset:640
	global_load_dwordx4 v[78:81], v191, s[86:87] offset:640
	global_load_dwordx4 v[82:85], v188, s[96:97] offset:640
	global_load_dwordx4 v[86:89], v188, s[98:99] offset:640
	ds_read_b128 v[90:93], v119 offset:20480
	ds_read_b128 v[208:211], v205 offset:40960
	ds_read_b128 v[212:215], v119 offset:23040
	ds_read_b128 v[216:219], v119 offset:25600
	ds_read_b128 v[220:223], v119 offset:28160
	s_waitcnt lgkmcnt(3)
	v_mfma_f32_16x16x32_bf16 v[6:9], v[90:93], v[208:211], v[6:9]
	s_waitcnt lgkmcnt(2)
	v_mfma_f32_16x16x32_bf16 v[30:33], v[212:215], v[208:211], v[30:33]
	s_waitcnt vmcnt(11)
	ds_write_b128 v206, v[228:231] offset:0
	s_waitcnt lgkmcnt(2)
	v_mfma_f32_16x16x32_bf16 v[38:41], v[216:219], v[208:211], v[38:41]
	s_waitcnt lgkmcnt(1)
	v_mfma_f32_16x16x32_bf16 v[42:45], v[220:223], v[208:211], v[42:45]
	ds_read_b128 v[208:211], v205 offset:43520
	s_waitcnt lgkmcnt(0)
	v_mfma_f32_16x16x32_bf16 v[46:49], v[90:93], v[208:211], v[46:49]
	v_mfma_f32_16x16x32_bf16 v[26:29], v[212:215], v[208:211], v[26:29]
	s_waitcnt vmcnt(10)
	ds_write_b128 v206, v[232:235] offset:10240
	v_mfma_f32_16x16x32_bf16 v[14:17], v[216:219], v[208:211], v[14:17]
	v_mfma_f32_16x16x32_bf16 v[10:13], v[220:223], v[208:211], v[10:13]
	ds_read_b128 v[208:211], v205 offset:46080
	s_waitcnt lgkmcnt(0)
	v_mfma_f32_16x16x32_bf16 v[34:37], v[90:93], v[208:211], v[34:37]
	v_mfma_f32_16x16x32_bf16 v[22:25], v[212:215], v[208:211], v[22:25]
	s_waitcnt vmcnt(9)
	ds_write_b128 v206, v[236:239] offset:20480
	v_mfma_f32_16x16x32_bf16 v[18:21], v[216:219], v[208:211], v[18:21]
	v_mfma_f32_16x16x32_bf16 v[62:65], v[220:223], v[208:211], v[62:65]
	ds_read_b128 v[208:211], v205 offset:48640
	s_waitcnt lgkmcnt(0)
	v_mfma_f32_16x16x32_bf16 v[58:61], v[90:93], v[208:211], v[58:61]
	ds_read_b128 v[90:93], v119 offset:20544
	v_mfma_f32_16x16x32_bf16 v[54:57], v[212:215], v[208:211], v[54:57]
	s_waitcnt vmcnt(8)
	ds_write_b128 v206, v[240:243] offset:30720
	ds_read_b128 v[212:215], v119 offset:23104
	v_mfma_f32_16x16x32_bf16 v[50:53], v[216:219], v[208:211], v[50:53]
	ds_read_b128 v[216:219], v119 offset:25664
	v_mfma_f32_16x16x32_bf16 v[2:5], v[220:223], v[208:211], v[2:5]
	ds_read_b128 v[220:223], v119 offset:28224
	ds_read_b128 v[208:211], v205 offset:41024
	ds_read_b128 v[224:227], v205 offset:48704
	s_waitcnt lgkmcnt(1)
	v_mfma_f32_16x16x32_bf16 v[6:9], v[90:93], v[208:211], v[6:9]
	v_mfma_f32_16x16x32_bf16 v[30:33], v[212:215], v[208:211], v[30:33]
	s_waitcnt vmcnt(7)
	ds_write_b128 v0, v[244:247] offset:0
	v_mfma_f32_16x16x32_bf16 v[38:41], v[216:219], v[208:211], v[38:41]
	v_mfma_f32_16x16x32_bf16 v[42:45], v[220:223], v[208:211], v[42:45]
	ds_read_b128 v[208:211], v205 offset:43584
	s_waitcnt lgkmcnt(0)
	v_mfma_f32_16x16x32_bf16 v[46:49], v[90:93], v[208:211], v[46:49]
	v_mfma_f32_16x16x32_bf16 v[26:29], v[212:215], v[208:211], v[26:29]
	s_waitcnt vmcnt(6)
	ds_write_b128 v0, v[248:251] offset:10240
	v_mfma_f32_16x16x32_bf16 v[14:17], v[216:219], v[208:211], v[14:17]
	v_mfma_f32_16x16x32_bf16 v[10:13], v[220:223], v[208:211], v[10:13]
	ds_read_b128 v[208:211], v205 offset:46144
	s_waitcnt lgkmcnt(0)
	v_mfma_f32_16x16x32_bf16 v[34:37], v[90:93], v[208:211], v[34:37]
	v_mfma_f32_16x16x32_bf16 v[22:25], v[212:215], v[208:211], v[22:25]
	v_mfma_f32_16x16x32_bf16 v[18:21], v[216:219], v[208:211], v[18:21]
	v_mfma_f32_16x16x32_bf16 v[62:65], v[220:223], v[208:211], v[62:65]
	v_mfma_f32_16x16x32_bf16 v[58:61], v[90:93], v[224:227], v[58:61]
	s_waitcnt lgkmcnt(0)
	v_mfma_f32_16x16x32_bf16 v[54:57], v[212:215], v[224:227], v[54:57]
	s_barrier
	v_mfma_f32_16x16x32_bf16 v[50:53], v[216:219], v[224:227], v[50:53]
	v_mfma_f32_16x16x32_bf16 v[2:5], v[220:223], v[224:227], v[2:5]
	global_load_dwordx4 v[228:231], v190, s[80:81] offset:768
	global_load_dwordx4 v[232:235], v191, s[80:81] offset:768
	global_load_dwordx4 v[236:239], v190, s[86:87] offset:768
	global_load_dwordx4 v[240:243], v191, s[86:87] offset:768
	global_load_dwordx4 v[244:247], v188, s[96:97] offset:768
	global_load_dwordx4 v[248:251], v188, s[98:99] offset:768
	ds_read_b128 v[90:93], v119 offset:0
	ds_read_b128 v[208:211], v205 offset:0
	ds_read_b128 v[212:215], v119 offset:2560
	ds_read_b128 v[216:219], v119 offset:5120
	ds_read_b128 v[220:223], v119 offset:7680
	s_waitcnt lgkmcnt(3)
	v_mfma_f32_16x16x32_bf16 v[6:9], v[90:93], v[208:211], v[6:9]
	s_waitcnt lgkmcnt(2)
	v_mfma_f32_16x16x32_bf16 v[30:33], v[212:215], v[208:211], v[30:33]
	s_waitcnt vmcnt(11)
	ds_write_b128 v207, v[66:69] offset:0
	s_waitcnt lgkmcnt(2)
	v_mfma_f32_16x16x32_bf16 v[38:41], v[216:219], v[208:211], v[38:41]
	s_waitcnt lgkmcnt(1)
	v_mfma_f32_16x16x32_bf16 v[42:45], v[220:223], v[208:211], v[42:45]
	ds_read_b128 v[208:211], v205 offset:2560
	s_waitcnt lgkmcnt(0)
	v_mfma_f32_16x16x32_bf16 v[46:49], v[90:93], v[208:211], v[46:49]
	v_mfma_f32_16x16x32_bf16 v[26:29], v[212:215], v[208:211], v[26:29]
	s_waitcnt vmcnt(10)
	ds_write_b128 v207, v[70:73] offset:10240
	v_mfma_f32_16x16x32_bf16 v[14:17], v[216:219], v[208:211], v[14:17]
	v_mfma_f32_16x16x32_bf16 v[10:13], v[220:223], v[208:211], v[10:13]
	ds_read_b128 v[208:211], v205 offset:5120
	s_waitcnt lgkmcnt(0)
	v_mfma_f32_16x16x32_bf16 v[34:37], v[90:93], v[208:211], v[34:37]
	v_mfma_f32_16x16x32_bf16 v[22:25], v[212:215], v[208:211], v[22:25]
	s_waitcnt vmcnt(9)
	ds_write_b128 v207, v[74:77] offset:20480
	v_mfma_f32_16x16x32_bf16 v[18:21], v[216:219], v[208:211], v[18:21]
	v_mfma_f32_16x16x32_bf16 v[62:65], v[220:223], v[208:211], v[62:65]
	ds_read_b128 v[208:211], v205 offset:7680
	s_waitcnt lgkmcnt(0)
	v_mfma_f32_16x16x32_bf16 v[58:61], v[90:93], v[208:211], v[58:61]
	ds_read_b128 v[90:93], v119 offset:64
	v_mfma_f32_16x16x32_bf16 v[54:57], v[212:215], v[208:211], v[54:57]
	s_waitcnt vmcnt(8)
	ds_write_b128 v207, v[78:81] offset:30720
	ds_read_b128 v[212:215], v119 offset:2624
	v_mfma_f32_16x16x32_bf16 v[50:53], v[216:219], v[208:211], v[50:53]
	ds_read_b128 v[216:219], v119 offset:5184
	v_mfma_f32_16x16x32_bf16 v[2:5], v[220:223], v[208:211], v[2:5]
	ds_read_b128 v[220:223], v119 offset:7744
	ds_read_b128 v[208:211], v205 offset:64
	ds_read_b128 v[224:227], v205 offset:7744
	s_waitcnt lgkmcnt(1)
	v_mfma_f32_16x16x32_bf16 v[6:9], v[90:93], v[208:211], v[6:9]
	v_mfma_f32_16x16x32_bf16 v[30:33], v[212:215], v[208:211], v[30:33]
	s_waitcnt vmcnt(7)
	ds_write_b128 v0, v[82:85] offset:20480
	v_mfma_f32_16x16x32_bf16 v[38:41], v[216:219], v[208:211], v[38:41]
	v_mfma_f32_16x16x32_bf16 v[42:45], v[220:223], v[208:211], v[42:45]
	ds_read_b128 v[208:211], v205 offset:2624
	s_waitcnt lgkmcnt(0)
	v_mfma_f32_16x16x32_bf16 v[46:49], v[90:93], v[208:211], v[46:49]
	v_mfma_f32_16x16x32_bf16 v[26:29], v[212:215], v[208:211], v[26:29]
	s_waitcnt vmcnt(6)
	ds_write_b128 v0, v[86:89] offset:30720
	v_mfma_f32_16x16x32_bf16 v[14:17], v[216:219], v[208:211], v[14:17]
	v_mfma_f32_16x16x32_bf16 v[10:13], v[220:223], v[208:211], v[10:13]
	ds_read_b128 v[208:211], v205 offset:5184
	s_waitcnt lgkmcnt(0)
	v_mfma_f32_16x16x32_bf16 v[34:37], v[90:93], v[208:211], v[34:37]
	v_mfma_f32_16x16x32_bf16 v[22:25], v[212:215], v[208:211], v[22:25]
	v_mfma_f32_16x16x32_bf16 v[18:21], v[216:219], v[208:211], v[18:21]
	v_mfma_f32_16x16x32_bf16 v[62:65], v[220:223], v[208:211], v[62:65]
	v_mfma_f32_16x16x32_bf16 v[58:61], v[90:93], v[224:227], v[58:61]
	s_waitcnt lgkmcnt(0)
	v_mfma_f32_16x16x32_bf16 v[54:57], v[212:215], v[224:227], v[54:57]
	s_barrier
	v_mfma_f32_16x16x32_bf16 v[50:53], v[216:219], v[224:227], v[50:53]
	v_mfma_f32_16x16x32_bf16 v[2:5], v[220:223], v[224:227], v[2:5]
	global_load_dwordx4 v[66:69], v190, s[80:81] offset:896
	global_load_dwordx4 v[70:73], v191, s[80:81] offset:896
	global_load_dwordx4 v[74:77], v190, s[86:87] offset:896
	global_load_dwordx4 v[78:81], v191, s[86:87] offset:896
	global_load_dwordx4 v[82:85], v188, s[96:97] offset:896
	global_load_dwordx4 v[86:89], v188, s[98:99] offset:896
	ds_read_b128 v[90:93], v119 offset:20480
	ds_read_b128 v[208:211], v205 offset:40960
	ds_read_b128 v[212:215], v119 offset:23040
	ds_read_b128 v[216:219], v119 offset:25600
	ds_read_b128 v[220:223], v119 offset:28160
	s_waitcnt lgkmcnt(3)
	v_mfma_f32_16x16x32_bf16 v[6:9], v[90:93], v[208:211], v[6:9]
	s_waitcnt lgkmcnt(2)
	v_mfma_f32_16x16x32_bf16 v[30:33], v[212:215], v[208:211], v[30:33]
	s_waitcnt vmcnt(11)
	ds_write_b128 v206, v[228:231] offset:0
	s_waitcnt lgkmcnt(2)
	v_mfma_f32_16x16x32_bf16 v[38:41], v[216:219], v[208:211], v[38:41]
	s_waitcnt lgkmcnt(1)
	v_mfma_f32_16x16x32_bf16 v[42:45], v[220:223], v[208:211], v[42:45]
	ds_read_b128 v[208:211], v205 offset:43520
	s_waitcnt lgkmcnt(0)
	v_mfma_f32_16x16x32_bf16 v[46:49], v[90:93], v[208:211], v[46:49]
	v_mfma_f32_16x16x32_bf16 v[26:29], v[212:215], v[208:211], v[26:29]
	s_waitcnt vmcnt(10)
	ds_write_b128 v206, v[232:235] offset:10240
	v_mfma_f32_16x16x32_bf16 v[14:17], v[216:219], v[208:211], v[14:17]
	v_mfma_f32_16x16x32_bf16 v[10:13], v[220:223], v[208:211], v[10:13]
	ds_read_b128 v[208:211], v205 offset:46080
	s_waitcnt lgkmcnt(0)
	v_mfma_f32_16x16x32_bf16 v[34:37], v[90:93], v[208:211], v[34:37]
	v_mfma_f32_16x16x32_bf16 v[22:25], v[212:215], v[208:211], v[22:25]
	s_waitcnt vmcnt(9)
	ds_write_b128 v206, v[236:239] offset:20480
	v_mfma_f32_16x16x32_bf16 v[18:21], v[216:219], v[208:211], v[18:21]
	v_mfma_f32_16x16x32_bf16 v[62:65], v[220:223], v[208:211], v[62:65]
	ds_read_b128 v[208:211], v205 offset:48640
	s_waitcnt lgkmcnt(0)
	v_mfma_f32_16x16x32_bf16 v[58:61], v[90:93], v[208:211], v[58:61]
	ds_read_b128 v[90:93], v119 offset:20544
	v_mfma_f32_16x16x32_bf16 v[54:57], v[212:215], v[208:211], v[54:57]
	s_waitcnt vmcnt(8)
	ds_write_b128 v206, v[240:243] offset:30720
	ds_read_b128 v[212:215], v119 offset:23104
	v_mfma_f32_16x16x32_bf16 v[50:53], v[216:219], v[208:211], v[50:53]
	ds_read_b128 v[216:219], v119 offset:25664
	v_mfma_f32_16x16x32_bf16 v[2:5], v[220:223], v[208:211], v[2:5]
	ds_read_b128 v[220:223], v119 offset:28224
	ds_read_b128 v[208:211], v205 offset:41024
	ds_read_b128 v[224:227], v205 offset:48704
	s_waitcnt lgkmcnt(1)
	v_mfma_f32_16x16x32_bf16 v[6:9], v[90:93], v[208:211], v[6:9]
	v_mfma_f32_16x16x32_bf16 v[30:33], v[212:215], v[208:211], v[30:33]
	s_waitcnt vmcnt(7)
	ds_write_b128 v0, v[244:247] offset:0
	v_mfma_f32_16x16x32_bf16 v[38:41], v[216:219], v[208:211], v[38:41]
	v_mfma_f32_16x16x32_bf16 v[42:45], v[220:223], v[208:211], v[42:45]
	ds_read_b128 v[208:211], v205 offset:43584
	s_waitcnt lgkmcnt(0)
	v_mfma_f32_16x16x32_bf16 v[46:49], v[90:93], v[208:211], v[46:49]
	v_mfma_f32_16x16x32_bf16 v[26:29], v[212:215], v[208:211], v[26:29]
	s_waitcnt vmcnt(6)
	ds_write_b128 v0, v[248:251] offset:10240
	s_movk_i32 s10, 0xc00
	s_mov_b32 s11, 0
	v_lshl_add_u64 v[244:245], v[128:129], 0, s[10:11]
	v_lshl_add_u64 v[246:247], v[132:133], 0, s[10:11]
	v_lshl_add_u64 v[248:249], v[152:153], 0, s[10:11]
	v_lshl_add_u64 v[250:251], v[154:155], 0, s[10:11]
	global_load_dwordx2 v[228:229], v[244:245], off
	global_load_dwordx2 v[230:231], v[244:245], off offset:32
	global_load_dwordx2 v[232:233], v[246:247], off
	global_load_dwordx2 v[234:235], v[246:247], off offset:32
	global_load_dwordx2 v[236:237], v[248:249], off
	global_load_dwordx2 v[238:239], v[248:249], off offset:32
	global_load_dwordx2 v[240:241], v[250:251], off
	global_load_dwordx2 v[242:243], v[250:251], off offset:32
	v_mfma_f32_16x16x32_bf16 v[14:17], v[216:219], v[208:211], v[14:17]
	v_mfma_f32_16x16x32_bf16 v[10:13], v[220:223], v[208:211], v[10:13]
	ds_read_b128 v[208:211], v205 offset:46144
	s_waitcnt lgkmcnt(0)
	v_mfma_f32_16x16x32_bf16 v[34:37], v[90:93], v[208:211], v[34:37]
	v_mfma_f32_16x16x32_bf16 v[22:25], v[212:215], v[208:211], v[22:25]
	v_mfma_f32_16x16x32_bf16 v[18:21], v[216:219], v[208:211], v[18:21]
	v_mfma_f32_16x16x32_bf16 v[62:65], v[220:223], v[208:211], v[62:65]
	v_mfma_f32_16x16x32_bf16 v[58:61], v[90:93], v[224:227], v[58:61]
	s_waitcnt lgkmcnt(0)
	v_mfma_f32_16x16x32_bf16 v[54:57], v[212:215], v[224:227], v[54:57]
	s_barrier
	v_mfma_f32_16x16x32_bf16 v[50:53], v[216:219], v[224:227], v[50:53]
	v_mfma_f32_16x16x32_bf16 v[2:5], v[220:223], v[224:227], v[2:5]
	ds_read_b128 v[90:93], v119 offset:0
	ds_read_b128 v[208:211], v205 offset:0
	ds_read_b128 v[212:215], v119 offset:2560
	ds_read_b128 v[216:219], v119 offset:5120
	ds_read_b128 v[220:223], v119 offset:7680
	s_waitcnt lgkmcnt(3)
	v_mfma_f32_16x16x32_bf16 v[6:9], v[90:93], v[208:211], v[6:9]
	s_waitcnt lgkmcnt(2)
	v_mfma_f32_16x16x32_bf16 v[30:33], v[212:215], v[208:211], v[30:33]
	s_waitcnt vmcnt(13)
	ds_write_b128 v207, v[66:69] offset:0
	s_waitcnt lgkmcnt(2)
	v_mfma_f32_16x16x32_bf16 v[38:41], v[216:219], v[208:211], v[38:41]
	s_waitcnt lgkmcnt(1)
	v_mfma_f32_16x16x32_bf16 v[42:45], v[220:223], v[208:211], v[42:45]
	ds_read_b128 v[208:211], v205 offset:2560
	s_waitcnt lgkmcnt(0)
	v_mfma_f32_16x16x32_bf16 v[46:49], v[90:93], v[208:211], v[46:49]
	v_mfma_f32_16x16x32_bf16 v[26:29], v[212:215], v[208:211], v[26:29]
	s_waitcnt vmcnt(12)
	ds_write_b128 v207, v[70:73] offset:10240
	v_mfma_f32_16x16x32_bf16 v[14:17], v[216:219], v[208:211], v[14:17]
	v_mfma_f32_16x16x32_bf16 v[10:13], v[220:223], v[208:211], v[10:13]
	ds_read_b128 v[208:211], v205 offset:5120
	s_waitcnt lgkmcnt(0)
	v_mfma_f32_16x16x32_bf16 v[34:37], v[90:93], v[208:211], v[34:37]
	v_mfma_f32_16x16x32_bf16 v[22:25], v[212:215], v[208:211], v[22:25]
	s_waitcnt vmcnt(11)
	ds_write_b128 v207, v[74:77] offset:20480
	v_mfma_f32_16x16x32_bf16 v[18:21], v[216:219], v[208:211], v[18:21]
	v_mfma_f32_16x16x32_bf16 v[62:65], v[220:223], v[208:211], v[62:65]
	ds_read_b128 v[208:211], v205 offset:7680
	s_waitcnt lgkmcnt(0)
	v_mfma_f32_16x16x32_bf16 v[58:61], v[90:93], v[208:211], v[58:61]
	ds_read_b128 v[90:93], v119 offset:64
	v_mfma_f32_16x16x32_bf16 v[54:57], v[212:215], v[208:211], v[54:57]
	s_waitcnt vmcnt(10)
	ds_write_b128 v207, v[78:81] offset:30720
	ds_read_b128 v[212:215], v119 offset:2624
	v_mfma_f32_16x16x32_bf16 v[50:53], v[216:219], v[208:211], v[50:53]
	ds_read_b128 v[216:219], v119 offset:5184
	v_mfma_f32_16x16x32_bf16 v[2:5], v[220:223], v[208:211], v[2:5]
	ds_read_b128 v[220:223], v119 offset:7744
	ds_read_b128 v[208:211], v205 offset:64
	ds_read_b128 v[224:227], v205 offset:7744
	s_waitcnt lgkmcnt(1)
	v_mfma_f32_16x16x32_bf16 v[6:9], v[90:93], v[208:211], v[6:9]
	v_mfma_f32_16x16x32_bf16 v[30:33], v[212:215], v[208:211], v[30:33]
	s_waitcnt vmcnt(9)
	ds_write_b128 v0, v[82:85] offset:20480
	v_mfma_f32_16x16x32_bf16 v[38:41], v[216:219], v[208:211], v[38:41]
	v_mfma_f32_16x16x32_bf16 v[42:45], v[220:223], v[208:211], v[42:45]
	ds_read_b128 v[208:211], v205 offset:2624
	s_waitcnt lgkmcnt(0)
	v_mfma_f32_16x16x32_bf16 v[46:49], v[90:93], v[208:211], v[46:49]
	v_mfma_f32_16x16x32_bf16 v[26:29], v[212:215], v[208:211], v[26:29]
	s_waitcnt vmcnt(8)
	ds_write_b128 v0, v[86:89] offset:30720
	v_mfma_f32_16x16x32_bf16 v[14:17], v[216:219], v[208:211], v[14:17]
	v_mfma_f32_16x16x32_bf16 v[10:13], v[220:223], v[208:211], v[10:13]
	ds_read_b128 v[208:211], v205 offset:5184
	s_waitcnt lgkmcnt(0)
	v_mfma_f32_16x16x32_bf16 v[34:37], v[90:93], v[208:211], v[34:37]
	v_mfma_f32_16x16x32_bf16 v[22:25], v[212:215], v[208:211], v[22:25]
	v_mfma_f32_16x16x32_bf16 v[18:21], v[216:219], v[208:211], v[18:21]
	v_mfma_f32_16x16x32_bf16 v[62:65], v[220:223], v[208:211], v[62:65]
	v_mfma_f32_16x16x32_bf16 v[58:61], v[90:93], v[224:227], v[58:61]
	s_waitcnt lgkmcnt(0)
	v_mfma_f32_16x16x32_bf16 v[54:57], v[212:215], v[224:227], v[54:57]
	s_barrier
	v_mfma_f32_16x16x32_bf16 v[50:53], v[216:219], v[224:227], v[50:53]
	v_mfma_f32_16x16x32_bf16 v[2:5], v[220:223], v[224:227], v[2:5]
	ds_read_b128 v[90:93], v119 offset:20480
	ds_read_b128 v[208:211], v205 offset:40960
	ds_read_b128 v[212:215], v119 offset:23040
	ds_read_b128 v[216:219], v119 offset:25600
	ds_read_b128 v[220:223], v119 offset:28160
	s_waitcnt lgkmcnt(3)
	v_mfma_f32_16x16x32_bf16 v[6:9], v[90:93], v[208:211], v[6:9]
	s_waitcnt lgkmcnt(2)
	v_mfma_f32_16x16x32_bf16 v[30:33], v[212:215], v[208:211], v[30:33]
	s_waitcnt lgkmcnt(1)
	v_mfma_f32_16x16x32_bf16 v[38:41], v[216:219], v[208:211], v[38:41]
	s_waitcnt lgkmcnt(0)
	v_mfma_f32_16x16x32_bf16 v[42:45], v[220:223], v[208:211], v[42:45]
	ds_read_b128 v[208:211], v205 offset:43520
	s_waitcnt lgkmcnt(0)
	v_mfma_f32_16x16x32_bf16 v[46:49], v[90:93], v[208:211], v[46:49]
	v_mfma_f32_16x16x32_bf16 v[26:29], v[212:215], v[208:211], v[26:29]
	v_mfma_f32_16x16x32_bf16 v[14:17], v[216:219], v[208:211], v[14:17]
	v_mfma_f32_16x16x32_bf16 v[10:13], v[220:223], v[208:211], v[10:13]
	ds_read_b128 v[208:211], v205 offset:46080
	s_waitcnt lgkmcnt(0)
	v_mfma_f32_16x16x32_bf16 v[34:37], v[90:93], v[208:211], v[34:37]
	v_mfma_f32_16x16x32_bf16 v[22:25], v[212:215], v[208:211], v[22:25]
	v_mfma_f32_16x16x32_bf16 v[18:21], v[216:219], v[208:211], v[18:21]
	v_mfma_f32_16x16x32_bf16 v[62:65], v[220:223], v[208:211], v[62:65]
	ds_read_b128 v[208:211], v205 offset:48640
	s_waitcnt lgkmcnt(0)
	v_mfma_f32_16x16x32_bf16 v[58:61], v[90:93], v[208:211], v[58:61]
	ds_read_b128 v[90:93], v119 offset:20544
	v_mfma_f32_16x16x32_bf16 v[54:57], v[212:215], v[208:211], v[54:57]
	ds_read_b128 v[212:215], v119 offset:23104
	v_mfma_f32_16x16x32_bf16 v[50:53], v[216:219], v[208:211], v[50:53]
	ds_read_b128 v[216:219], v119 offset:25664
	v_mfma_f32_16x16x32_bf16 v[2:5], v[220:223], v[208:211], v[2:5]
	ds_read_b128 v[220:223], v119 offset:28224
	ds_read_b128 v[208:211], v205 offset:41024
	ds_read_b128 v[224:227], v205 offset:48704
	s_waitcnt lgkmcnt(1)
	v_mfma_f32_16x16x32_bf16 v[6:9], v[90:93], v[208:211], v[6:9]
	s_waitcnt vmcnt(0)
	v_mfma_f32_16x16x32_bf16 v[30:33], v[212:215], v[208:211], v[30:33]
	v_mfma_f32_16x16x32_bf16 v[38:41], v[216:219], v[208:211], v[38:41]
	v_mfma_f32_16x16x32_bf16 v[42:45], v[220:223], v[208:211], v[42:45]
	v_cvt_f32_ubyte0_e32 v248, v228
	v_cvt_f32_ubyte1_e32 v249, v228
	v_cvt_f32_ubyte2_e32 v250, v228
	v_cvt_f32_ubyte3_e32 v251, v228
	v_mul_f32_e32 v248, s34, v248
	v_mul_f32_e32 v249, s34, v249
	v_mul_f32_e32 v250, s34, v250
	v_mul_f32_e32 v251, s34, v251
	v_fma_f32 v184, v6, v248, v184
	v_fma_f32 v185, v7, v249, v185
	v_fma_f32 v186, v8, v250, v186
	v_fma_f32 v187, v9, v251, v187
	ds_read_b128 v[208:211], v205 offset:43584
	s_waitcnt lgkmcnt(0)
	v_mfma_f32_16x16x32_bf16 v[46:49], v[90:93], v[208:211], v[46:49]
	v_cvt_f32_ubyte0_e32 v244, v229
	v_cvt_f32_ubyte1_e32 v245, v229
	v_cvt_f32_ubyte2_e32 v246, v229
	v_cvt_f32_ubyte3_e32 v247, v229
	v_mul_f32_e32 v244, s34, v244
	v_mul_f32_e32 v245, s34, v245
	v_mul_f32_e32 v246, s34, v246
	v_mul_f32_e32 v247, s34, v247
	v_fma_f32 v180, v30, v244, v180
	v_fma_f32 v181, v31, v245, v181
	v_fma_f32 v182, v32, v246, v182
	v_fma_f32 v183, v33, v247, v183
	v_mfma_f32_16x16x32_bf16 v[26:29], v[212:215], v[208:211], v[26:29]
	v_cvt_f32_ubyte0_e32 v248, v230
	v_cvt_f32_ubyte1_e32 v249, v230
	v_cvt_f32_ubyte2_e32 v250, v230
	v_cvt_f32_ubyte3_e32 v251, v230
	v_mul_f32_e32 v248, s34, v248
	v_mul_f32_e32 v249, s34, v249
	v_mul_f32_e32 v250, s34, v250
	v_mul_f32_e32 v251, s34, v251
	v_fma_f32 v176, v38, v248, v176
	v_fma_f32 v177, v39, v249, v177
	v_fma_f32 v178, v40, v250, v178
	v_fma_f32 v179, v41, v251, v179
	v_mfma_f32_16x16x32_bf16 v[14:17], v[216:219], v[208:211], v[14:17]
	v_cvt_f32_ubyte0_e32 v244, v231
	v_cvt_f32_ubyte1_e32 v245, v231
	v_cvt_f32_ubyte2_e32 v246, v231
	v_cvt_f32_ubyte3_e32 v247, v231
	v_mul_f32_e32 v244, s34, v244
	v_mul_f32_e32 v245, s34, v245
	v_mul_f32_e32 v246, s34, v246
	v_mul_f32_e32 v247, s34, v247
	v_fma_f32 v172, v42, v244, v172
	v_fma_f32 v173, v43, v245, v173
	v_fma_f32 v174, v44, v246, v174
	v_fma_f32 v175, v45, v247, v175
	v_mfma_f32_16x16x32_bf16 v[10:13], v[220:223], v[208:211], v[10:13]
	v_cvt_f32_ubyte0_e32 v248, v232
	v_cvt_f32_ubyte1_e32 v249, v232
	v_cvt_f32_ubyte2_e32 v250, v232
	v_cvt_f32_ubyte3_e32 v251, v232
	v_mul_f32_e32 v248, s34, v248
	v_mul_f32_e32 v249, s34, v249
	v_mul_f32_e32 v250, s34, v250
	v_mul_f32_e32 v251, s34, v251
	v_fma_f32 v168, v46, v248, v168
	v_fma_f32 v169, v47, v249, v169
	v_fma_f32 v170, v48, v250, v170
	v_fma_f32 v171, v49, v251, v171
	ds_read_b128 v[208:211], v205 offset:46144
	s_waitcnt lgkmcnt(0)
	v_mfma_f32_16x16x32_bf16 v[34:37], v[90:93], v[208:211], v[34:37]
	v_cvt_f32_ubyte0_e32 v244, v233
	v_cvt_f32_ubyte1_e32 v245, v233
	v_cvt_f32_ubyte2_e32 v246, v233
	v_cvt_f32_ubyte3_e32 v247, v233
	v_mul_f32_e32 v244, s34, v244
	v_mul_f32_e32 v245, s34, v245
	v_mul_f32_e32 v246, s34, v246
	v_mul_f32_e32 v247, s34, v247
	v_fma_f32 v164, v26, v244, v164
	v_fma_f32 v165, v27, v245, v165
	v_fma_f32 v166, v28, v246, v166
	v_fma_f32 v167, v29, v247, v167
	v_mfma_f32_16x16x32_bf16 v[22:25], v[212:215], v[208:211], v[22:25]
	v_cvt_f32_ubyte0_e32 v248, v234
	v_cvt_f32_ubyte1_e32 v249, v234
	v_cvt_f32_ubyte2_e32 v250, v234
	v_cvt_f32_ubyte3_e32 v251, v234
	v_mul_f32_e32 v248, s34, v248
	v_mul_f32_e32 v249, s34, v249
	v_mul_f32_e32 v250, s34, v250
	v_mul_f32_e32 v251, s34, v251
	v_fma_f32 v160, v14, v248, v160
	v_fma_f32 v161, v15, v249, v161
	v_fma_f32 v162, v16, v250, v162
	v_fma_f32 v163, v17, v251, v163
	v_mfma_f32_16x16x32_bf16 v[18:21], v[216:219], v[208:211], v[18:21]
	v_cvt_f32_ubyte0_e32 v244, v235
	v_cvt_f32_ubyte1_e32 v245, v235
	v_cvt_f32_ubyte2_e32 v246, v235
	v_cvt_f32_ubyte3_e32 v247, v235
	v_mul_f32_e32 v244, s34, v244
	v_mul_f32_e32 v245, s34, v245
	v_mul_f32_e32 v246, s34, v246
	v_mul_f32_e32 v247, s34, v247
	v_fma_f32 v156, v10, v244, v156
	v_fma_f32 v157, v11, v245, v157
	v_fma_f32 v158, v12, v246, v158
	v_fma_f32 v159, v13, v247, v159
	v_mfma_f32_16x16x32_bf16 v[62:65], v[220:223], v[208:211], v[62:65]
	v_cvt_f32_ubyte0_e32 v248, v236
	v_cvt_f32_ubyte1_e32 v249, v236
	v_cvt_f32_ubyte2_e32 v250, v236
	v_cvt_f32_ubyte3_e32 v251, v236
	v_mul_f32_e32 v248, s34, v248
	v_mul_f32_e32 v249, s34, v249
	v_mul_f32_e32 v250, s34, v250
	v_mul_f32_e32 v251, s34, v251
	v_fma_f32 v136, v34, v248, v136
	v_fma_f32 v137, v35, v249, v137
	v_fma_f32 v150, v36, v250, v150
	v_fma_f32 v151, v37, v251, v151
	v_mfma_f32_16x16x32_bf16 v[58:61], v[90:93], v[224:227], v[58:61]
	v_cvt_f32_ubyte0_e32 v244, v237
	v_cvt_f32_ubyte1_e32 v245, v237
	v_cvt_f32_ubyte2_e32 v246, v237
	v_cvt_f32_ubyte3_e32 v247, v237
	v_mul_f32_e32 v244, s34, v244
	v_mul_f32_e32 v245, s34, v245
	v_mul_f32_e32 v246, s34, v246
	v_mul_f32_e32 v247, s34, v247
	v_fma_f32 v130, v22, v244, v130
	v_fma_f32 v131, v23, v245, v131
	v_fma_f32 v134, v24, v246, v134
	v_fma_f32 v135, v25, v247, v135
	v_mfma_f32_16x16x32_bf16 v[54:57], v[212:215], v[224:227], v[54:57]
	v_cvt_f32_ubyte0_e32 v248, v238
	v_cvt_f32_ubyte1_e32 v249, v238
	v_cvt_f32_ubyte2_e32 v250, v238
	v_cvt_f32_ubyte3_e32 v251, v238
	v_mul_f32_e32 v248, s34, v248
	v_mul_f32_e32 v249, s34, v249
	v_mul_f32_e32 v250, s34, v250
	v_mul_f32_e32 v251, s34, v251
	v_fma_f32 v124, v18, v248, v124
	v_fma_f32 v125, v19, v249, v125
	v_fma_f32 v126, v20, v250, v126
	v_fma_f32 v127, v21, v251, v127
	v_mfma_f32_16x16x32_bf16 v[50:53], v[216:219], v[224:227], v[50:53]
	v_cvt_f32_ubyte0_e32 v244, v239
	v_cvt_f32_ubyte1_e32 v245, v239
	v_cvt_f32_ubyte2_e32 v246, v239
	v_cvt_f32_ubyte3_e32 v247, v239
	v_mul_f32_e32 v244, s34, v244
	v_mul_f32_e32 v245, s34, v245
	v_mul_f32_e32 v246, s34, v246
	v_mul_f32_e32 v247, s34, v247
	v_fma_f32 v120, v62, v244, v120
	v_fma_f32 v121, v63, v245, v121
	v_fma_f32 v122, v64, v246, v122
	v_fma_f32 v123, v65, v247, v123
	v_mfma_f32_16x16x32_bf16 v[2:5], v[220:223], v[224:227], v[2:5]
	v_cvt_f32_ubyte0_e32 v248, v240
	v_cvt_f32_ubyte1_e32 v249, v240
	v_cvt_f32_ubyte2_e32 v250, v240
	v_cvt_f32_ubyte3_e32 v251, v240
	v_mul_f32_e32 v248, s34, v248
	v_mul_f32_e32 v249, s34, v249
	v_mul_f32_e32 v250, s34, v250
	v_mul_f32_e32 v251, s34, v251
	v_fma_f32 v114, v58, v248, v114
	v_fma_f32 v115, v59, v249, v115
	v_fma_f32 v116, v60, v250, v116
	v_fma_f32 v117, v61, v251, v117
	s_nop 7
	s_nop 3
	v_cvt_f32_ubyte0_e32 v248, v241
	v_cvt_f32_ubyte1_e32 v249, v241
	v_cvt_f32_ubyte2_e32 v250, v241
	v_cvt_f32_ubyte3_e32 v251, v241
	v_mul_f32_e32 v248, s34, v248
	v_mul_f32_e32 v249, s34, v249
	v_mul_f32_e32 v250, s34, v250
	v_mul_f32_e32 v251, s34, v251
	v_fma_f32 v106, v54, v248, v106
	v_fma_f32 v107, v55, v249, v107
	v_fma_f32 v108, v56, v250, v108
	v_fma_f32 v109, v57, v251, v109
	v_cvt_f32_ubyte0_e32 v244, v242
	v_cvt_f32_ubyte1_e32 v245, v242
	v_cvt_f32_ubyte2_e32 v246, v242
	v_cvt_f32_ubyte3_e32 v247, v242
	v_mul_f32_e32 v244, s34, v244
	v_mul_f32_e32 v245, s34, v245
	v_mul_f32_e32 v246, s34, v246
	v_mul_f32_e32 v247, s34, v247
	v_fma_f32 v100, v50, v244, v100
	v_fma_f32 v101, v51, v245, v101
	v_fma_f32 v102, v52, v246, v102
	v_fma_f32 v103, v53, v247, v103
	v_cvt_f32_ubyte0_e32 v248, v243
	v_cvt_f32_ubyte1_e32 v249, v243
	v_cvt_f32_ubyte2_e32 v250, v243
	v_cvt_f32_ubyte3_e32 v251, v243
	v_mul_f32_e32 v248, s34, v248
	v_mul_f32_e32 v249, s34, v249
	v_mul_f32_e32 v250, s34, v250
	v_mul_f32_e32 v251, s34, v251
	v_fma_f32 v96, v2, v248, v96
	v_fma_f32 v97, v3, v249, v97
	v_fma_f32 v98, v4, v250, v98
	v_fma_f32 v99, v5, v251, v99
	s_mov_b32 s66, 4
	s_add_u32 s6, s6, 0x400000
	s_addc_u32 s7, s7, 0
	s_cmp_eq_u32 s66, 4
	s_cbranch_scc0 .LBB0_1004
	v_lshlrev_b32_e32 v0, 1, v118
	v_lshl_add_u64 v[6:7], s[4:5], 0, v[0:1]
	v_lshlrev_b64 v[2:3], 11, v[112:113]
	v_lshl_add_u64 v[8:9], v[6:7], 0, v[2:3]
	v_cvt_pk_bf16_f32 v2, v184, v185
	v_cvt_pk_bf16_f32 v3, v186, v187
	v_cvt_pk_bf16_f32 v4, v180, v181
	v_cvt_pk_bf16_f32 v5, v182, v183
	global_store_dwordx4 v[8:9], v[2:5], off
	v_readlane_b32 s46, v254, 29
	s_mov_b32 s38, 0
	v_cvt_pk_bf16_f32 v2, v176, v177
	v_cvt_pk_bf16_f32 v3, v178, v179
	v_cvt_pk_bf16_f32 v4, v172, v173
	v_cvt_pk_bf16_f32 v5, v174, v175
	global_store_dwordx4 v[8:9], v[2:5], off offset:64
	v_readlane_b32 s47, v254, 30
	s_nop 0
	v_lshlrev_b64 v[2:3], 11, v[110:111]
	v_lshl_add_u64 v[8:9], v[6:7], 0, v[2:3]
	v_cvt_pk_bf16_f32 v2, v168, v169
	v_cvt_pk_bf16_f32 v3, v170, v171
	v_cvt_pk_bf16_f32 v4, v164, v165
	v_cvt_pk_bf16_f32 v5, v166, v167
	global_store_dwordx4 v[8:9], v[2:5], off
	s_nop 1
	v_cvt_pk_bf16_f32 v2, v160, v161
	v_cvt_pk_bf16_f32 v3, v162, v163
	v_cvt_pk_bf16_f32 v4, v156, v157
	v_cvt_pk_bf16_f32 v5, v158, v159
	global_store_dwordx4 v[8:9], v[2:5], off offset:64
	s_nop 1
	v_lshlrev_b64 v[2:3], 11, v[104:105]
	v_lshl_add_u64 v[8:9], v[6:7], 0, v[2:3]
	v_cvt_pk_bf16_f32 v2, v136, v137
	v_cvt_pk_bf16_f32 v3, v150, v151
	v_cvt_pk_bf16_f32 v4, v130, v131
	v_cvt_pk_bf16_f32 v5, v134, v135
	global_store_dwordx4 v[8:9], v[2:5], off
	s_nop 1
	v_cvt_pk_bf16_f32 v2, v124, v125
	v_cvt_pk_bf16_f32 v3, v126, v127
	v_cvt_pk_bf16_f32 v4, v120, v121
	v_cvt_pk_bf16_f32 v5, v122, v123
	global_store_dwordx4 v[8:9], v[2:5], off offset:64
	s_nop 1
	v_lshlrev_b64 v[2:3], 11, v[94:95]
	v_lshl_add_u64 v[6:7], v[6:7], 0, v[2:3]
	v_cvt_pk_bf16_f32 v2, v114, v115
	v_cvt_pk_bf16_f32 v3, v116, v117
	v_cvt_pk_bf16_f32 v4, v106, v107
	v_cvt_pk_bf16_f32 v5, v108, v109
	global_store_dwordx4 v[6:7], v[2:5], off
	s_nop 1
	v_cvt_pk_bf16_f32 v2, v100, v101
	v_cvt_pk_bf16_f32 v3, v102, v103
	v_cvt_pk_bf16_f32 v4, v96, v97
	v_cvt_pk_bf16_f32 v5, v98, v99
	global_store_dwordx4 v[6:7], v[2:5], off offset:64
